# K-loops: back-edge pointer and counter adds moved from after the closing barrier to just before the previous load segment's final wait; only compare and branch remain after the barrier
# speedup vs baseline: 1.0082x; 1.0057x over previous
; #define PG8_STAGE(bufoff, gbase, voff) do { _Pragma("unroll") for (int _i = 0; _i < 2; ++_i) \
;         __builtin_amdgcn_global_load_lds((const unsigned*)((const char*)(gbase) + (voff)[_i]), (LAS unsigned*)(lds + (bufoff) + ldsw + _i * 8192), 16, 0, 0); } while (0)
; #define PG8_WAIT_V(n) asm volatile("s_waitcnt vmcnt(" #n ")" ::: "memory")
; template <class Epi, class Sched = StaticOrder, class EpiSub = NoSub, bool FAST = false>
; __device__ __forceinline__ void gemm_phase(LAS unsigned char* lds, const Gemm g, const Sched& S, const Epi& E, const EpiSub& ES = EpiSub()) {
;     ...
;         const bool has_next = S.next(ui + 1, nxt);
;         const size_t nko = (has_next && nxt.kb >= 0) ? nxt.kb * ksubB : 0;
;         const char* nA = has_next ? (const char*)g.A + (size_t)nxt.pm * tstepA + (size_t)nxt.pn * g.acs + nko : cA; const char* nB = has_next ? (const char*)g.Bt + (size_t)nxt.pn * tstepB + nko : cB;
;         const int nt = cur.kb < 0 ? ntMain : ntSub;
;         for (int t = 0; t < nt; t += 2) {
;             const bool last = (t == nt - 2);
;             const char* a1 = cA + (size_t)(t + 1) * kstep;
;             const char* a2 = last ? nA : cA + (size_t)(t + 2) * kstep; const char* b2 = last ? nB : cB + (size_t)(t + 2) * kstep;
;             const char* a3 = a2 + kstep; const char* b3 = b2 + kstep;
;             if constexpr (FAST && PG8_SP2) {
;             PG8_LDB(B0, 0, 0); PG8_LDB(B1, 0, 1); PG8_SCHED; PG8_LDA(At, 0, 0); PG8_STAGE(PG8_SA(1, 1), a1 + hstepA, voffA);
;             PG8_WAIT_V(8); PG8_WAIT_L(0); PG8_BAR; PG8_MMA(0, 0, At, B0); PG8_MMA(0, 1, At, B1); PG8_BAR; PG8_SCHED;
;             PG8_LDA(At, 0, 1); PG8_STAGE(PG8_SB(0, 0), b2, voffB); PG8_STAGE(PG8_SB(0, 1), b2 + hstepB, voffB); PG8_STAGE(PG8_SA(0, 0), a2, voffA);
;             PG8_WAIT_V(8); PG8_WAIT_L(0); PG8_BAR; PG8_MMA(1, 0, At, B0); PG8_MMA(1, 1, At, B1); PG8_BAR; PG8_SCHED;
;             PG8_LDB(B0, 1, 0); PG8_LDB(B1, 1, 1); PG8_SCHED; PG8_LDA(At, 1, 0); PG8_STAGE(PG8_SA(0, 1), a2 + hstepA, voffA);
;             PG8_WAIT_V(8); PG8_WAIT_L(0); PG8_BAR; PG8_MMA(0, 0, At, B0); PG8_MMA(0, 1, At, B1); PG8_BAR; PG8_SCHED;
;             PG8_LDA(At, 1, 1); PG8_STAGE(PG8_SB(1, 0), b3, voffB); PG8_STAGE(PG8_SB(1, 1), b3 + hstepB, voffB); PG8_STAGE(PG8_SA(1, 0), a3, voffA);
;             PG8_WAIT_V(8); PG8_WAIT_L(0); PG8_BAR; PG8_MMA(1, 0, At, B0); PG8_MMA(1, 1, At, B1); PG8_BAR; PG8_SCHED;
.LBB0_215:
	s_ashr_i32 s15, s14, 31
	s_lshl_b64 s[2:3], s[14:15], 20
	v_readlane_b32 s16, v254, 36
	v_readlane_b32 s17, v254, 37
	s_add_u32 s16, s16, s2
	s_addc_u32 s17, s17, s3
	s_and_b64 s[2:3], s[0:1], exec
	s_cselect_b32 s2, s17, s23
	s_cselect_b32 s3, s16, s22
	s_ashr_i32 s13, s12, 31
	s_lshl_b64 s[18:19], s[12:13], 20
	s_add_u32 s18, s28, s18
	s_addc_u32 s19, s29, s19
	s_and_b64 s[26:27], s[0:1], exec
	s_cselect_b32 s13, s19, s25
	s_cselect_b32 s15, s18, s24
	s_add_u32 s22, s22, 0x80080
	s_addc_u32 s23, s23, 0
	s_add_u32 s48, s24, 0x100
	s_addc_u32 s49, s25, 0
	s_mov_b32 s50, -2
	ds_read_b128 v[154:157], v150
	ds_read_b128 v[158:161], v150 offset:1024
	ds_read_b128 v[162:165], v150 offset:2048
	ds_read_b128 v[166:169], v150 offset:3072
	ds_read_b128 v[170:173], v151
	ds_read_b128 v[174:177], v151 offset:1024
	ds_read_b128 v[178:181], v151 offset:2048
	ds_read_b128 v[182:185], v151 offset:3072
	s_add_u32 s24, s22, 0xfff80080
	s_addc_u32 s25, s23, -1
	s_cmp_eq_u32 s50, 28
	s_cselect_b32 s27, s2, s25
	s_cselect_b32 s26, s3, s24
	s_cselect_b32 s25, s13, s49
	s_cselect_b32 s24, s15, s48
	v_lshl_add_u64 v[144:145], s[22:23], 0, v[136:137]
	s_add_i32 m0, s21, 0xc000
	ds_read_b128 v[186:189], v152
	ds_read_b128 v[194:197], v152 offset:1024
	ds_read_b128 v[198:201], v152 offset:2048
	ds_read_b128 v[202:205], v152 offset:3072
	ds_read_b128 v[206:209], v152 offset:4096
	ds_read_b128 v[210:213], v152 offset:5120
	ds_read_b128 v[214:217], v152 offset:6144
	ds_read_b128 v[218:221], v152 offset:7168
	global_load_lds_dwordx4 v[144:145], off
	v_lshl_add_u64 v[144:145], s[22:23], 0, v[138:139]
	s_add_i32 m0, s21, 0xe000
	s_nop 0
	global_load_lds_dwordx4 v[144:145], off
	s_waitcnt vmcnt(8)
	s_waitcnt lgkmcnt(0)
	s_barrier
	v_mfma_f32_16x16x32_bf16 v[124:127], v[154:157], v[186:189], 0
	v_mfma_f32_16x16x32_bf16 v[120:123], v[162:165], v[186:189], 0
	v_mfma_f32_16x16x32_bf16 v[116:119], v[154:157], v[198:201], 0
	v_mfma_f32_16x16x32_bf16 v[108:111], v[162:165], v[198:201], 0
	v_mfma_f32_16x16x32_bf16 v[100:103], v[154:157], v[206:209], 0
	v_mfma_f32_16x16x32_bf16 v[92:95], v[162:165], v[206:209], 0
	v_mfma_f32_16x16x32_bf16 v[84:87], v[154:157], v[214:217], 0
	v_mfma_f32_16x16x32_bf16 v[76:79], v[162:165], v[214:217], 0
	v_mfma_f32_16x16x32_bf16 v[124:127], v[158:161], v[194:197], v[124:127]
	v_mfma_f32_16x16x32_bf16 v[120:123], v[166:169], v[194:197], v[120:123]
	v_mfma_f32_16x16x32_bf16 v[116:119], v[158:161], v[202:205], v[116:119]
	v_mfma_f32_16x16x32_bf16 v[108:111], v[166:169], v[202:205], v[108:111]
	v_mfma_f32_16x16x32_bf16 v[100:103], v[158:161], v[210:213], v[100:103]
	v_mfma_f32_16x16x32_bf16 v[92:95], v[166:169], v[210:213], v[92:95]
	v_mfma_f32_16x16x32_bf16 v[84:87], v[158:161], v[218:221], v[84:87]
	v_mfma_f32_16x16x32_bf16 v[76:79], v[166:169], v[218:221], v[76:79]
	v_mfma_f32_16x16x32_bf16 v[112:115], v[170:173], v[186:189], 0
	v_mfma_f32_16x16x32_bf16 v[104:107], v[178:181], v[186:189], 0
	v_mfma_f32_16x16x32_bf16 v[96:99], v[170:173], v[198:201], 0
	v_mfma_f32_16x16x32_bf16 v[88:91], v[178:181], v[198:201], 0
	v_mfma_f32_16x16x32_bf16 v[80:83], v[170:173], v[206:209], 0
	v_mfma_f32_16x16x32_bf16 v[72:75], v[178:181], v[206:209], 0
	v_mfma_f32_16x16x32_bf16 v[68:71], v[170:173], v[214:217], 0
	v_mfma_f32_16x16x32_bf16 v[64:67], v[178:181], v[214:217], 0
	v_mfma_f32_16x16x32_bf16 v[112:115], v[174:177], v[194:197], v[112:115]
	v_mfma_f32_16x16x32_bf16 v[104:107], v[182:185], v[194:197], v[104:107]
	v_mfma_f32_16x16x32_bf16 v[96:99], v[174:177], v[202:205], v[96:99]
	v_mfma_f32_16x16x32_bf16 v[88:91], v[182:185], v[202:205], v[88:91]
	v_mfma_f32_16x16x32_bf16 v[80:83], v[174:177], v[210:213], v[80:83]
	v_mfma_f32_16x16x32_bf16 v[72:75], v[182:185], v[210:213], v[72:75]
	v_mfma_f32_16x16x32_bf16 v[68:71], v[174:177], v[218:221], v[68:71]
	v_mfma_f32_16x16x32_bf16 v[64:67], v[182:185], v[218:221], v[64:67]
	s_barrier
	s_add_i32 s51, s41, s30
	v_lshl_add_u64 v[144:145], s[24:25], 0, v[130:131]
	s_mov_b32 m0, s51
	ds_read_b128 v[186:189], v152 offset:16384
	ds_read_b128 v[194:197], v152 offset:17408
	ds_read_b128 v[198:201], v152 offset:18432
	ds_read_b128 v[202:205], v152 offset:19456
	ds_read_b128 v[206:209], v152 offset:20480
	ds_read_b128 v[210:213], v152 offset:21504
	ds_read_b128 v[214:217], v152 offset:22528
	ds_read_b128 v[218:221], v152 offset:23552
	global_load_lds_dwordx4 v[144:145], off
	s_add_i32 m0, s51, 0x2000
	s_add_u32 s68, s24, 0x80000
	v_lshl_add_u64 v[190:191], s[24:25], 0, v[134:135]
	s_addc_u32 s69, s25, 0
	s_add_i32 s51, s42, s30
	global_load_lds_dwordx4 v[190:191], off
	v_lshl_add_u64 v[222:223], s[68:69], 0, v[130:131]
	s_mov_b32 m0, s51
	v_lshl_add_u64 v[224:225], s[26:27], 0, v[132:133]
	global_load_lds_dwordx4 v[222:223], off
	v_lshl_add_u64 v[222:223], s[68:69], 0, v[134:135]
	s_add_i32 m0, s51, 0x2000
	s_nop 0
	global_load_lds_dwordx4 v[222:223], off
	v_lshl_add_u64 v[222:223], s[26:27], 0, v[128:129]
	s_mov_b32 m0, s21
	s_nop 0
	global_load_lds_dwordx4 v[222:223], off
	s_mov_b32 m0, s34
	s_nop 0
	global_load_lds_dwordx4 v[224:225], off
	s_waitcnt vmcnt(8)
	s_waitcnt lgkmcnt(0)
	s_barrier
; #define PG8_STAGE(bufoff, gbase, voff) do { _Pragma("unroll") for (int _i = 0; _i < 2; ++_i) \
;         __builtin_amdgcn_global_load_lds((const unsigned*)((const char*)(gbase) + (voff)[_i]), (LAS unsigned*)(lds + (bufoff) + ldsw + _i * 8192), 16, 0, 0); } while (0)
; #define PG8_LDA(dst, b, h) do { _Pragma("unroll") for (int m = 0; m < 4; ++m) _Pragma("unroll") for (int k = 0; k < 2; ++k) dst[m][k] = *(const LAS bf16x8*)(lds + PG8_SA(b, h) + aoff + m * 2048 + k * 1024); } while (0)
; #define PG8_LDB(dst, b, h) do { _Pragma("unroll") for (int n = 0; n < 2; ++n) _Pragma("unroll") for (int k = 0; k < 2; ++k) dst[n][k] = *(const LAS bf16x8*)(lds + PG8_SB(b, h) + boff + n * 2048 + k * 1024); } while (0)
; #define PG8_MMA(ai, bj, At, Bt) do { __builtin_amdgcn_s_setprio(1); _Pragma("unroll") for (int m = 0; m < 4; ++m) _Pragma("unroll") for (int n = 0; n < 2; ++n) _Pragma("unroll") for (int k = 0; k < 2; ++k) \
;         acc[ai][bj][m][n] = __builtin_amdgcn_mfma_f32_16x16x32_bf16(Bt[n][k], At[m][k], acc[ai][bj][m][n], 0, 0, 0); __builtin_amdgcn_s_setprio(0); } while (0)
; #define PG8_BAR __builtin_amdgcn_s_barrier()
; template <class Epi, class Sched = StaticOrder, class EpiSub = NoSub, bool FAST = false>
; __device__ __forceinline__ void gemm_phase(LAS unsigned char* lds, const Gemm g, const Sched& S, const Epi& E, const EpiSub& ES = EpiSub()) {
;     ...
;             PG8_LDB(B0, 0, 0); PG8_LDB(B1, 0, 1); PG8_SCHED; PG8_LDA(At, 0, 0); PG8_STAGE(PG8_SA(1, 1), a1 + hstepA, voffA);
;             PG8_WAIT_V(8); PG8_WAIT_L(0); PG8_BAR; PG8_MMA(0, 0, At, B0); PG8_MMA(0, 1, At, B1); PG8_BAR; PG8_SCHED;
;             PG8_LDA(At, 0, 1); PG8_STAGE(PG8_SB(0, 0), b2, voffB); PG8_STAGE(PG8_SB(0, 1), b2 + hstepB, voffB); PG8_STAGE(PG8_SA(0, 0), a2, voffA);
;             PG8_WAIT_V(8); PG8_WAIT_L(0); PG8_BAR; PG8_MMA(1, 0, At, B0); PG8_MMA(1, 1, At, B1); PG8_BAR; PG8_SCHED;
;             PG8_LDB(B0, 1, 0); PG8_LDB(B1, 1, 1); PG8_SCHED; PG8_LDA(At, 1, 0); PG8_STAGE(PG8_SA(0, 1), a2 + hstepA, voffA);
;             PG8_WAIT_V(8); PG8_WAIT_L(0); PG8_BAR; PG8_MMA(0, 0, At, B0); PG8_MMA(0, 1, At, B1); PG8_BAR; PG8_SCHED;
;             PG8_LDA(At, 1, 1); PG8_STAGE(PG8_SB(1, 0), b3, voffB); PG8_STAGE(PG8_SB(1, 1), b3 + hstepB, voffB); PG8_STAGE(PG8_SA(1, 0), a3, voffA);
;             PG8_WAIT_V(8); PG8_WAIT_L(0); PG8_BAR; PG8_MMA(1, 0, At, B0); PG8_MMA(1, 1, At, B1); PG8_BAR; PG8_SCHED;
	v_mfma_f32_16x16x32_bf16 v[60:63], v[154:157], v[186:189], 0
	v_mfma_f32_16x16x32_bf16 v[56:59], v[162:165], v[186:189], 0
	v_mfma_f32_16x16x32_bf16 v[52:55], v[154:157], v[198:201], 0
	v_mfma_f32_16x16x32_bf16 v[44:47], v[162:165], v[198:201], 0
	v_mfma_f32_16x16x32_bf16 v[36:39], v[154:157], v[206:209], 0
	v_mfma_f32_16x16x32_bf16 v[28:31], v[162:165], v[206:209], 0
	v_mfma_f32_16x16x32_bf16 v[20:23], v[154:157], v[214:217], 0
	v_mfma_f32_16x16x32_bf16 v[12:15], v[162:165], v[214:217], 0
	v_mfma_f32_16x16x32_bf16 v[60:63], v[158:161], v[194:197], v[60:63]
	v_mfma_f32_16x16x32_bf16 v[56:59], v[166:169], v[194:197], v[56:59]
	v_mfma_f32_16x16x32_bf16 v[52:55], v[158:161], v[202:205], v[52:55]
	v_mfma_f32_16x16x32_bf16 v[44:47], v[166:169], v[202:205], v[44:47]
	v_mfma_f32_16x16x32_bf16 v[36:39], v[158:161], v[210:213], v[36:39]
	v_mfma_f32_16x16x32_bf16 v[28:31], v[166:169], v[210:213], v[28:31]
	v_mfma_f32_16x16x32_bf16 v[20:23], v[158:161], v[218:221], v[20:23]
	v_mfma_f32_16x16x32_bf16 v[12:15], v[166:169], v[218:221], v[12:15]
	v_mfma_f32_16x16x32_bf16 v[48:51], v[170:173], v[186:189], 0
	v_mfma_f32_16x16x32_bf16 v[40:43], v[178:181], v[186:189], 0
	v_mfma_f32_16x16x32_bf16 v[32:35], v[170:173], v[198:201], 0
	v_mfma_f32_16x16x32_bf16 v[24:27], v[178:181], v[198:201], 0
	v_mfma_f32_16x16x32_bf16 v[16:19], v[170:173], v[206:209], 0
	v_mfma_f32_16x16x32_bf16 v[8:11], v[178:181], v[206:209], 0
	v_mfma_f32_16x16x32_bf16 v[4:7], v[170:173], v[214:217], 0
	v_mfma_f32_16x16x32_bf16 v[0:3], v[178:181], v[214:217], 0
	v_mfma_f32_16x16x32_bf16 v[48:51], v[174:177], v[194:197], v[48:51]
	v_mfma_f32_16x16x32_bf16 v[40:43], v[182:185], v[194:197], v[40:43]
	v_mfma_f32_16x16x32_bf16 v[32:35], v[174:177], v[202:205], v[32:35]
	v_mfma_f32_16x16x32_bf16 v[24:27], v[182:185], v[202:205], v[24:27]
	v_mfma_f32_16x16x32_bf16 v[16:19], v[174:177], v[210:213], v[16:19]
	v_mfma_f32_16x16x32_bf16 v[8:11], v[182:185], v[210:213], v[8:11]
	v_mfma_f32_16x16x32_bf16 v[4:7], v[174:177], v[218:221], v[4:7]
	v_mfma_f32_16x16x32_bf16 v[0:3], v[182:185], v[218:221], v[0:3]
	s_barrier
	s_add_i32 s51, 0, 0x18000
	v_add_u32_e32 v153, s51, v148
	s_add_i32 s68, 0, 0x1c000
	ds_read_b128 v[154:157], v153
	ds_read_b128 v[158:161], v153 offset:1024
	ds_read_b128 v[162:165], v153 offset:2048
	ds_read_b128 v[166:169], v153 offset:3072
	v_add_u32_e32 v153, s68, v148
	ds_read_b128 v[170:173], v153
	ds_read_b128 v[174:177], v153 offset:1024
	ds_read_b128 v[178:181], v153 offset:2048
	ds_read_b128 v[182:185], v153 offset:3072
	s_add_u32 s26, s26, 0x80000
	s_addc_u32 s27, s27, 0
	s_mov_b32 m0, s35
	v_lshl_add_u64 v[226:227], s[26:27], 0, v[128:129]
	ds_read_b128 v[186:189], v152 offset:32768
	ds_read_b128 v[194:197], v152 offset:33792
	ds_read_b128 v[198:201], v152 offset:34816
	ds_read_b128 v[202:205], v152 offset:35840
	ds_read_b128 v[206:209], v152 offset:36864
	ds_read_b128 v[210:213], v152 offset:37888
	ds_read_b128 v[214:217], v152 offset:38912
	ds_read_b128 v[218:221], v152 offset:39936
	global_load_lds_dwordx4 v[226:227], off
	v_lshl_add_u64 v[226:227], s[26:27], 0, v[132:133]
	s_mov_b32 m0, s36
	s_nop 0
	global_load_lds_dwordx4 v[226:227], off
	s_waitcnt vmcnt(8)
	s_waitcnt lgkmcnt(0)
	s_barrier
	v_mfma_f32_16x16x32_bf16 v[124:127], v[154:157], v[186:189], v[124:127]
	v_mfma_f32_16x16x32_bf16 v[120:123], v[162:165], v[186:189], v[120:123]
	v_mfma_f32_16x16x32_bf16 v[116:119], v[154:157], v[198:201], v[116:119]
	v_mfma_f32_16x16x32_bf16 v[108:111], v[162:165], v[198:201], v[108:111]
	v_mfma_f32_16x16x32_bf16 v[100:103], v[154:157], v[206:209], v[100:103]
	v_mfma_f32_16x16x32_bf16 v[92:95], v[162:165], v[206:209], v[92:95]
	v_mfma_f32_16x16x32_bf16 v[84:87], v[154:157], v[214:217], v[84:87]
	v_mfma_f32_16x16x32_bf16 v[76:79], v[162:165], v[214:217], v[76:79]
	v_mfma_f32_16x16x32_bf16 v[124:127], v[158:161], v[194:197], v[124:127]
	v_mfma_f32_16x16x32_bf16 v[120:123], v[166:169], v[194:197], v[120:123]
	v_mfma_f32_16x16x32_bf16 v[116:119], v[158:161], v[202:205], v[116:119]
	v_mfma_f32_16x16x32_bf16 v[108:111], v[166:169], v[202:205], v[108:111]
	v_mfma_f32_16x16x32_bf16 v[100:103], v[158:161], v[210:213], v[100:103]
	v_mfma_f32_16x16x32_bf16 v[92:95], v[166:169], v[210:213], v[92:95]
	v_mfma_f32_16x16x32_bf16 v[84:87], v[158:161], v[218:221], v[84:87]
	v_mfma_f32_16x16x32_bf16 v[76:79], v[166:169], v[218:221], v[76:79]
	v_mfma_f32_16x16x32_bf16 v[112:115], v[170:173], v[186:189], v[112:115]
	v_mfma_f32_16x16x32_bf16 v[104:107], v[178:181], v[186:189], v[104:107]
	v_mfma_f32_16x16x32_bf16 v[96:99], v[170:173], v[198:201], v[96:99]
	v_mfma_f32_16x16x32_bf16 v[88:91], v[178:181], v[198:201], v[88:91]
	v_mfma_f32_16x16x32_bf16 v[80:83], v[170:173], v[206:209], v[80:83]
	v_mfma_f32_16x16x32_bf16 v[72:75], v[178:181], v[206:209], v[72:75]
	v_mfma_f32_16x16x32_bf16 v[68:71], v[170:173], v[214:217], v[68:71]
	v_mfma_f32_16x16x32_bf16 v[64:67], v[178:181], v[214:217], v[64:67]
	v_mfma_f32_16x16x32_bf16 v[112:115], v[174:177], v[194:197], v[112:115]
	v_mfma_f32_16x16x32_bf16 v[104:107], v[182:185], v[194:197], v[104:107]
	v_mfma_f32_16x16x32_bf16 v[96:99], v[174:177], v[202:205], v[96:99]
	v_mfma_f32_16x16x32_bf16 v[88:91], v[182:185], v[202:205], v[88:91]
	v_mfma_f32_16x16x32_bf16 v[80:83], v[174:177], v[210:213], v[80:83]
	v_mfma_f32_16x16x32_bf16 v[72:75], v[182:185], v[210:213], v[72:75]
	v_mfma_f32_16x16x32_bf16 v[68:71], v[174:177], v[218:221], v[68:71]
	v_mfma_f32_16x16x32_bf16 v[64:67], v[182:185], v[218:221], v[64:67]
	s_barrier
; #define PG8_STAGE(bufoff, gbase, voff) do { _Pragma("unroll") for (int _i = 0; _i < 2; ++_i) \
;         __builtin_amdgcn_global_load_lds((const unsigned*)((const char*)(gbase) + (voff)[_i]), (LAS unsigned*)(lds + (bufoff) + ldsw + _i * 8192), 16, 0, 0); } while (0)
; #define PG8_LDA(dst, b, h) do { _Pragma("unroll") for (int m = 0; m < 4; ++m) _Pragma("unroll") for (int k = 0; k < 2; ++k) dst[m][k] = *(const LAS bf16x8*)(lds + PG8_SA(b, h) + aoff + m * 2048 + k * 1024); } while (0)
; #define PG8_LDB(dst, b, h) do { _Pragma("unroll") for (int n = 0; n < 2; ++n) _Pragma("unroll") for (int k = 0; k < 2; ++k) dst[n][k] = *(const LAS bf16x8*)(lds + PG8_SB(b, h) + boff + n * 2048 + k * 1024); } while (0)
; #define PG8_MMA(ai, bj, At, Bt) do { __builtin_amdgcn_s_setprio(1); _Pragma("unroll") for (int m = 0; m < 4; ++m) _Pragma("unroll") for (int n = 0; n < 2; ++n) _Pragma("unroll") for (int k = 0; k < 2; ++k) \
;         acc[ai][bj][m][n] = __builtin_amdgcn_mfma_f32_16x16x32_bf16(Bt[n][k], At[m][k], acc[ai][bj][m][n], 0, 0, 0); __builtin_amdgcn_s_setprio(0); } while (0)
; #define PG8_BAR __builtin_amdgcn_s_barrier()
; template <class Epi, class Sched = StaticOrder, class EpiSub = NoSub, bool FAST = false>
; __device__ __forceinline__ void gemm_phase(LAS unsigned char* lds, const Gemm g, const Sched& S, const Epi& E, const EpiSub& ES = EpiSub()) {
;     ...
;             PG8_LDB(B0, 0, 0); PG8_LDB(B1, 0, 1); PG8_SCHED; PG8_LDA(At, 0, 0); PG8_STAGE(PG8_SA(1, 1), a1 + hstepA, voffA);
;             PG8_WAIT_V(8); PG8_WAIT_L(0); PG8_BAR; PG8_MMA(0, 0, At, B0); PG8_MMA(0, 1, At, B1); PG8_BAR; PG8_SCHED;
;             PG8_LDA(At, 0, 1); PG8_STAGE(PG8_SB(0, 0), b2, voffB); PG8_STAGE(PG8_SB(0, 1), b2 + hstepB, voffB); PG8_STAGE(PG8_SA(0, 0), a2, voffA);
;             PG8_WAIT_V(8); PG8_WAIT_L(0); PG8_BAR; PG8_MMA(1, 0, At, B0); PG8_MMA(1, 1, At, B1); PG8_BAR; PG8_SCHED;
;             PG8_LDB(B0, 1, 0); PG8_LDB(B1, 1, 1); PG8_SCHED; PG8_LDA(At, 1, 0); PG8_STAGE(PG8_SA(0, 1), a2 + hstepA, voffA);
;             PG8_WAIT_V(8); PG8_WAIT_L(0); PG8_BAR; PG8_MMA(0, 0, At, B0); PG8_MMA(0, 1, At, B1); PG8_BAR; PG8_SCHED;
;             PG8_LDA(At, 1, 1); PG8_STAGE(PG8_SB(1, 0), b3, voffB); PG8_STAGE(PG8_SB(1, 1), b3 + hstepB, voffB); PG8_STAGE(PG8_SA(1, 0), a3, voffA);
;             PG8_WAIT_V(8); PG8_WAIT_L(0); PG8_BAR; PG8_MMA(1, 0, At, B0); PG8_MMA(1, 1, At, B1); PG8_BAR; PG8_SCHED;
	s_add_i32 s26, s51, s30
	v_lshl_add_u64 v[144:145], v[144:145], 0, s[8:9]
	s_mov_b32 m0, s26
	ds_read_b128 v[186:189], v152 offset:49152
	ds_read_b128 v[194:197], v152 offset:50176
	ds_read_b128 v[198:201], v152 offset:51200
	ds_read_b128 v[202:205], v152 offset:52224
	ds_read_b128 v[206:209], v152 offset:53248
	ds_read_b128 v[210:213], v152 offset:54272
	ds_read_b128 v[214:217], v152 offset:55296
	ds_read_b128 v[218:221], v152 offset:56320
	global_load_lds_dwordx4 v[144:145], off
	s_add_i32 m0, s26, 0x2000
	s_add_u32 s24, s24, 0x80080
	v_lshl_add_u64 v[144:145], v[190:191], 0, s[8:9]
	s_addc_u32 s25, s25, 0
	s_add_i32 s26, s68, s30
	global_load_lds_dwordx4 v[144:145], off
	v_lshl_add_u64 v[144:145], s[24:25], 0, v[130:131]
	s_mov_b32 m0, s26
	s_nop 0
	global_load_lds_dwordx4 v[144:145], off
	v_lshl_add_u64 v[144:145], s[24:25], 0, v[134:135]
	s_add_i32 m0, s26, 0x2000
	s_nop 0
	global_load_lds_dwordx4 v[144:145], off
	v_lshl_add_u64 v[144:145], v[222:223], 0, s[8:9]
	s_mov_b32 m0, s39
	s_nop 0
	global_load_lds_dwordx4 v[144:145], off
	v_lshl_add_u64 v[144:145], v[224:225], 0, s[8:9]
	s_mov_b32 m0, s40
	s_nop 0
	global_load_lds_dwordx4 v[144:145], off
	s_add_i32 s50, s50, 2
	s_add_u32 s22, s22, 0x100
	s_addc_u32 s23, s23, 0
	s_add_u32 s48, s48, 0x100
	s_addc_u32 s49, s49, 0
	s_waitcnt vmcnt(8)
	s_waitcnt lgkmcnt(0)
	s_barrier
	v_mfma_f32_16x16x32_bf16 v[60:63], v[154:157], v[186:189], v[60:63]
	v_mfma_f32_16x16x32_bf16 v[56:59], v[162:165], v[186:189], v[56:59]
	v_mfma_f32_16x16x32_bf16 v[52:55], v[154:157], v[198:201], v[52:55]
	v_mfma_f32_16x16x32_bf16 v[44:47], v[162:165], v[198:201], v[44:47]
	v_mfma_f32_16x16x32_bf16 v[36:39], v[154:157], v[206:209], v[36:39]
	v_mfma_f32_16x16x32_bf16 v[28:31], v[162:165], v[206:209], v[28:31]
	v_mfma_f32_16x16x32_bf16 v[20:23], v[154:157], v[214:217], v[20:23]
	v_mfma_f32_16x16x32_bf16 v[12:15], v[162:165], v[214:217], v[12:15]
	v_mfma_f32_16x16x32_bf16 v[60:63], v[158:161], v[194:197], v[60:63]
	v_mfma_f32_16x16x32_bf16 v[56:59], v[166:169], v[194:197], v[56:59]
	v_mfma_f32_16x16x32_bf16 v[52:55], v[158:161], v[202:205], v[52:55]
	v_mfma_f32_16x16x32_bf16 v[44:47], v[166:169], v[202:205], v[44:47]
	v_mfma_f32_16x16x32_bf16 v[36:39], v[158:161], v[210:213], v[36:39]
	v_mfma_f32_16x16x32_bf16 v[28:31], v[166:169], v[210:213], v[28:31]
	v_mfma_f32_16x16x32_bf16 v[20:23], v[158:161], v[218:221], v[20:23]
	v_mfma_f32_16x16x32_bf16 v[12:15], v[166:169], v[218:221], v[12:15]
	v_mfma_f32_16x16x32_bf16 v[48:51], v[170:173], v[186:189], v[48:51]
	v_mfma_f32_16x16x32_bf16 v[40:43], v[178:181], v[186:189], v[40:43]
	v_mfma_f32_16x16x32_bf16 v[32:35], v[170:173], v[198:201], v[32:35]
	v_mfma_f32_16x16x32_bf16 v[24:27], v[178:181], v[198:201], v[24:27]
	v_mfma_f32_16x16x32_bf16 v[16:19], v[170:173], v[206:209], v[16:19]
	v_mfma_f32_16x16x32_bf16 v[8:11], v[178:181], v[206:209], v[8:11]
	v_mfma_f32_16x16x32_bf16 v[4:7], v[170:173], v[214:217], v[4:7]
	v_mfma_f32_16x16x32_bf16 v[0:3], v[178:181], v[214:217], v[0:3]
	v_mfma_f32_16x16x32_bf16 v[48:51], v[174:177], v[194:197], v[48:51]
	v_mfma_f32_16x16x32_bf16 v[40:43], v[182:185], v[194:197], v[40:43]
	v_mfma_f32_16x16x32_bf16 v[32:35], v[174:177], v[202:205], v[32:35]
	v_mfma_f32_16x16x32_bf16 v[24:27], v[182:185], v[202:205], v[24:27]
	v_mfma_f32_16x16x32_bf16 v[16:19], v[174:177], v[210:213], v[16:19]
	v_mfma_f32_16x16x32_bf16 v[8:11], v[182:185], v[210:213], v[8:11]
	v_mfma_f32_16x16x32_bf16 v[4:7], v[174:177], v[218:221], v[4:7]
	v_mfma_f32_16x16x32_bf16 v[0:3], v[182:185], v[218:221], v[0:3]
	s_barrier
	s_cmp_gt_u32 s50, 29
	s_cbranch_scc1 .Lkpeel_216_exit
.LBB0_216:
	ds_read_b128 v[154:157], v150
	ds_read_b128 v[158:161], v150 offset:1024
	ds_read_b128 v[162:165], v150 offset:2048
	ds_read_b128 v[166:169], v150 offset:3072
	ds_read_b128 v[170:173], v151
	ds_read_b128 v[174:177], v151 offset:1024
	ds_read_b128 v[178:181], v151 offset:2048
	ds_read_b128 v[182:185], v151 offset:3072
	s_add_u32 s24, s22, 0xfff80080
	s_addc_u32 s25, s23, -1
	s_cmp_eq_u32 s50, 28
	s_cselect_b32 s27, s2, s25
	s_cselect_b32 s26, s3, s24
	s_cselect_b32 s25, s13, s49
	s_cselect_b32 s24, s15, s48
	v_lshl_add_u64 v[144:145], s[22:23], 0, v[136:137]
	s_add_i32 m0, s21, 0xc000
	ds_read_b128 v[186:189], v152
	ds_read_b128 v[194:197], v152 offset:1024
	ds_read_b128 v[198:201], v152 offset:2048
	ds_read_b128 v[202:205], v152 offset:3072
	ds_read_b128 v[206:209], v152 offset:4096
	ds_read_b128 v[210:213], v152 offset:5120
	ds_read_b128 v[214:217], v152 offset:6144
	ds_read_b128 v[218:221], v152 offset:7168
	global_load_lds_dwordx4 v[144:145], off
	v_lshl_add_u64 v[144:145], s[22:23], 0, v[138:139]
	s_add_i32 m0, s21, 0xe000
	s_nop 0
	global_load_lds_dwordx4 v[144:145], off
	s_waitcnt vmcnt(8)
	s_waitcnt lgkmcnt(0)
	s_barrier
; #define PG8_STAGE(bufoff, gbase, voff) do { _Pragma("unroll") for (int _i = 0; _i < 2; ++_i) \
;         __builtin_amdgcn_global_load_lds((const unsigned*)((const char*)(gbase) + (voff)[_i]), (LAS unsigned*)(lds + (bufoff) + ldsw + _i * 8192), 16, 0, 0); } while (0)
; #define PG8_LDA(dst, b, h) do { _Pragma("unroll") for (int m = 0; m < 4; ++m) _Pragma("unroll") for (int k = 0; k < 2; ++k) dst[m][k] = *(const LAS bf16x8*)(lds + PG8_SA(b, h) + aoff + m * 2048 + k * 1024); } while (0)
; #define PG8_LDB(dst, b, h) do { _Pragma("unroll") for (int n = 0; n < 2; ++n) _Pragma("unroll") for (int k = 0; k < 2; ++k) dst[n][k] = *(const LAS bf16x8*)(lds + PG8_SB(b, h) + boff + n * 2048 + k * 1024); } while (0)
; #define PG8_MMA(ai, bj, At, Bt) do { __builtin_amdgcn_s_setprio(1); _Pragma("unroll") for (int m = 0; m < 4; ++m) _Pragma("unroll") for (int n = 0; n < 2; ++n) _Pragma("unroll") for (int k = 0; k < 2; ++k) \
;         acc[ai][bj][m][n] = __builtin_amdgcn_mfma_f32_16x16x32_bf16(Bt[n][k], At[m][k], acc[ai][bj][m][n], 0, 0, 0); __builtin_amdgcn_s_setprio(0); } while (0)
; #define PG8_BAR __builtin_amdgcn_s_barrier()
; template <class Epi, class Sched = StaticOrder, class EpiSub = NoSub, bool FAST = false>
; __device__ __forceinline__ void gemm_phase(LAS unsigned char* lds, const Gemm g, const Sched& S, const Epi& E, const EpiSub& ES = EpiSub()) {
;     ...
;             PG8_LDB(B0, 0, 0); PG8_LDB(B1, 0, 1); PG8_SCHED; PG8_LDA(At, 0, 0); PG8_STAGE(PG8_SA(1, 1), a1 + hstepA, voffA);
;             PG8_WAIT_V(8); PG8_WAIT_L(0); PG8_BAR; PG8_MMA(0, 0, At, B0); PG8_MMA(0, 1, At, B1); PG8_BAR; PG8_SCHED;
;             PG8_LDA(At, 0, 1); PG8_STAGE(PG8_SB(0, 0), b2, voffB); PG8_STAGE(PG8_SB(0, 1), b2 + hstepB, voffB); PG8_STAGE(PG8_SA(0, 0), a2, voffA);
;             PG8_WAIT_V(8); PG8_WAIT_L(0); PG8_BAR; PG8_MMA(1, 0, At, B0); PG8_MMA(1, 1, At, B1); PG8_BAR; PG8_SCHED;
;             PG8_LDB(B0, 1, 0); PG8_LDB(B1, 1, 1); PG8_SCHED; PG8_LDA(At, 1, 0); PG8_STAGE(PG8_SA(0, 1), a2 + hstepA, voffA);
;             PG8_WAIT_V(8); PG8_WAIT_L(0); PG8_BAR; PG8_MMA(0, 0, At, B0); PG8_MMA(0, 1, At, B1); PG8_BAR; PG8_SCHED;
;             PG8_LDA(At, 1, 1); PG8_STAGE(PG8_SB(1, 0), b3, voffB); PG8_STAGE(PG8_SB(1, 1), b3 + hstepB, voffB); PG8_STAGE(PG8_SA(1, 0), a3, voffA);
;             PG8_WAIT_V(8); PG8_WAIT_L(0); PG8_BAR; PG8_MMA(1, 0, At, B0); PG8_MMA(1, 1, At, B1); PG8_BAR; PG8_SCHED;
	v_mfma_f32_16x16x32_bf16 v[124:127], v[154:157], v[186:189], v[124:127]
	v_mfma_f32_16x16x32_bf16 v[120:123], v[162:165], v[186:189], v[120:123]
	v_mfma_f32_16x16x32_bf16 v[116:119], v[154:157], v[198:201], v[116:119]
	v_mfma_f32_16x16x32_bf16 v[108:111], v[162:165], v[198:201], v[108:111]
	v_mfma_f32_16x16x32_bf16 v[100:103], v[154:157], v[206:209], v[100:103]
	v_mfma_f32_16x16x32_bf16 v[92:95], v[162:165], v[206:209], v[92:95]
	v_mfma_f32_16x16x32_bf16 v[84:87], v[154:157], v[214:217], v[84:87]
	v_mfma_f32_16x16x32_bf16 v[76:79], v[162:165], v[214:217], v[76:79]
	v_mfma_f32_16x16x32_bf16 v[124:127], v[158:161], v[194:197], v[124:127]
	v_mfma_f32_16x16x32_bf16 v[120:123], v[166:169], v[194:197], v[120:123]
	v_mfma_f32_16x16x32_bf16 v[116:119], v[158:161], v[202:205], v[116:119]
	v_mfma_f32_16x16x32_bf16 v[108:111], v[166:169], v[202:205], v[108:111]
	v_mfma_f32_16x16x32_bf16 v[100:103], v[158:161], v[210:213], v[100:103]
	v_mfma_f32_16x16x32_bf16 v[92:95], v[166:169], v[210:213], v[92:95]
	v_mfma_f32_16x16x32_bf16 v[84:87], v[158:161], v[218:221], v[84:87]
	v_mfma_f32_16x16x32_bf16 v[76:79], v[166:169], v[218:221], v[76:79]
	v_mfma_f32_16x16x32_bf16 v[112:115], v[170:173], v[186:189], v[112:115]
	v_mfma_f32_16x16x32_bf16 v[104:107], v[178:181], v[186:189], v[104:107]
	v_mfma_f32_16x16x32_bf16 v[96:99], v[170:173], v[198:201], v[96:99]
	v_mfma_f32_16x16x32_bf16 v[88:91], v[178:181], v[198:201], v[88:91]
	v_mfma_f32_16x16x32_bf16 v[80:83], v[170:173], v[206:209], v[80:83]
	v_mfma_f32_16x16x32_bf16 v[72:75], v[178:181], v[206:209], v[72:75]
	v_mfma_f32_16x16x32_bf16 v[68:71], v[170:173], v[214:217], v[68:71]
	v_mfma_f32_16x16x32_bf16 v[64:67], v[178:181], v[214:217], v[64:67]
	v_mfma_f32_16x16x32_bf16 v[112:115], v[174:177], v[194:197], v[112:115]
	v_mfma_f32_16x16x32_bf16 v[104:107], v[182:185], v[194:197], v[104:107]
	v_mfma_f32_16x16x32_bf16 v[96:99], v[174:177], v[202:205], v[96:99]
	v_mfma_f32_16x16x32_bf16 v[88:91], v[182:185], v[202:205], v[88:91]
	v_mfma_f32_16x16x32_bf16 v[80:83], v[174:177], v[210:213], v[80:83]
	v_mfma_f32_16x16x32_bf16 v[72:75], v[182:185], v[210:213], v[72:75]
	v_mfma_f32_16x16x32_bf16 v[68:71], v[174:177], v[218:221], v[68:71]
	v_mfma_f32_16x16x32_bf16 v[64:67], v[182:185], v[218:221], v[64:67]
	s_barrier
	s_add_i32 s51, s41, s30
	v_lshl_add_u64 v[144:145], s[24:25], 0, v[130:131]
	s_mov_b32 m0, s51
	ds_read_b128 v[186:189], v152 offset:16384
	ds_read_b128 v[194:197], v152 offset:17408
	ds_read_b128 v[198:201], v152 offset:18432
	ds_read_b128 v[202:205], v152 offset:19456
	ds_read_b128 v[206:209], v152 offset:20480
	ds_read_b128 v[210:213], v152 offset:21504
	ds_read_b128 v[214:217], v152 offset:22528
	ds_read_b128 v[218:221], v152 offset:23552
	global_load_lds_dwordx4 v[144:145], off
	s_add_i32 m0, s51, 0x2000
	s_add_u32 s68, s24, 0x80000
	v_lshl_add_u64 v[190:191], s[24:25], 0, v[134:135]
	s_addc_u32 s69, s25, 0
	s_add_i32 s51, s42, s30
	global_load_lds_dwordx4 v[190:191], off
	v_lshl_add_u64 v[222:223], s[68:69], 0, v[130:131]
	s_mov_b32 m0, s51
	v_lshl_add_u64 v[224:225], s[26:27], 0, v[132:133]
	global_load_lds_dwordx4 v[222:223], off
	v_lshl_add_u64 v[222:223], s[68:69], 0, v[134:135]
	s_add_i32 m0, s51, 0x2000
	s_nop 0
	global_load_lds_dwordx4 v[222:223], off
	v_lshl_add_u64 v[222:223], s[26:27], 0, v[128:129]
	s_mov_b32 m0, s21
	s_nop 0
	global_load_lds_dwordx4 v[222:223], off
	s_mov_b32 m0, s34
	s_nop 0
	global_load_lds_dwordx4 v[224:225], off
	s_waitcnt vmcnt(8)
	s_waitcnt lgkmcnt(0)
	s_barrier
	v_mfma_f32_16x16x32_bf16 v[60:63], v[154:157], v[186:189], v[60:63]
	v_mfma_f32_16x16x32_bf16 v[56:59], v[162:165], v[186:189], v[56:59]
	v_mfma_f32_16x16x32_bf16 v[52:55], v[154:157], v[198:201], v[52:55]
	v_mfma_f32_16x16x32_bf16 v[44:47], v[162:165], v[198:201], v[44:47]
	v_mfma_f32_16x16x32_bf16 v[36:39], v[154:157], v[206:209], v[36:39]
	v_mfma_f32_16x16x32_bf16 v[28:31], v[162:165], v[206:209], v[28:31]
	v_mfma_f32_16x16x32_bf16 v[20:23], v[154:157], v[214:217], v[20:23]
	v_mfma_f32_16x16x32_bf16 v[12:15], v[162:165], v[214:217], v[12:15]
	v_mfma_f32_16x16x32_bf16 v[60:63], v[158:161], v[194:197], v[60:63]
	v_mfma_f32_16x16x32_bf16 v[56:59], v[166:169], v[194:197], v[56:59]
	v_mfma_f32_16x16x32_bf16 v[52:55], v[158:161], v[202:205], v[52:55]
	v_mfma_f32_16x16x32_bf16 v[44:47], v[166:169], v[202:205], v[44:47]
	v_mfma_f32_16x16x32_bf16 v[36:39], v[158:161], v[210:213], v[36:39]
	v_mfma_f32_16x16x32_bf16 v[28:31], v[166:169], v[210:213], v[28:31]
	v_mfma_f32_16x16x32_bf16 v[20:23], v[158:161], v[218:221], v[20:23]
	v_mfma_f32_16x16x32_bf16 v[12:15], v[166:169], v[218:221], v[12:15]
	v_mfma_f32_16x16x32_bf16 v[48:51], v[170:173], v[186:189], v[48:51]
	v_mfma_f32_16x16x32_bf16 v[40:43], v[178:181], v[186:189], v[40:43]
	v_mfma_f32_16x16x32_bf16 v[32:35], v[170:173], v[198:201], v[32:35]
	v_mfma_f32_16x16x32_bf16 v[24:27], v[178:181], v[198:201], v[24:27]
	v_mfma_f32_16x16x32_bf16 v[16:19], v[170:173], v[206:209], v[16:19]
	v_mfma_f32_16x16x32_bf16 v[8:11], v[178:181], v[206:209], v[8:11]
	v_mfma_f32_16x16x32_bf16 v[4:7], v[170:173], v[214:217], v[4:7]
	v_mfma_f32_16x16x32_bf16 v[0:3], v[178:181], v[214:217], v[0:3]
	v_mfma_f32_16x16x32_bf16 v[48:51], v[174:177], v[194:197], v[48:51]
	v_mfma_f32_16x16x32_bf16 v[40:43], v[182:185], v[194:197], v[40:43]
	v_mfma_f32_16x16x32_bf16 v[32:35], v[174:177], v[202:205], v[32:35]
	v_mfma_f32_16x16x32_bf16 v[24:27], v[182:185], v[202:205], v[24:27]
	v_mfma_f32_16x16x32_bf16 v[16:19], v[174:177], v[210:213], v[16:19]
	v_mfma_f32_16x16x32_bf16 v[8:11], v[182:185], v[210:213], v[8:11]
	v_mfma_f32_16x16x32_bf16 v[4:7], v[174:177], v[218:221], v[4:7]
	v_mfma_f32_16x16x32_bf16 v[0:3], v[182:185], v[218:221], v[0:3]
	s_barrier
; #define PG8_STAGE(bufoff, gbase, voff) do { _Pragma("unroll") for (int _i = 0; _i < 2; ++_i) \
;         __builtin_amdgcn_global_load_lds((const unsigned*)((const char*)(gbase) + (voff)[_i]), (LAS unsigned*)(lds + (bufoff) + ldsw + _i * 8192), 16, 0, 0); } while (0)
; #define PG8_LDA(dst, b, h) do { _Pragma("unroll") for (int m = 0; m < 4; ++m) _Pragma("unroll") for (int k = 0; k < 2; ++k) dst[m][k] = *(const LAS bf16x8*)(lds + PG8_SA(b, h) + aoff + m * 2048 + k * 1024); } while (0)
; #define PG8_LDB(dst, b, h) do { _Pragma("unroll") for (int n = 0; n < 2; ++n) _Pragma("unroll") for (int k = 0; k < 2; ++k) dst[n][k] = *(const LAS bf16x8*)(lds + PG8_SB(b, h) + boff + n * 2048 + k * 1024); } while (0)
; #define PG8_MMA(ai, bj, At, Bt) do { __builtin_amdgcn_s_setprio(1); _Pragma("unroll") for (int m = 0; m < 4; ++m) _Pragma("unroll") for (int n = 0; n < 2; ++n) _Pragma("unroll") for (int k = 0; k < 2; ++k) \
;         acc[ai][bj][m][n] = __builtin_amdgcn_mfma_f32_16x16x32_bf16(Bt[n][k], At[m][k], acc[ai][bj][m][n], 0, 0, 0); __builtin_amdgcn_s_setprio(0); } while (0)
; #define PG8_BAR __builtin_amdgcn_s_barrier()
; template <class Epi, class Sched = StaticOrder, class EpiSub = NoSub, bool FAST = false>
; __device__ __forceinline__ void gemm_phase(LAS unsigned char* lds, const Gemm g, const Sched& S, const Epi& E, const EpiSub& ES = EpiSub()) {
;     ...
;             PG8_LDB(B0, 0, 0); PG8_LDB(B1, 0, 1); PG8_SCHED; PG8_LDA(At, 0, 0); PG8_STAGE(PG8_SA(1, 1), a1 + hstepA, voffA);
;             PG8_WAIT_V(8); PG8_WAIT_L(0); PG8_BAR; PG8_MMA(0, 0, At, B0); PG8_MMA(0, 1, At, B1); PG8_BAR; PG8_SCHED;
;             PG8_LDA(At, 0, 1); PG8_STAGE(PG8_SB(0, 0), b2, voffB); PG8_STAGE(PG8_SB(0, 1), b2 + hstepB, voffB); PG8_STAGE(PG8_SA(0, 0), a2, voffA);
;             PG8_WAIT_V(8); PG8_WAIT_L(0); PG8_BAR; PG8_MMA(1, 0, At, B0); PG8_MMA(1, 1, At, B1); PG8_BAR; PG8_SCHED;
;             PG8_LDB(B0, 1, 0); PG8_LDB(B1, 1, 1); PG8_SCHED; PG8_LDA(At, 1, 0); PG8_STAGE(PG8_SA(0, 1), a2 + hstepA, voffA);
;             PG8_WAIT_V(8); PG8_WAIT_L(0); PG8_BAR; PG8_MMA(0, 0, At, B0); PG8_MMA(0, 1, At, B1); PG8_BAR; PG8_SCHED;
;             PG8_LDA(At, 1, 1); PG8_STAGE(PG8_SB(1, 0), b3, voffB); PG8_STAGE(PG8_SB(1, 1), b3 + hstepB, voffB); PG8_STAGE(PG8_SA(1, 0), a3, voffA);
;             PG8_WAIT_V(8); PG8_WAIT_L(0); PG8_BAR; PG8_MMA(1, 0, At, B0); PG8_MMA(1, 1, At, B1); PG8_BAR; PG8_SCHED;
	s_add_i32 s51, 0, 0x18000
	v_add_u32_e32 v153, s51, v148
	s_add_i32 s68, 0, 0x1c000
	ds_read_b128 v[154:157], v153
	ds_read_b128 v[158:161], v153 offset:1024
	ds_read_b128 v[162:165], v153 offset:2048
	ds_read_b128 v[166:169], v153 offset:3072
	v_add_u32_e32 v153, s68, v148
	ds_read_b128 v[170:173], v153
	ds_read_b128 v[174:177], v153 offset:1024
	ds_read_b128 v[178:181], v153 offset:2048
	ds_read_b128 v[182:185], v153 offset:3072
	s_add_u32 s26, s26, 0x80000
	s_addc_u32 s27, s27, 0
	s_mov_b32 m0, s35
	v_lshl_add_u64 v[226:227], s[26:27], 0, v[128:129]
	ds_read_b128 v[186:189], v152 offset:32768
	ds_read_b128 v[194:197], v152 offset:33792
	ds_read_b128 v[198:201], v152 offset:34816
	ds_read_b128 v[202:205], v152 offset:35840
	ds_read_b128 v[206:209], v152 offset:36864
	ds_read_b128 v[210:213], v152 offset:37888
	ds_read_b128 v[214:217], v152 offset:38912
	ds_read_b128 v[218:221], v152 offset:39936
	global_load_lds_dwordx4 v[226:227], off
	v_lshl_add_u64 v[226:227], s[26:27], 0, v[132:133]
	s_mov_b32 m0, s36
	s_nop 0
	global_load_lds_dwordx4 v[226:227], off
	s_waitcnt vmcnt(8)
	s_waitcnt lgkmcnt(0)
	s_barrier
	v_mfma_f32_16x16x32_bf16 v[124:127], v[154:157], v[186:189], v[124:127]
	v_mfma_f32_16x16x32_bf16 v[120:123], v[162:165], v[186:189], v[120:123]
	v_mfma_f32_16x16x32_bf16 v[116:119], v[154:157], v[198:201], v[116:119]
	v_mfma_f32_16x16x32_bf16 v[108:111], v[162:165], v[198:201], v[108:111]
	v_mfma_f32_16x16x32_bf16 v[100:103], v[154:157], v[206:209], v[100:103]
	v_mfma_f32_16x16x32_bf16 v[92:95], v[162:165], v[206:209], v[92:95]
	v_mfma_f32_16x16x32_bf16 v[84:87], v[154:157], v[214:217], v[84:87]
	v_mfma_f32_16x16x32_bf16 v[76:79], v[162:165], v[214:217], v[76:79]
	v_mfma_f32_16x16x32_bf16 v[124:127], v[158:161], v[194:197], v[124:127]
	v_mfma_f32_16x16x32_bf16 v[120:123], v[166:169], v[194:197], v[120:123]
	v_mfma_f32_16x16x32_bf16 v[116:119], v[158:161], v[202:205], v[116:119]
	v_mfma_f32_16x16x32_bf16 v[108:111], v[166:169], v[202:205], v[108:111]
	v_mfma_f32_16x16x32_bf16 v[100:103], v[158:161], v[210:213], v[100:103]
	v_mfma_f32_16x16x32_bf16 v[92:95], v[166:169], v[210:213], v[92:95]
	v_mfma_f32_16x16x32_bf16 v[84:87], v[158:161], v[218:221], v[84:87]
	v_mfma_f32_16x16x32_bf16 v[76:79], v[166:169], v[218:221], v[76:79]
	v_mfma_f32_16x16x32_bf16 v[112:115], v[170:173], v[186:189], v[112:115]
	v_mfma_f32_16x16x32_bf16 v[104:107], v[178:181], v[186:189], v[104:107]
	v_mfma_f32_16x16x32_bf16 v[96:99], v[170:173], v[198:201], v[96:99]
	v_mfma_f32_16x16x32_bf16 v[88:91], v[178:181], v[198:201], v[88:91]
	v_mfma_f32_16x16x32_bf16 v[80:83], v[170:173], v[206:209], v[80:83]
	v_mfma_f32_16x16x32_bf16 v[72:75], v[178:181], v[206:209], v[72:75]
	v_mfma_f32_16x16x32_bf16 v[68:71], v[170:173], v[214:217], v[68:71]
	v_mfma_f32_16x16x32_bf16 v[64:67], v[178:181], v[214:217], v[64:67]
	v_mfma_f32_16x16x32_bf16 v[112:115], v[174:177], v[194:197], v[112:115]
	v_mfma_f32_16x16x32_bf16 v[104:107], v[182:185], v[194:197], v[104:107]
	v_mfma_f32_16x16x32_bf16 v[96:99], v[174:177], v[202:205], v[96:99]
	v_mfma_f32_16x16x32_bf16 v[88:91], v[182:185], v[202:205], v[88:91]
	v_mfma_f32_16x16x32_bf16 v[80:83], v[174:177], v[210:213], v[80:83]
	v_mfma_f32_16x16x32_bf16 v[72:75], v[182:185], v[210:213], v[72:75]
	v_mfma_f32_16x16x32_bf16 v[68:71], v[174:177], v[218:221], v[68:71]
	v_mfma_f32_16x16x32_bf16 v[64:67], v[182:185], v[218:221], v[64:67]
	s_barrier
	s_add_i32 s26, s51, s30
	v_lshl_add_u64 v[144:145], v[144:145], 0, s[8:9]
	s_mov_b32 m0, s26
	ds_read_b128 v[186:189], v152 offset:49152
	ds_read_b128 v[194:197], v152 offset:50176
	ds_read_b128 v[198:201], v152 offset:51200
	ds_read_b128 v[202:205], v152 offset:52224
	ds_read_b128 v[206:209], v152 offset:53248
	ds_read_b128 v[210:213], v152 offset:54272
	ds_read_b128 v[214:217], v152 offset:55296
	ds_read_b128 v[218:221], v152 offset:56320
	global_load_lds_dwordx4 v[144:145], off
	s_add_i32 m0, s26, 0x2000
	s_add_u32 s24, s24, 0x80080
	v_lshl_add_u64 v[144:145], v[190:191], 0, s[8:9]
	s_addc_u32 s25, s25, 0
	s_add_i32 s26, s68, s30
	global_load_lds_dwordx4 v[144:145], off
	v_lshl_add_u64 v[144:145], s[24:25], 0, v[130:131]
	s_mov_b32 m0, s26
	s_nop 0
	global_load_lds_dwordx4 v[144:145], off
	v_lshl_add_u64 v[144:145], s[24:25], 0, v[134:135]
	s_add_i32 m0, s26, 0x2000
	s_nop 0
	global_load_lds_dwordx4 v[144:145], off
	v_lshl_add_u64 v[144:145], v[222:223], 0, s[8:9]
	s_mov_b32 m0, s39
	s_nop 0
	global_load_lds_dwordx4 v[144:145], off
	v_lshl_add_u64 v[144:145], v[224:225], 0, s[8:9]
	s_mov_b32 m0, s40
	s_nop 0
	global_load_lds_dwordx4 v[144:145], off
	s_add_i32 s50, s50, 2
	s_add_u32 s22, s22, 0x100
	s_addc_u32 s23, s23, 0
	s_add_u32 s48, s48, 0x100
	s_addc_u32 s49, s49, 0
	s_waitcnt vmcnt(8)
	s_waitcnt lgkmcnt(0)
	s_barrier
	v_mfma_f32_16x16x32_bf16 v[60:63], v[154:157], v[186:189], v[60:63]
	v_mfma_f32_16x16x32_bf16 v[56:59], v[162:165], v[186:189], v[56:59]
	v_mfma_f32_16x16x32_bf16 v[52:55], v[154:157], v[198:201], v[52:55]
	v_mfma_f32_16x16x32_bf16 v[44:47], v[162:165], v[198:201], v[44:47]
	v_mfma_f32_16x16x32_bf16 v[36:39], v[154:157], v[206:209], v[36:39]
	v_mfma_f32_16x16x32_bf16 v[28:31], v[162:165], v[206:209], v[28:31]
	v_mfma_f32_16x16x32_bf16 v[20:23], v[154:157], v[214:217], v[20:23]
	v_mfma_f32_16x16x32_bf16 v[12:15], v[162:165], v[214:217], v[12:15]
	v_mfma_f32_16x16x32_bf16 v[60:63], v[158:161], v[194:197], v[60:63]
	v_mfma_f32_16x16x32_bf16 v[56:59], v[166:169], v[194:197], v[56:59]
	v_mfma_f32_16x16x32_bf16 v[52:55], v[158:161], v[202:205], v[52:55]
	v_mfma_f32_16x16x32_bf16 v[44:47], v[166:169], v[202:205], v[44:47]
	v_mfma_f32_16x16x32_bf16 v[36:39], v[158:161], v[210:213], v[36:39]
	v_mfma_f32_16x16x32_bf16 v[28:31], v[166:169], v[210:213], v[28:31]
	v_mfma_f32_16x16x32_bf16 v[20:23], v[158:161], v[218:221], v[20:23]
	v_mfma_f32_16x16x32_bf16 v[12:15], v[166:169], v[218:221], v[12:15]
	v_mfma_f32_16x16x32_bf16 v[48:51], v[170:173], v[186:189], v[48:51]
	v_mfma_f32_16x16x32_bf16 v[40:43], v[178:181], v[186:189], v[40:43]
	v_mfma_f32_16x16x32_bf16 v[32:35], v[170:173], v[198:201], v[32:35]
	v_mfma_f32_16x16x32_bf16 v[24:27], v[178:181], v[198:201], v[24:27]
	v_mfma_f32_16x16x32_bf16 v[16:19], v[170:173], v[206:209], v[16:19]
	v_mfma_f32_16x16x32_bf16 v[8:11], v[178:181], v[206:209], v[8:11]
	v_mfma_f32_16x16x32_bf16 v[4:7], v[170:173], v[214:217], v[4:7]
	v_mfma_f32_16x16x32_bf16 v[0:3], v[178:181], v[214:217], v[0:3]
	v_mfma_f32_16x16x32_bf16 v[48:51], v[174:177], v[194:197], v[48:51]
	v_mfma_f32_16x16x32_bf16 v[40:43], v[182:185], v[194:197], v[40:43]
	v_mfma_f32_16x16x32_bf16 v[32:35], v[174:177], v[202:205], v[32:35]
	v_mfma_f32_16x16x32_bf16 v[24:27], v[182:185], v[202:205], v[24:27]
	v_mfma_f32_16x16x32_bf16 v[16:19], v[174:177], v[210:213], v[16:19]
	v_mfma_f32_16x16x32_bf16 v[8:11], v[182:185], v[210:213], v[8:11]
	v_mfma_f32_16x16x32_bf16 v[4:7], v[174:177], v[218:221], v[4:7]
	v_mfma_f32_16x16x32_bf16 v[0:3], v[182:185], v[218:221], v[0:3]
	s_barrier
	s_cmp_gt_u32 s50, 29
	s_cbranch_scc0 .LBB0_216

; #define PG8_STAGE(bufoff, gbase, voff) do { _Pragma("unroll") for (int _i = 0; _i < 2; ++_i) \
;         __builtin_amdgcn_global_load_lds((const unsigned*)((const char*)(gbase) + (voff)[_i]), (LAS unsigned*)(lds + (bufoff) + ldsw + _i * 8192), 16, 0, 0); } while (0)
; #define PG8_WAIT_V(n) asm volatile("s_waitcnt vmcnt(" #n ")" ::: "memory")
; #define PG8_BAR __builtin_amdgcn_s_barrier()
; template <class Epi, class Sched = StaticOrder, class EpiSub = NoSub, bool FAST = false>
; __device__ __forceinline__ void gemm_phase(LAS unsigned char* lds, const Gemm g, const Sched& S, const Epi& E, const EpiSub& ES = EpiSub()) {
;     ...
;         const size_t nko = (has_next && nxt.kb >= 0) ? nxt.kb * ksubB : 0;
;         const char* nA = has_next ? (const char*)g.A + (size_t)nxt.pm * tstepA + (size_t)nxt.pn * g.acs + nko : cA; const char* nB = has_next ? (const char*)g.Bt + (size_t)nxt.pn * tstepB + nko : cB;
;         const int nt = cur.kb < 0 ? ntMain : ntSub;
;         for (int t = 0; t < nt; t += 2) {
;             const bool last = (t == nt - 2);
;             const char* a1 = cA + (size_t)(t + 1) * kstep;
;             const char* a2 = last ? nA : cA + (size_t)(t + 2) * kstep; const char* b2 = last ? nB : cB + (size_t)(t + 2) * kstep;
;             const char* a3 = a2 + kstep; const char* b3 = b2 + kstep;
;             if constexpr (FAST && PG8_SP2) {
;             PG8_LDB(B0, 0, 0); PG8_LDB(B1, 0, 1); PG8_SCHED; PG8_LDA(At, 0, 0); PG8_STAGE(PG8_SA(1, 1), a1 + hstepA, voffA);
;             PG8_WAIT_V(8); PG8_WAIT_L(0); PG8_BAR; PG8_MMA(0, 0, At, B0); PG8_MMA(0, 1, At, B1); PG8_BAR; PG8_SCHED;
;             PG8_LDA(At, 0, 1); PG8_STAGE(PG8_SB(0, 0), b2, voffB); PG8_STAGE(PG8_SB(0, 1), b2 + hstepB, voffB); PG8_STAGE(PG8_SA(0, 0), a2, voffA);
;             PG8_WAIT_V(8); PG8_WAIT_L(0); PG8_BAR; PG8_MMA(1, 0, At, B0); PG8_MMA(1, 1, At, B1); PG8_BAR; PG8_SCHED;
;             PG8_LDB(B0, 1, 0); PG8_LDB(B1, 1, 1); PG8_SCHED; PG8_LDA(At, 1, 0); PG8_STAGE(PG8_SA(0, 1), a2 + hstepA, voffA);
;             PG8_WAIT_V(8); PG8_WAIT_L(0); PG8_BAR; PG8_MMA(0, 0, At, B0); PG8_MMA(0, 1, At, B1); PG8_BAR; PG8_SCHED;
;             PG8_LDA(At, 1, 1); PG8_STAGE(PG8_SB(1, 0), b3, voffB); PG8_STAGE(PG8_SB(1, 1), b3 + hstepB, voffB); PG8_STAGE(PG8_SA(1, 0), a3, voffA);
;             PG8_WAIT_V(8); PG8_WAIT_L(0); PG8_BAR; PG8_MMA(1, 0, At, B0); PG8_MMA(1, 1, At, B1); PG8_BAR; PG8_SCHED;
.LBB0_599:
	s_cmp_gt_i32 s8, -1
	s_cselect_b64 s[30:31], -1, 0
	s_and_b64 s[30:31], s[28:29], s[30:31]
	s_lshl_b64 s[36:37], s[8:9], 9
	s_and_b64 s[30:31], s[30:31], exec
	s_cselect_b32 s7, s37, 0
	s_cselect_b32 s33, s36, 0
	s_ashr_i32 s27, s26, 31
	s_lshl_b64 s[30:31], s[26:27], 19
	s_add_u32 s1, s78, s30
	s_addc_u32 s5, s79, s31
	s_add_u32 s30, s1, s33
	s_addc_u32 s31, s5, s7
	s_and_b64 s[36:37], s[28:29], exec
	s_cselect_b32 s1, s31, s41
	s_cselect_b32 s5, s30, s40
	s_ashr_i32 s25, s24, 31
	s_lshl_b64 s[36:37], s[24:25], 19
	s_add_u32 s25, s2, s36
	s_addc_u32 s27, s3, s37
	s_add_u32 s36, s25, s33
	s_addc_u32 s37, s27, s7
	s_and_b64 s[38:39], s[28:29], exec
	s_cselect_b32 s7, s37, s43
	s_cselect_b32 s25, s36, s42
	s_cmp_gt_i32 s0, -1
	s_cselect_b64 s[38:39], -1, 0
	s_cmp_lt_i32 s0, 0
	s_cselect_b32 s27, 16, 4
	s_add_i32 s33, s27, -2
	s_add_u32 s40, s40, 0x40080
	s_addc_u32 s41, s41, 0
	s_add_u32 s48, s42, 0x100
	s_mov_b32 s50, 0
	s_addc_u32 s49, s43, 0
	ds_read_b128 v[100:103], v186
	ds_read_b128 v[112:115], v186 offset:1024
	ds_read_b128 v[124:127], v186 offset:2048
	ds_read_b128 v[136:139], v186 offset:3072
	ds_read_b128 v[144:147], v187
	ds_read_b128 v[148:151], v187 offset:1024
	ds_read_b128 v[152:155], v187 offset:2048
	ds_read_b128 v[170:173], v187 offset:3072
	s_add_i32 s51, s50, 2
	s_add_u32 s42, s40, 0xfffc0080
	s_addc_u32 s43, s41, -1
	s_cmp_eq_u32 s33, s50
	s_cselect_b32 s53, s1, s43
	s_cselect_b32 s52, s5, s42
	s_cselect_b32 s43, s7, s49
	s_cselect_b32 s42, s25, s48
	v_lshl_add_u64 v[190:191], s[40:41], 0, v[164:165]
	s_add_i32 m0, s55, 0xc000
	ds_read_b128 v[174:177], v188
	ds_read_b128 v[178:181], v188 offset:1024
	ds_read_b128 v[194:197], v188 offset:2048
	ds_read_b128 v[198:201], v188 offset:3072
	ds_read_b128 v[202:205], v188 offset:4096
	ds_read_b128 v[206:209], v188 offset:5120
	ds_read_b128 v[210:213], v188 offset:6144
	ds_read_b128 v[214:217], v188 offset:7168
	global_load_lds_dwordx4 v[190:191], off
	v_lshl_add_u64 v[190:191], s[40:41], 0, v[166:167]
	s_add_i32 m0, s55, 0xe000
	s_nop 0
	global_load_lds_dwordx4 v[190:191], off
	s_waitcnt vmcnt(8)
	s_waitcnt lgkmcnt(0)
	s_barrier
	v_mfma_f32_16x16x32_bf16 v[140:143], v[100:103], v[174:177], 0
	v_mfma_f32_16x16x32_bf16 v[132:135], v[124:127], v[174:177], 0
	v_mfma_f32_16x16x32_bf16 v[116:119], v[100:103], v[194:197], 0
	v_mfma_f32_16x16x32_bf16 v[108:111], v[124:127], v[194:197], 0
	v_mfma_f32_16x16x32_bf16 v[92:95], v[100:103], v[202:205], 0
	v_mfma_f32_16x16x32_bf16 v[88:91], v[124:127], v[202:205], 0
	v_mfma_f32_16x16x32_bf16 v[76:79], v[100:103], v[210:213], 0
	v_mfma_f32_16x16x32_bf16 v[72:75], v[124:127], v[210:213], 0
	v_mfma_f32_16x16x32_bf16 v[140:143], v[112:115], v[178:181], v[140:143]
	v_mfma_f32_16x16x32_bf16 v[132:135], v[136:139], v[178:181], v[132:135]
	v_mfma_f32_16x16x32_bf16 v[116:119], v[112:115], v[198:201], v[116:119]
	v_mfma_f32_16x16x32_bf16 v[108:111], v[136:139], v[198:201], v[108:111]
	v_mfma_f32_16x16x32_bf16 v[92:95], v[112:115], v[206:209], v[92:95]
	v_mfma_f32_16x16x32_bf16 v[88:91], v[136:139], v[206:209], v[88:91]
	v_mfma_f32_16x16x32_bf16 v[76:79], v[112:115], v[214:217], v[76:79]
	v_mfma_f32_16x16x32_bf16 v[72:75], v[136:139], v[214:217], v[72:75]
	v_mfma_f32_16x16x32_bf16 v[128:131], v[144:147], v[174:177], 0
	v_mfma_f32_16x16x32_bf16 v[120:123], v[152:155], v[174:177], 0
	v_mfma_f32_16x16x32_bf16 v[104:107], v[144:147], v[194:197], 0
	v_mfma_f32_16x16x32_bf16 v[96:99], v[152:155], v[194:197], 0
	v_mfma_f32_16x16x32_bf16 v[84:87], v[144:147], v[202:205], 0
	v_mfma_f32_16x16x32_bf16 v[80:83], v[152:155], v[202:205], 0
	v_mfma_f32_16x16x32_bf16 v[68:71], v[144:147], v[210:213], 0
	v_mfma_f32_16x16x32_bf16 v[64:67], v[152:155], v[210:213], 0
	v_mfma_f32_16x16x32_bf16 v[128:131], v[148:151], v[178:181], v[128:131]
	v_mfma_f32_16x16x32_bf16 v[120:123], v[170:173], v[178:181], v[120:123]
	v_mfma_f32_16x16x32_bf16 v[104:107], v[148:151], v[198:201], v[104:107]
	v_mfma_f32_16x16x32_bf16 v[96:99], v[170:173], v[198:201], v[96:99]
	v_mfma_f32_16x16x32_bf16 v[84:87], v[148:151], v[206:209], v[84:87]
	v_mfma_f32_16x16x32_bf16 v[80:83], v[170:173], v[206:209], v[80:83]
	v_mfma_f32_16x16x32_bf16 v[68:71], v[148:151], v[214:217], v[68:71]
	v_mfma_f32_16x16x32_bf16 v[64:67], v[170:173], v[214:217], v[64:67]
	s_barrier
	s_add_i32 s50, s75, s54
	v_lshl_add_u64 v[190:191], s[42:43], 0, v[158:159]
	s_mov_b32 m0, s50
	ds_read_b128 v[174:177], v188 offset:16384
	ds_read_b128 v[178:181], v188 offset:17408
	ds_read_b128 v[194:197], v188 offset:18432
	ds_read_b128 v[198:201], v188 offset:19456
	ds_read_b128 v[202:205], v188 offset:20480
	ds_read_b128 v[206:209], v188 offset:21504
	ds_read_b128 v[210:213], v188 offset:22528
	ds_read_b128 v[214:217], v188 offset:23552
	global_load_lds_dwordx4 v[190:191], off
	s_add_i32 m0, s50, 0x2000
	s_add_u32 s70, s42, 0x40000
	v_lshl_add_u64 v[218:219], s[42:43], 0, v[162:163]
	s_addc_u32 s71, s43, 0
	s_add_i32 s50, s80, s54
	global_load_lds_dwordx4 v[218:219], off
	v_lshl_add_u64 v[220:221], s[70:71], 0, v[158:159]
	s_mov_b32 m0, s50
	v_lshl_add_u64 v[222:223], s[52:53], 0, v[160:161]
	global_load_lds_dwordx4 v[220:221], off
	v_lshl_add_u64 v[220:221], s[70:71], 0, v[162:163]
	s_add_i32 m0, s50, 0x2000
	s_nop 0
	global_load_lds_dwordx4 v[220:221], off
	v_lshl_add_u64 v[220:221], s[52:53], 0, v[156:157]
	s_mov_b32 m0, s55
	s_nop 0
	global_load_lds_dwordx4 v[220:221], off
	s_mov_b32 m0, s56
	s_nop 0
	global_load_lds_dwordx4 v[222:223], off
	s_waitcnt vmcnt(8)
	s_waitcnt lgkmcnt(0)
	s_barrier
; #define PG8_STAGE(bufoff, gbase, voff) do { _Pragma("unroll") for (int _i = 0; _i < 2; ++_i) \
;         __builtin_amdgcn_global_load_lds((const unsigned*)((const char*)(gbase) + (voff)[_i]), (LAS unsigned*)(lds + (bufoff) + ldsw + _i * 8192), 16, 0, 0); } while (0)
; #define PG8_LDA(dst, b, h) do { _Pragma("unroll") for (int m = 0; m < 4; ++m) _Pragma("unroll") for (int k = 0; k < 2; ++k) dst[m][k] = *(const LAS bf16x8*)(lds + PG8_SA(b, h) + aoff + m * 2048 + k * 1024); } while (0)
; #define PG8_LDB(dst, b, h) do { _Pragma("unroll") for (int n = 0; n < 2; ++n) _Pragma("unroll") for (int k = 0; k < 2; ++k) dst[n][k] = *(const LAS bf16x8*)(lds + PG8_SB(b, h) + boff + n * 2048 + k * 1024); } while (0)
; #define PG8_MMA(ai, bj, At, Bt) do { __builtin_amdgcn_s_setprio(1); _Pragma("unroll") for (int m = 0; m < 4; ++m) _Pragma("unroll") for (int n = 0; n < 2; ++n) _Pragma("unroll") for (int k = 0; k < 2; ++k) \
;         acc[ai][bj][m][n] = __builtin_amdgcn_mfma_f32_16x16x32_bf16(Bt[n][k], At[m][k], acc[ai][bj][m][n], 0, 0, 0); __builtin_amdgcn_s_setprio(0); } while (0)
; #define PG8_BAR __builtin_amdgcn_s_barrier()
; template <class Epi, class Sched = StaticOrder, class EpiSub = NoSub, bool FAST = false>
; __device__ __forceinline__ void gemm_phase(LAS unsigned char* lds, const Gemm g, const Sched& S, const Epi& E, const EpiSub& ES = EpiSub()) {
;     ...
;             PG8_LDB(B0, 0, 0); PG8_LDB(B1, 0, 1); PG8_SCHED; PG8_LDA(At, 0, 0); PG8_STAGE(PG8_SA(1, 1), a1 + hstepA, voffA);
;             PG8_WAIT_V(8); PG8_WAIT_L(0); PG8_BAR; PG8_MMA(0, 0, At, B0); PG8_MMA(0, 1, At, B1); PG8_BAR; PG8_SCHED;
;             PG8_LDA(At, 0, 1); PG8_STAGE(PG8_SB(0, 0), b2, voffB); PG8_STAGE(PG8_SB(0, 1), b2 + hstepB, voffB); PG8_STAGE(PG8_SA(0, 0), a2, voffA);
;             PG8_WAIT_V(8); PG8_WAIT_L(0); PG8_BAR; PG8_MMA(1, 0, At, B0); PG8_MMA(1, 1, At, B1); PG8_BAR; PG8_SCHED;
;             PG8_LDB(B0, 1, 0); PG8_LDB(B1, 1, 1); PG8_SCHED; PG8_LDA(At, 1, 0); PG8_STAGE(PG8_SA(0, 1), a2 + hstepA, voffA);
;             PG8_WAIT_V(8); PG8_WAIT_L(0); PG8_BAR; PG8_MMA(0, 0, At, B0); PG8_MMA(0, 1, At, B1); PG8_BAR; PG8_SCHED;
;             PG8_LDA(At, 1, 1); PG8_STAGE(PG8_SB(1, 0), b3, voffB); PG8_STAGE(PG8_SB(1, 1), b3 + hstepB, voffB); PG8_STAGE(PG8_SA(1, 0), a3, voffA);
;             PG8_WAIT_V(8); PG8_WAIT_L(0); PG8_BAR; PG8_MMA(1, 0, At, B0); PG8_MMA(1, 1, At, B1); PG8_BAR; PG8_SCHED;
	v_mfma_f32_16x16x32_bf16 v[60:63], v[100:103], v[174:177], 0
	v_mfma_f32_16x16x32_bf16 v[56:59], v[124:127], v[174:177], 0
	v_mfma_f32_16x16x32_bf16 v[44:47], v[100:103], v[194:197], 0
	v_mfma_f32_16x16x32_bf16 v[40:43], v[124:127], v[194:197], 0
	v_mfma_f32_16x16x32_bf16 v[28:31], v[100:103], v[202:205], 0
	v_mfma_f32_16x16x32_bf16 v[24:27], v[124:127], v[202:205], 0
	v_mfma_f32_16x16x32_bf16 v[12:15], v[100:103], v[210:213], 0
	v_mfma_f32_16x16x32_bf16 v[8:11], v[124:127], v[210:213], 0
	v_mfma_f32_16x16x32_bf16 v[60:63], v[112:115], v[178:181], v[60:63]
	v_mfma_f32_16x16x32_bf16 v[56:59], v[136:139], v[178:181], v[56:59]
	v_mfma_f32_16x16x32_bf16 v[44:47], v[112:115], v[198:201], v[44:47]
	v_mfma_f32_16x16x32_bf16 v[40:43], v[136:139], v[198:201], v[40:43]
	v_mfma_f32_16x16x32_bf16 v[28:31], v[112:115], v[206:209], v[28:31]
	v_mfma_f32_16x16x32_bf16 v[24:27], v[136:139], v[206:209], v[24:27]
	v_mfma_f32_16x16x32_bf16 v[12:15], v[112:115], v[214:217], v[12:15]
	v_mfma_f32_16x16x32_bf16 v[8:11], v[136:139], v[214:217], v[8:11]
	v_mfma_f32_16x16x32_bf16 v[52:55], v[144:147], v[174:177], 0
	v_mfma_f32_16x16x32_bf16 v[48:51], v[152:155], v[174:177], 0
	v_mfma_f32_16x16x32_bf16 v[36:39], v[144:147], v[194:197], 0
	v_mfma_f32_16x16x32_bf16 v[32:35], v[152:155], v[194:197], 0
	v_mfma_f32_16x16x32_bf16 v[20:23], v[144:147], v[202:205], 0
	v_mfma_f32_16x16x32_bf16 v[16:19], v[152:155], v[202:205], 0
	v_mfma_f32_16x16x32_bf16 v[4:7], v[144:147], v[210:213], 0
	v_mfma_f32_16x16x32_bf16 v[0:3], v[152:155], v[210:213], 0
	v_mfma_f32_16x16x32_bf16 v[52:55], v[148:151], v[178:181], v[52:55]
	v_mfma_f32_16x16x32_bf16 v[48:51], v[170:173], v[178:181], v[48:51]
	v_mfma_f32_16x16x32_bf16 v[36:39], v[148:151], v[198:201], v[36:39]
	v_mfma_f32_16x16x32_bf16 v[32:35], v[170:173], v[198:201], v[32:35]
	v_mfma_f32_16x16x32_bf16 v[20:23], v[148:151], v[206:209], v[20:23]
	v_mfma_f32_16x16x32_bf16 v[16:19], v[170:173], v[206:209], v[16:19]
	v_mfma_f32_16x16x32_bf16 v[4:7], v[148:151], v[214:217], v[4:7]
	v_mfma_f32_16x16x32_bf16 v[0:3], v[170:173], v[214:217], v[0:3]
	s_barrier
	s_add_i32 s50, 0, 0x18000
	s_add_i32 s70, 0, 0x1c000
	v_add_u32_e32 v136, s50, v183
	v_add_u32_e32 v170, s70, v183
	ds_read_b128 v[100:103], v136
	ds_read_b128 v[112:115], v136 offset:1024
	ds_read_b128 v[124:127], v136 offset:2048
	ds_read_b128 v[136:139], v136 offset:3072
	ds_read_b128 v[144:147], v170
	ds_read_b128 v[148:151], v170 offset:1024
	ds_read_b128 v[152:155], v170 offset:2048
	ds_read_b128 v[170:173], v170 offset:3072
	s_add_u32 s52, s52, 0x40000
	s_addc_u32 s53, s53, 0
	s_mov_b32 m0, s57
	v_lshl_add_u64 v[224:225], s[52:53], 0, v[156:157]
	ds_read_b128 v[174:177], v188 offset:32768
	ds_read_b128 v[178:181], v188 offset:33792
	ds_read_b128 v[194:197], v188 offset:34816
	ds_read_b128 v[198:201], v188 offset:35840
	ds_read_b128 v[202:205], v188 offset:36864
	ds_read_b128 v[206:209], v188 offset:37888
	ds_read_b128 v[210:213], v188 offset:38912
	ds_read_b128 v[214:217], v188 offset:39936
	global_load_lds_dwordx4 v[224:225], off
	v_lshl_add_u64 v[224:225], s[52:53], 0, v[160:161]
	s_mov_b32 m0, s58
	s_nop 0
	global_load_lds_dwordx4 v[224:225], off
	s_waitcnt vmcnt(8)
	s_waitcnt lgkmcnt(0)
	s_barrier
	v_mfma_f32_16x16x32_bf16 v[140:143], v[100:103], v[174:177], v[140:143]
	v_mfma_f32_16x16x32_bf16 v[132:135], v[124:127], v[174:177], v[132:135]
	v_mfma_f32_16x16x32_bf16 v[116:119], v[100:103], v[194:197], v[116:119]
	v_mfma_f32_16x16x32_bf16 v[108:111], v[124:127], v[194:197], v[108:111]
	v_mfma_f32_16x16x32_bf16 v[92:95], v[100:103], v[202:205], v[92:95]
	v_mfma_f32_16x16x32_bf16 v[88:91], v[124:127], v[202:205], v[88:91]
	v_mfma_f32_16x16x32_bf16 v[76:79], v[100:103], v[210:213], v[76:79]
	v_mfma_f32_16x16x32_bf16 v[72:75], v[124:127], v[210:213], v[72:75]
	v_mfma_f32_16x16x32_bf16 v[140:143], v[112:115], v[178:181], v[140:143]
	v_mfma_f32_16x16x32_bf16 v[132:135], v[136:139], v[178:181], v[132:135]
	v_mfma_f32_16x16x32_bf16 v[116:119], v[112:115], v[198:201], v[116:119]
	v_mfma_f32_16x16x32_bf16 v[108:111], v[136:139], v[198:201], v[108:111]
	v_mfma_f32_16x16x32_bf16 v[92:95], v[112:115], v[206:209], v[92:95]
	v_mfma_f32_16x16x32_bf16 v[88:91], v[136:139], v[206:209], v[88:91]
	v_mfma_f32_16x16x32_bf16 v[76:79], v[112:115], v[214:217], v[76:79]
	v_mfma_f32_16x16x32_bf16 v[72:75], v[136:139], v[214:217], v[72:75]
	v_mfma_f32_16x16x32_bf16 v[128:131], v[144:147], v[174:177], v[128:131]
	v_mfma_f32_16x16x32_bf16 v[120:123], v[152:155], v[174:177], v[120:123]
	v_mfma_f32_16x16x32_bf16 v[104:107], v[144:147], v[194:197], v[104:107]
	v_mfma_f32_16x16x32_bf16 v[96:99], v[152:155], v[194:197], v[96:99]
	v_mfma_f32_16x16x32_bf16 v[84:87], v[144:147], v[202:205], v[84:87]
	v_mfma_f32_16x16x32_bf16 v[80:83], v[152:155], v[202:205], v[80:83]
	v_mfma_f32_16x16x32_bf16 v[68:71], v[144:147], v[210:213], v[68:71]
	v_mfma_f32_16x16x32_bf16 v[64:67], v[152:155], v[210:213], v[64:67]
	v_mfma_f32_16x16x32_bf16 v[128:131], v[148:151], v[178:181], v[128:131]
	v_mfma_f32_16x16x32_bf16 v[120:123], v[170:173], v[178:181], v[120:123]
	v_mfma_f32_16x16x32_bf16 v[104:107], v[148:151], v[198:201], v[104:107]
	v_mfma_f32_16x16x32_bf16 v[96:99], v[170:173], v[198:201], v[96:99]
	v_mfma_f32_16x16x32_bf16 v[84:87], v[148:151], v[206:209], v[84:87]
	v_mfma_f32_16x16x32_bf16 v[80:83], v[170:173], v[206:209], v[80:83]
	v_mfma_f32_16x16x32_bf16 v[68:71], v[148:151], v[214:217], v[68:71]
	v_mfma_f32_16x16x32_bf16 v[64:67], v[170:173], v[214:217], v[64:67]
	s_barrier
; #define PG8_STAGE(bufoff, gbase, voff) do { _Pragma("unroll") for (int _i = 0; _i < 2; ++_i) \
;         __builtin_amdgcn_global_load_lds((const unsigned*)((const char*)(gbase) + (voff)[_i]), (LAS unsigned*)(lds + (bufoff) + ldsw + _i * 8192), 16, 0, 0); } while (0)
; #define PG8_LDA(dst, b, h) do { _Pragma("unroll") for (int m = 0; m < 4; ++m) _Pragma("unroll") for (int k = 0; k < 2; ++k) dst[m][k] = *(const LAS bf16x8*)(lds + PG8_SA(b, h) + aoff + m * 2048 + k * 1024); } while (0)
; #define PG8_LDB(dst, b, h) do { _Pragma("unroll") for (int n = 0; n < 2; ++n) _Pragma("unroll") for (int k = 0; k < 2; ++k) dst[n][k] = *(const LAS bf16x8*)(lds + PG8_SB(b, h) + boff + n * 2048 + k * 1024); } while (0)
; #define PG8_MMA(ai, bj, At, Bt) do { __builtin_amdgcn_s_setprio(1); _Pragma("unroll") for (int m = 0; m < 4; ++m) _Pragma("unroll") for (int n = 0; n < 2; ++n) _Pragma("unroll") for (int k = 0; k < 2; ++k) \
;         acc[ai][bj][m][n] = __builtin_amdgcn_mfma_f32_16x16x32_bf16(Bt[n][k], At[m][k], acc[ai][bj][m][n], 0, 0, 0); __builtin_amdgcn_s_setprio(0); } while (0)
; #define PG8_BAR __builtin_amdgcn_s_barrier()
; template <class Epi, class Sched = StaticOrder, class EpiSub = NoSub, bool FAST = false>
; __device__ __forceinline__ void gemm_phase(LAS unsigned char* lds, const Gemm g, const Sched& S, const Epi& E, const EpiSub& ES = EpiSub()) {
;     ...
;             PG8_LDB(B0, 0, 0); PG8_LDB(B1, 0, 1); PG8_SCHED; PG8_LDA(At, 0, 0); PG8_STAGE(PG8_SA(1, 1), a1 + hstepA, voffA);
;             PG8_WAIT_V(8); PG8_WAIT_L(0); PG8_BAR; PG8_MMA(0, 0, At, B0); PG8_MMA(0, 1, At, B1); PG8_BAR; PG8_SCHED;
;             PG8_LDA(At, 0, 1); PG8_STAGE(PG8_SB(0, 0), b2, voffB); PG8_STAGE(PG8_SB(0, 1), b2 + hstepB, voffB); PG8_STAGE(PG8_SA(0, 0), a2, voffA);
;             PG8_WAIT_V(8); PG8_WAIT_L(0); PG8_BAR; PG8_MMA(1, 0, At, B0); PG8_MMA(1, 1, At, B1); PG8_BAR; PG8_SCHED;
;             PG8_LDB(B0, 1, 0); PG8_LDB(B1, 1, 1); PG8_SCHED; PG8_LDA(At, 1, 0); PG8_STAGE(PG8_SA(0, 1), a2 + hstepA, voffA);
;             PG8_WAIT_V(8); PG8_WAIT_L(0); PG8_BAR; PG8_MMA(0, 0, At, B0); PG8_MMA(0, 1, At, B1); PG8_BAR; PG8_SCHED;
;             PG8_LDA(At, 1, 1); PG8_STAGE(PG8_SB(1, 0), b3, voffB); PG8_STAGE(PG8_SB(1, 1), b3 + hstepB, voffB); PG8_STAGE(PG8_SA(1, 0), a3, voffA);
;             PG8_WAIT_V(8); PG8_WAIT_L(0); PG8_BAR; PG8_MMA(1, 0, At, B0); PG8_MMA(1, 1, At, B1); PG8_BAR; PG8_SCHED;
	s_add_i32 s50, s50, s54
	v_lshl_add_u64 v[190:191], v[190:191], 0, s[12:13]
	s_mov_b32 m0, s50
	ds_read_b128 v[174:177], v188 offset:49152
	ds_read_b128 v[178:181], v188 offset:50176
	ds_read_b128 v[194:197], v188 offset:51200
	ds_read_b128 v[198:201], v188 offset:52224
	ds_read_b128 v[202:205], v188 offset:53248
	ds_read_b128 v[206:209], v188 offset:54272
	ds_read_b128 v[210:213], v188 offset:55296
	ds_read_b128 v[214:217], v188 offset:56320
	global_load_lds_dwordx4 v[190:191], off
	s_add_i32 m0, s50, 0x2000
	s_add_u32 s42, s42, 0x40080
	v_lshl_add_u64 v[190:191], v[218:219], 0, s[12:13]
	s_addc_u32 s43, s43, 0
	s_add_i32 s50, s70, s54
	global_load_lds_dwordx4 v[190:191], off
	v_lshl_add_u64 v[190:191], s[42:43], 0, v[158:159]
	s_mov_b32 m0, s50
	s_nop 0
	global_load_lds_dwordx4 v[190:191], off
	v_lshl_add_u64 v[190:191], s[42:43], 0, v[162:163]
	s_add_i32 m0, s50, 0x2000
	s_nop 0
	global_load_lds_dwordx4 v[190:191], off
	v_lshl_add_u64 v[190:191], v[220:221], 0, s[12:13]
	s_mov_b32 m0, s69
	s_nop 0
	global_load_lds_dwordx4 v[190:191], off
	v_lshl_add_u64 v[190:191], v[222:223], 0, s[12:13]
	s_mov_b32 m0, s74
	s_nop 0
	global_load_lds_dwordx4 v[190:191], off
	s_add_u32 s40, s40, 0x100
	s_addc_u32 s41, s41, 0
	s_add_u32 s48, s48, 0x100
	s_addc_u32 s49, s49, 0
	s_waitcnt vmcnt(8)
	s_waitcnt lgkmcnt(0)
	s_barrier
	v_mfma_f32_16x16x32_bf16 v[60:63], v[100:103], v[174:177], v[60:63]
	v_mfma_f32_16x16x32_bf16 v[56:59], v[124:127], v[174:177], v[56:59]
	v_mfma_f32_16x16x32_bf16 v[44:47], v[100:103], v[194:197], v[44:47]
	v_mfma_f32_16x16x32_bf16 v[40:43], v[124:127], v[194:197], v[40:43]
	v_mfma_f32_16x16x32_bf16 v[28:31], v[100:103], v[202:205], v[28:31]
	v_mfma_f32_16x16x32_bf16 v[24:27], v[124:127], v[202:205], v[24:27]
	v_mfma_f32_16x16x32_bf16 v[12:15], v[100:103], v[210:213], v[12:15]
	v_mfma_f32_16x16x32_bf16 v[8:11], v[124:127], v[210:213], v[8:11]
	v_mfma_f32_16x16x32_bf16 v[60:63], v[112:115], v[178:181], v[60:63]
	v_mfma_f32_16x16x32_bf16 v[56:59], v[136:139], v[178:181], v[56:59]
	v_mfma_f32_16x16x32_bf16 v[44:47], v[112:115], v[198:201], v[44:47]
	v_mfma_f32_16x16x32_bf16 v[40:43], v[136:139], v[198:201], v[40:43]
	v_mfma_f32_16x16x32_bf16 v[28:31], v[112:115], v[206:209], v[28:31]
	v_mfma_f32_16x16x32_bf16 v[24:27], v[136:139], v[206:209], v[24:27]
	v_mfma_f32_16x16x32_bf16 v[12:15], v[112:115], v[214:217], v[12:15]
	v_mfma_f32_16x16x32_bf16 v[8:11], v[136:139], v[214:217], v[8:11]
	v_mfma_f32_16x16x32_bf16 v[52:55], v[144:147], v[174:177], v[52:55]
	v_mfma_f32_16x16x32_bf16 v[48:51], v[152:155], v[174:177], v[48:51]
	v_mfma_f32_16x16x32_bf16 v[36:39], v[144:147], v[194:197], v[36:39]
	v_mfma_f32_16x16x32_bf16 v[32:35], v[152:155], v[194:197], v[32:35]
	v_mfma_f32_16x16x32_bf16 v[20:23], v[144:147], v[202:205], v[20:23]
	v_mfma_f32_16x16x32_bf16 v[16:19], v[152:155], v[202:205], v[16:19]
	v_mfma_f32_16x16x32_bf16 v[4:7], v[144:147], v[210:213], v[4:7]
	v_mfma_f32_16x16x32_bf16 v[0:3], v[152:155], v[210:213], v[0:3]
	v_mfma_f32_16x16x32_bf16 v[52:55], v[148:151], v[178:181], v[52:55]
	v_mfma_f32_16x16x32_bf16 v[48:51], v[170:173], v[178:181], v[48:51]
	v_mfma_f32_16x16x32_bf16 v[36:39], v[148:151], v[198:201], v[36:39]
	v_mfma_f32_16x16x32_bf16 v[32:35], v[170:173], v[198:201], v[32:35]
	v_mfma_f32_16x16x32_bf16 v[20:23], v[148:151], v[206:209], v[20:23]
	v_mfma_f32_16x16x32_bf16 v[16:19], v[170:173], v[206:209], v[16:19]
	v_mfma_f32_16x16x32_bf16 v[4:7], v[148:151], v[214:217], v[4:7]
	v_mfma_f32_16x16x32_bf16 v[0:3], v[170:173], v[214:217], v[0:3]
	s_barrier
	s_cmp_ge_u32 s51, s27
	s_mov_b32 s50, s51
	s_cbranch_scc1 .Lkpeel_600_exit
.LBB0_600:
	ds_read_b128 v[100:103], v186
	ds_read_b128 v[112:115], v186 offset:1024
	ds_read_b128 v[124:127], v186 offset:2048
	ds_read_b128 v[136:139], v186 offset:3072
	ds_read_b128 v[144:147], v187
	ds_read_b128 v[148:151], v187 offset:1024
	ds_read_b128 v[152:155], v187 offset:2048
	ds_read_b128 v[170:173], v187 offset:3072
	s_add_i32 s51, s50, 2
	s_add_u32 s42, s40, 0xfffc0080
	s_addc_u32 s43, s41, -1
	s_cmp_eq_u32 s33, s50
	s_cselect_b32 s53, s1, s43
	s_cselect_b32 s52, s5, s42
	s_cselect_b32 s43, s7, s49
	s_cselect_b32 s42, s25, s48
	v_lshl_add_u64 v[190:191], s[40:41], 0, v[164:165]
	s_add_i32 m0, s55, 0xc000
	ds_read_b128 v[174:177], v188
	ds_read_b128 v[178:181], v188 offset:1024
	ds_read_b128 v[194:197], v188 offset:2048
	ds_read_b128 v[198:201], v188 offset:3072
	ds_read_b128 v[202:205], v188 offset:4096
	ds_read_b128 v[206:209], v188 offset:5120
	ds_read_b128 v[210:213], v188 offset:6144
	ds_read_b128 v[214:217], v188 offset:7168
	global_load_lds_dwordx4 v[190:191], off
	v_lshl_add_u64 v[190:191], s[40:41], 0, v[166:167]
	s_add_i32 m0, s55, 0xe000
	s_nop 0
	global_load_lds_dwordx4 v[190:191], off
	s_waitcnt vmcnt(8)
	s_waitcnt lgkmcnt(0)
	s_barrier
; #define PG8_STAGE(bufoff, gbase, voff) do { _Pragma("unroll") for (int _i = 0; _i < 2; ++_i) \
;         __builtin_amdgcn_global_load_lds((const unsigned*)((const char*)(gbase) + (voff)[_i]), (LAS unsigned*)(lds + (bufoff) + ldsw + _i * 8192), 16, 0, 0); } while (0)
; #define PG8_LDA(dst, b, h) do { _Pragma("unroll") for (int m = 0; m < 4; ++m) _Pragma("unroll") for (int k = 0; k < 2; ++k) dst[m][k] = *(const LAS bf16x8*)(lds + PG8_SA(b, h) + aoff + m * 2048 + k * 1024); } while (0)
; #define PG8_LDB(dst, b, h) do { _Pragma("unroll") for (int n = 0; n < 2; ++n) _Pragma("unroll") for (int k = 0; k < 2; ++k) dst[n][k] = *(const LAS bf16x8*)(lds + PG8_SB(b, h) + boff + n * 2048 + k * 1024); } while (0)
; #define PG8_MMA(ai, bj, At, Bt) do { __builtin_amdgcn_s_setprio(1); _Pragma("unroll") for (int m = 0; m < 4; ++m) _Pragma("unroll") for (int n = 0; n < 2; ++n) _Pragma("unroll") for (int k = 0; k < 2; ++k) \
;         acc[ai][bj][m][n] = __builtin_amdgcn_mfma_f32_16x16x32_bf16(Bt[n][k], At[m][k], acc[ai][bj][m][n], 0, 0, 0); __builtin_amdgcn_s_setprio(0); } while (0)
; #define PG8_BAR __builtin_amdgcn_s_barrier()
; template <class Epi, class Sched = StaticOrder, class EpiSub = NoSub, bool FAST = false>
; __device__ __forceinline__ void gemm_phase(LAS unsigned char* lds, const Gemm g, const Sched& S, const Epi& E, const EpiSub& ES = EpiSub()) {
;     ...
;             PG8_LDB(B0, 0, 0); PG8_LDB(B1, 0, 1); PG8_SCHED; PG8_LDA(At, 0, 0); PG8_STAGE(PG8_SA(1, 1), a1 + hstepA, voffA);
;             PG8_WAIT_V(8); PG8_WAIT_L(0); PG8_BAR; PG8_MMA(0, 0, At, B0); PG8_MMA(0, 1, At, B1); PG8_BAR; PG8_SCHED;
;             PG8_LDA(At, 0, 1); PG8_STAGE(PG8_SB(0, 0), b2, voffB); PG8_STAGE(PG8_SB(0, 1), b2 + hstepB, voffB); PG8_STAGE(PG8_SA(0, 0), a2, voffA);
;             PG8_WAIT_V(8); PG8_WAIT_L(0); PG8_BAR; PG8_MMA(1, 0, At, B0); PG8_MMA(1, 1, At, B1); PG8_BAR; PG8_SCHED;
;             PG8_LDB(B0, 1, 0); PG8_LDB(B1, 1, 1); PG8_SCHED; PG8_LDA(At, 1, 0); PG8_STAGE(PG8_SA(0, 1), a2 + hstepA, voffA);
;             PG8_WAIT_V(8); PG8_WAIT_L(0); PG8_BAR; PG8_MMA(0, 0, At, B0); PG8_MMA(0, 1, At, B1); PG8_BAR; PG8_SCHED;
;             PG8_LDA(At, 1, 1); PG8_STAGE(PG8_SB(1, 0), b3, voffB); PG8_STAGE(PG8_SB(1, 1), b3 + hstepB, voffB); PG8_STAGE(PG8_SA(1, 0), a3, voffA);
;             PG8_WAIT_V(8); PG8_WAIT_L(0); PG8_BAR; PG8_MMA(1, 0, At, B0); PG8_MMA(1, 1, At, B1); PG8_BAR; PG8_SCHED;
	v_mfma_f32_16x16x32_bf16 v[140:143], v[100:103], v[174:177], v[140:143]
	v_mfma_f32_16x16x32_bf16 v[132:135], v[124:127], v[174:177], v[132:135]
	v_mfma_f32_16x16x32_bf16 v[116:119], v[100:103], v[194:197], v[116:119]
	v_mfma_f32_16x16x32_bf16 v[108:111], v[124:127], v[194:197], v[108:111]
	v_mfma_f32_16x16x32_bf16 v[92:95], v[100:103], v[202:205], v[92:95]
	v_mfma_f32_16x16x32_bf16 v[88:91], v[124:127], v[202:205], v[88:91]
	v_mfma_f32_16x16x32_bf16 v[76:79], v[100:103], v[210:213], v[76:79]
	v_mfma_f32_16x16x32_bf16 v[72:75], v[124:127], v[210:213], v[72:75]
	v_mfma_f32_16x16x32_bf16 v[140:143], v[112:115], v[178:181], v[140:143]
	v_mfma_f32_16x16x32_bf16 v[132:135], v[136:139], v[178:181], v[132:135]
	v_mfma_f32_16x16x32_bf16 v[116:119], v[112:115], v[198:201], v[116:119]
	v_mfma_f32_16x16x32_bf16 v[108:111], v[136:139], v[198:201], v[108:111]
	v_mfma_f32_16x16x32_bf16 v[92:95], v[112:115], v[206:209], v[92:95]
	v_mfma_f32_16x16x32_bf16 v[88:91], v[136:139], v[206:209], v[88:91]
	v_mfma_f32_16x16x32_bf16 v[76:79], v[112:115], v[214:217], v[76:79]
	v_mfma_f32_16x16x32_bf16 v[72:75], v[136:139], v[214:217], v[72:75]
	v_mfma_f32_16x16x32_bf16 v[128:131], v[144:147], v[174:177], v[128:131]
	v_mfma_f32_16x16x32_bf16 v[120:123], v[152:155], v[174:177], v[120:123]
	v_mfma_f32_16x16x32_bf16 v[104:107], v[144:147], v[194:197], v[104:107]
	v_mfma_f32_16x16x32_bf16 v[96:99], v[152:155], v[194:197], v[96:99]
	v_mfma_f32_16x16x32_bf16 v[84:87], v[144:147], v[202:205], v[84:87]
	v_mfma_f32_16x16x32_bf16 v[80:83], v[152:155], v[202:205], v[80:83]
	v_mfma_f32_16x16x32_bf16 v[68:71], v[144:147], v[210:213], v[68:71]
	v_mfma_f32_16x16x32_bf16 v[64:67], v[152:155], v[210:213], v[64:67]
	v_mfma_f32_16x16x32_bf16 v[128:131], v[148:151], v[178:181], v[128:131]
	v_mfma_f32_16x16x32_bf16 v[120:123], v[170:173], v[178:181], v[120:123]
	v_mfma_f32_16x16x32_bf16 v[104:107], v[148:151], v[198:201], v[104:107]
	v_mfma_f32_16x16x32_bf16 v[96:99], v[170:173], v[198:201], v[96:99]
	v_mfma_f32_16x16x32_bf16 v[84:87], v[148:151], v[206:209], v[84:87]
	v_mfma_f32_16x16x32_bf16 v[80:83], v[170:173], v[206:209], v[80:83]
	v_mfma_f32_16x16x32_bf16 v[68:71], v[148:151], v[214:217], v[68:71]
	v_mfma_f32_16x16x32_bf16 v[64:67], v[170:173], v[214:217], v[64:67]
	s_barrier
	s_add_i32 s50, s75, s54
	v_lshl_add_u64 v[190:191], s[42:43], 0, v[158:159]
	s_mov_b32 m0, s50
	ds_read_b128 v[174:177], v188 offset:16384
	ds_read_b128 v[178:181], v188 offset:17408
	ds_read_b128 v[194:197], v188 offset:18432
	ds_read_b128 v[198:201], v188 offset:19456
	ds_read_b128 v[202:205], v188 offset:20480
	ds_read_b128 v[206:209], v188 offset:21504
	ds_read_b128 v[210:213], v188 offset:22528
	ds_read_b128 v[214:217], v188 offset:23552
	global_load_lds_dwordx4 v[190:191], off
	s_add_i32 m0, s50, 0x2000
	s_add_u32 s70, s42, 0x40000
	v_lshl_add_u64 v[218:219], s[42:43], 0, v[162:163]
	s_addc_u32 s71, s43, 0
	s_add_i32 s50, s80, s54
	global_load_lds_dwordx4 v[218:219], off
	v_lshl_add_u64 v[220:221], s[70:71], 0, v[158:159]
	s_mov_b32 m0, s50
	v_lshl_add_u64 v[222:223], s[52:53], 0, v[160:161]
	global_load_lds_dwordx4 v[220:221], off
	v_lshl_add_u64 v[220:221], s[70:71], 0, v[162:163]
	s_add_i32 m0, s50, 0x2000
	s_nop 0
	global_load_lds_dwordx4 v[220:221], off
	v_lshl_add_u64 v[220:221], s[52:53], 0, v[156:157]
	s_mov_b32 m0, s55
	s_nop 0
	global_load_lds_dwordx4 v[220:221], off
	s_mov_b32 m0, s56
	s_nop 0
	global_load_lds_dwordx4 v[222:223], off
	s_waitcnt vmcnt(8)
	s_waitcnt lgkmcnt(0)
	s_barrier
	v_mfma_f32_16x16x32_bf16 v[60:63], v[100:103], v[174:177], v[60:63]
	v_mfma_f32_16x16x32_bf16 v[56:59], v[124:127], v[174:177], v[56:59]
	v_mfma_f32_16x16x32_bf16 v[44:47], v[100:103], v[194:197], v[44:47]
	v_mfma_f32_16x16x32_bf16 v[40:43], v[124:127], v[194:197], v[40:43]
	v_mfma_f32_16x16x32_bf16 v[28:31], v[100:103], v[202:205], v[28:31]
	v_mfma_f32_16x16x32_bf16 v[24:27], v[124:127], v[202:205], v[24:27]
	v_mfma_f32_16x16x32_bf16 v[12:15], v[100:103], v[210:213], v[12:15]
	v_mfma_f32_16x16x32_bf16 v[8:11], v[124:127], v[210:213], v[8:11]
	v_mfma_f32_16x16x32_bf16 v[60:63], v[112:115], v[178:181], v[60:63]
	v_mfma_f32_16x16x32_bf16 v[56:59], v[136:139], v[178:181], v[56:59]
	v_mfma_f32_16x16x32_bf16 v[44:47], v[112:115], v[198:201], v[44:47]
	v_mfma_f32_16x16x32_bf16 v[40:43], v[136:139], v[198:201], v[40:43]
	v_mfma_f32_16x16x32_bf16 v[28:31], v[112:115], v[206:209], v[28:31]
	v_mfma_f32_16x16x32_bf16 v[24:27], v[136:139], v[206:209], v[24:27]
	v_mfma_f32_16x16x32_bf16 v[12:15], v[112:115], v[214:217], v[12:15]
	v_mfma_f32_16x16x32_bf16 v[8:11], v[136:139], v[214:217], v[8:11]
	v_mfma_f32_16x16x32_bf16 v[52:55], v[144:147], v[174:177], v[52:55]
	v_mfma_f32_16x16x32_bf16 v[48:51], v[152:155], v[174:177], v[48:51]
	v_mfma_f32_16x16x32_bf16 v[36:39], v[144:147], v[194:197], v[36:39]
	v_mfma_f32_16x16x32_bf16 v[32:35], v[152:155], v[194:197], v[32:35]
	v_mfma_f32_16x16x32_bf16 v[20:23], v[144:147], v[202:205], v[20:23]
	v_mfma_f32_16x16x32_bf16 v[16:19], v[152:155], v[202:205], v[16:19]
	v_mfma_f32_16x16x32_bf16 v[4:7], v[144:147], v[210:213], v[4:7]
	v_mfma_f32_16x16x32_bf16 v[0:3], v[152:155], v[210:213], v[0:3]
	v_mfma_f32_16x16x32_bf16 v[52:55], v[148:151], v[178:181], v[52:55]
	v_mfma_f32_16x16x32_bf16 v[48:51], v[170:173], v[178:181], v[48:51]
	v_mfma_f32_16x16x32_bf16 v[36:39], v[148:151], v[198:201], v[36:39]
	v_mfma_f32_16x16x32_bf16 v[32:35], v[170:173], v[198:201], v[32:35]
	v_mfma_f32_16x16x32_bf16 v[20:23], v[148:151], v[206:209], v[20:23]
	v_mfma_f32_16x16x32_bf16 v[16:19], v[170:173], v[206:209], v[16:19]
	v_mfma_f32_16x16x32_bf16 v[4:7], v[148:151], v[214:217], v[4:7]
	v_mfma_f32_16x16x32_bf16 v[0:3], v[170:173], v[214:217], v[0:3]
	s_barrier
; #define PG8_STAGE(bufoff, gbase, voff) do { _Pragma("unroll") for (int _i = 0; _i < 2; ++_i) \
;         __builtin_amdgcn_global_load_lds((const unsigned*)((const char*)(gbase) + (voff)[_i]), (LAS unsigned*)(lds + (bufoff) + ldsw + _i * 8192), 16, 0, 0); } while (0)
; #define PG8_LDA(dst, b, h) do { _Pragma("unroll") for (int m = 0; m < 4; ++m) _Pragma("unroll") for (int k = 0; k < 2; ++k) dst[m][k] = *(const LAS bf16x8*)(lds + PG8_SA(b, h) + aoff + m * 2048 + k * 1024); } while (0)
; #define PG8_LDB(dst, b, h) do { _Pragma("unroll") for (int n = 0; n < 2; ++n) _Pragma("unroll") for (int k = 0; k < 2; ++k) dst[n][k] = *(const LAS bf16x8*)(lds + PG8_SB(b, h) + boff + n * 2048 + k * 1024); } while (0)
; #define PG8_MMA(ai, bj, At, Bt) do { __builtin_amdgcn_s_setprio(1); _Pragma("unroll") for (int m = 0; m < 4; ++m) _Pragma("unroll") for (int n = 0; n < 2; ++n) _Pragma("unroll") for (int k = 0; k < 2; ++k) \
;         acc[ai][bj][m][n] = __builtin_amdgcn_mfma_f32_16x16x32_bf16(Bt[n][k], At[m][k], acc[ai][bj][m][n], 0, 0, 0); __builtin_amdgcn_s_setprio(0); } while (0)
; #define PG8_BAR __builtin_amdgcn_s_barrier()
; template <class Epi, class Sched = StaticOrder, class EpiSub = NoSub, bool FAST = false>
; __device__ __forceinline__ void gemm_phase(LAS unsigned char* lds, const Gemm g, const Sched& S, const Epi& E, const EpiSub& ES = EpiSub()) {
;     ...
;             PG8_LDB(B0, 0, 0); PG8_LDB(B1, 0, 1); PG8_SCHED; PG8_LDA(At, 0, 0); PG8_STAGE(PG8_SA(1, 1), a1 + hstepA, voffA);
;             PG8_WAIT_V(8); PG8_WAIT_L(0); PG8_BAR; PG8_MMA(0, 0, At, B0); PG8_MMA(0, 1, At, B1); PG8_BAR; PG8_SCHED;
;             PG8_LDA(At, 0, 1); PG8_STAGE(PG8_SB(0, 0), b2, voffB); PG8_STAGE(PG8_SB(0, 1), b2 + hstepB, voffB); PG8_STAGE(PG8_SA(0, 0), a2, voffA);
;             PG8_WAIT_V(8); PG8_WAIT_L(0); PG8_BAR; PG8_MMA(1, 0, At, B0); PG8_MMA(1, 1, At, B1); PG8_BAR; PG8_SCHED;
;             PG8_LDB(B0, 1, 0); PG8_LDB(B1, 1, 1); PG8_SCHED; PG8_LDA(At, 1, 0); PG8_STAGE(PG8_SA(0, 1), a2 + hstepA, voffA);
;             PG8_WAIT_V(8); PG8_WAIT_L(0); PG8_BAR; PG8_MMA(0, 0, At, B0); PG8_MMA(0, 1, At, B1); PG8_BAR; PG8_SCHED;
;             PG8_LDA(At, 1, 1); PG8_STAGE(PG8_SB(1, 0), b3, voffB); PG8_STAGE(PG8_SB(1, 1), b3 + hstepB, voffB); PG8_STAGE(PG8_SA(1, 0), a3, voffA);
;             PG8_WAIT_V(8); PG8_WAIT_L(0); PG8_BAR; PG8_MMA(1, 0, At, B0); PG8_MMA(1, 1, At, B1); PG8_BAR; PG8_SCHED;
	s_add_i32 s50, 0, 0x18000
	s_add_i32 s70, 0, 0x1c000
	v_add_u32_e32 v136, s50, v183
	v_add_u32_e32 v170, s70, v183
	ds_read_b128 v[100:103], v136
	ds_read_b128 v[112:115], v136 offset:1024
	ds_read_b128 v[124:127], v136 offset:2048
	ds_read_b128 v[136:139], v136 offset:3072
	ds_read_b128 v[144:147], v170
	ds_read_b128 v[148:151], v170 offset:1024
	ds_read_b128 v[152:155], v170 offset:2048
	ds_read_b128 v[170:173], v170 offset:3072
	s_add_u32 s52, s52, 0x40000
	s_addc_u32 s53, s53, 0
	s_mov_b32 m0, s57
	v_lshl_add_u64 v[224:225], s[52:53], 0, v[156:157]
	ds_read_b128 v[174:177], v188 offset:32768
	ds_read_b128 v[178:181], v188 offset:33792
	ds_read_b128 v[194:197], v188 offset:34816
	ds_read_b128 v[198:201], v188 offset:35840
	ds_read_b128 v[202:205], v188 offset:36864
	ds_read_b128 v[206:209], v188 offset:37888
	ds_read_b128 v[210:213], v188 offset:38912
	ds_read_b128 v[214:217], v188 offset:39936
	global_load_lds_dwordx4 v[224:225], off
	v_lshl_add_u64 v[224:225], s[52:53], 0, v[160:161]
	s_mov_b32 m0, s58
	s_nop 0
	global_load_lds_dwordx4 v[224:225], off
	s_waitcnt vmcnt(8)
	s_waitcnt lgkmcnt(0)
	s_barrier
	v_mfma_f32_16x16x32_bf16 v[140:143], v[100:103], v[174:177], v[140:143]
	v_mfma_f32_16x16x32_bf16 v[132:135], v[124:127], v[174:177], v[132:135]
	v_mfma_f32_16x16x32_bf16 v[116:119], v[100:103], v[194:197], v[116:119]
	v_mfma_f32_16x16x32_bf16 v[108:111], v[124:127], v[194:197], v[108:111]
	v_mfma_f32_16x16x32_bf16 v[92:95], v[100:103], v[202:205], v[92:95]
	v_mfma_f32_16x16x32_bf16 v[88:91], v[124:127], v[202:205], v[88:91]
	v_mfma_f32_16x16x32_bf16 v[76:79], v[100:103], v[210:213], v[76:79]
	v_mfma_f32_16x16x32_bf16 v[72:75], v[124:127], v[210:213], v[72:75]
	v_mfma_f32_16x16x32_bf16 v[140:143], v[112:115], v[178:181], v[140:143]
	v_mfma_f32_16x16x32_bf16 v[132:135], v[136:139], v[178:181], v[132:135]
	v_mfma_f32_16x16x32_bf16 v[116:119], v[112:115], v[198:201], v[116:119]
	v_mfma_f32_16x16x32_bf16 v[108:111], v[136:139], v[198:201], v[108:111]
	v_mfma_f32_16x16x32_bf16 v[92:95], v[112:115], v[206:209], v[92:95]
	v_mfma_f32_16x16x32_bf16 v[88:91], v[136:139], v[206:209], v[88:91]
	v_mfma_f32_16x16x32_bf16 v[76:79], v[112:115], v[214:217], v[76:79]
	v_mfma_f32_16x16x32_bf16 v[72:75], v[136:139], v[214:217], v[72:75]
	v_mfma_f32_16x16x32_bf16 v[128:131], v[144:147], v[174:177], v[128:131]
	v_mfma_f32_16x16x32_bf16 v[120:123], v[152:155], v[174:177], v[120:123]
	v_mfma_f32_16x16x32_bf16 v[104:107], v[144:147], v[194:197], v[104:107]
	v_mfma_f32_16x16x32_bf16 v[96:99], v[152:155], v[194:197], v[96:99]
	v_mfma_f32_16x16x32_bf16 v[84:87], v[144:147], v[202:205], v[84:87]
	v_mfma_f32_16x16x32_bf16 v[80:83], v[152:155], v[202:205], v[80:83]
	v_mfma_f32_16x16x32_bf16 v[68:71], v[144:147], v[210:213], v[68:71]
	v_mfma_f32_16x16x32_bf16 v[64:67], v[152:155], v[210:213], v[64:67]
	v_mfma_f32_16x16x32_bf16 v[128:131], v[148:151], v[178:181], v[128:131]
	v_mfma_f32_16x16x32_bf16 v[120:123], v[170:173], v[178:181], v[120:123]
	v_mfma_f32_16x16x32_bf16 v[104:107], v[148:151], v[198:201], v[104:107]
	v_mfma_f32_16x16x32_bf16 v[96:99], v[170:173], v[198:201], v[96:99]
	v_mfma_f32_16x16x32_bf16 v[84:87], v[148:151], v[206:209], v[84:87]
	v_mfma_f32_16x16x32_bf16 v[80:83], v[170:173], v[206:209], v[80:83]
	v_mfma_f32_16x16x32_bf16 v[68:71], v[148:151], v[214:217], v[68:71]
	v_mfma_f32_16x16x32_bf16 v[64:67], v[170:173], v[214:217], v[64:67]
	s_barrier
	s_add_i32 s50, s50, s54
	v_lshl_add_u64 v[190:191], v[190:191], 0, s[12:13]
	s_mov_b32 m0, s50
	ds_read_b128 v[174:177], v188 offset:49152
	ds_read_b128 v[178:181], v188 offset:50176
	ds_read_b128 v[194:197], v188 offset:51200
	ds_read_b128 v[198:201], v188 offset:52224
	ds_read_b128 v[202:205], v188 offset:53248
	ds_read_b128 v[206:209], v188 offset:54272
	ds_read_b128 v[210:213], v188 offset:55296
	ds_read_b128 v[214:217], v188 offset:56320
	global_load_lds_dwordx4 v[190:191], off
	s_add_i32 m0, s50, 0x2000
	s_add_u32 s42, s42, 0x40080
	v_lshl_add_u64 v[190:191], v[218:219], 0, s[12:13]
	s_addc_u32 s43, s43, 0
	s_add_i32 s50, s70, s54
	global_load_lds_dwordx4 v[190:191], off
	v_lshl_add_u64 v[190:191], s[42:43], 0, v[158:159]
	s_mov_b32 m0, s50
	s_nop 0
	global_load_lds_dwordx4 v[190:191], off
	v_lshl_add_u64 v[190:191], s[42:43], 0, v[162:163]
	s_add_i32 m0, s50, 0x2000
	s_nop 0
	global_load_lds_dwordx4 v[190:191], off
	v_lshl_add_u64 v[190:191], v[220:221], 0, s[12:13]
	s_mov_b32 m0, s69
	s_nop 0
	global_load_lds_dwordx4 v[190:191], off
	v_lshl_add_u64 v[190:191], v[222:223], 0, s[12:13]
	s_mov_b32 m0, s74
	s_nop 0
	global_load_lds_dwordx4 v[190:191], off
	s_add_u32 s40, s40, 0x100
	s_addc_u32 s41, s41, 0
	s_add_u32 s48, s48, 0x100
	s_addc_u32 s49, s49, 0
	s_waitcnt vmcnt(8)
	s_waitcnt lgkmcnt(0)
	s_barrier
	v_mfma_f32_16x16x32_bf16 v[60:63], v[100:103], v[174:177], v[60:63]
	v_mfma_f32_16x16x32_bf16 v[56:59], v[124:127], v[174:177], v[56:59]
	v_mfma_f32_16x16x32_bf16 v[44:47], v[100:103], v[194:197], v[44:47]
	v_mfma_f32_16x16x32_bf16 v[40:43], v[124:127], v[194:197], v[40:43]
	v_mfma_f32_16x16x32_bf16 v[28:31], v[100:103], v[202:205], v[28:31]
	v_mfma_f32_16x16x32_bf16 v[24:27], v[124:127], v[202:205], v[24:27]
	v_mfma_f32_16x16x32_bf16 v[12:15], v[100:103], v[210:213], v[12:15]
	v_mfma_f32_16x16x32_bf16 v[8:11], v[124:127], v[210:213], v[8:11]
	v_mfma_f32_16x16x32_bf16 v[60:63], v[112:115], v[178:181], v[60:63]
	v_mfma_f32_16x16x32_bf16 v[56:59], v[136:139], v[178:181], v[56:59]
	v_mfma_f32_16x16x32_bf16 v[44:47], v[112:115], v[198:201], v[44:47]
	v_mfma_f32_16x16x32_bf16 v[40:43], v[136:139], v[198:201], v[40:43]
	v_mfma_f32_16x16x32_bf16 v[28:31], v[112:115], v[206:209], v[28:31]
	v_mfma_f32_16x16x32_bf16 v[24:27], v[136:139], v[206:209], v[24:27]
	v_mfma_f32_16x16x32_bf16 v[12:15], v[112:115], v[214:217], v[12:15]
	v_mfma_f32_16x16x32_bf16 v[8:11], v[136:139], v[214:217], v[8:11]
	v_mfma_f32_16x16x32_bf16 v[52:55], v[144:147], v[174:177], v[52:55]
	v_mfma_f32_16x16x32_bf16 v[48:51], v[152:155], v[174:177], v[48:51]
	v_mfma_f32_16x16x32_bf16 v[36:39], v[144:147], v[194:197], v[36:39]
	v_mfma_f32_16x16x32_bf16 v[32:35], v[152:155], v[194:197], v[32:35]
	v_mfma_f32_16x16x32_bf16 v[20:23], v[144:147], v[202:205], v[20:23]
	v_mfma_f32_16x16x32_bf16 v[16:19], v[152:155], v[202:205], v[16:19]
	v_mfma_f32_16x16x32_bf16 v[4:7], v[144:147], v[210:213], v[4:7]
	v_mfma_f32_16x16x32_bf16 v[0:3], v[152:155], v[210:213], v[0:3]
	v_mfma_f32_16x16x32_bf16 v[52:55], v[148:151], v[178:181], v[52:55]
	v_mfma_f32_16x16x32_bf16 v[48:51], v[170:173], v[178:181], v[48:51]
	v_mfma_f32_16x16x32_bf16 v[36:39], v[148:151], v[198:201], v[36:39]
	v_mfma_f32_16x16x32_bf16 v[32:35], v[170:173], v[198:201], v[32:35]
	v_mfma_f32_16x16x32_bf16 v[20:23], v[148:151], v[206:209], v[20:23]
	v_mfma_f32_16x16x32_bf16 v[16:19], v[170:173], v[206:209], v[16:19]
	v_mfma_f32_16x16x32_bf16 v[4:7], v[148:151], v[214:217], v[4:7]
	v_mfma_f32_16x16x32_bf16 v[0:3], v[170:173], v[214:217], v[0:3]
	s_barrier
	s_cmp_ge_u32 s51, s27
	s_mov_b32 s50, s51
	s_cbranch_scc0 .LBB0_600

; #define PG8_STAGE(bufoff, gbase, voff) do { _Pragma("unroll") for (int _i = 0; _i < 2; ++_i) \
;         __builtin_amdgcn_global_load_lds((const unsigned*)((const char*)(gbase) + (voff)[_i]), (LAS unsigned*)(lds + (bufoff) + ldsw + _i * 8192), 16, 0, 0); } while (0)
; #define PG8_WAIT_V(n) asm volatile("s_waitcnt vmcnt(" #n ")" ::: "memory")
; #define PG8_BAR __builtin_amdgcn_s_barrier()
; template <class Epi, class Sched = StaticOrder, class EpiSub = NoSub, bool FAST = false>
; __device__ __forceinline__ void gemm_phase(LAS unsigned char* lds, const Gemm g, const Sched& S, const Epi& E, const EpiSub& ES = EpiSub()) {
;     ...
;         const size_t nko = (has_next && nxt.kb >= 0) ? nxt.kb * ksubB : 0;
;         const char* nA = has_next ? (const char*)g.A + (size_t)nxt.pm * tstepA + (size_t)nxt.pn * g.acs + nko : cA; const char* nB = has_next ? (const char*)g.Bt + (size_t)nxt.pn * tstepB + nko : cB;
;         const int nt = cur.kb < 0 ? ntMain : ntSub;
;         for (int t = 0; t < nt; t += 2) {
;             const bool last = (t == nt - 2);
;             const char* a1 = cA + (size_t)(t + 1) * kstep;
;             const char* a2 = last ? nA : cA + (size_t)(t + 2) * kstep; const char* b2 = last ? nB : cB + (size_t)(t + 2) * kstep;
;             const char* a3 = a2 + kstep; const char* b3 = b2 + kstep;
;             if constexpr (FAST && PG8_SP2) {
;             PG8_LDB(B0, 0, 0); PG8_LDB(B1, 0, 1); PG8_SCHED; PG8_LDA(At, 0, 0); PG8_STAGE(PG8_SA(1, 1), a1 + hstepA, voffA);
;             PG8_WAIT_V(8); PG8_WAIT_L(0); PG8_BAR; PG8_MMA(0, 0, At, B0); PG8_MMA(0, 1, At, B1); PG8_BAR; PG8_SCHED;
;             PG8_LDA(At, 0, 1); PG8_STAGE(PG8_SB(0, 0), b2, voffB); PG8_STAGE(PG8_SB(0, 1), b2 + hstepB, voffB); PG8_STAGE(PG8_SA(0, 0), a2, voffA);
;             PG8_WAIT_V(8); PG8_WAIT_L(0); PG8_BAR; PG8_MMA(1, 0, At, B0); PG8_MMA(1, 1, At, B1); PG8_BAR; PG8_SCHED;
;             PG8_LDB(B0, 1, 0); PG8_LDB(B1, 1, 1); PG8_SCHED; PG8_LDA(At, 1, 0); PG8_STAGE(PG8_SA(0, 1), a2 + hstepA, voffA);
;             PG8_WAIT_V(8); PG8_WAIT_L(0); PG8_BAR; PG8_MMA(0, 0, At, B0); PG8_MMA(0, 1, At, B1); PG8_BAR; PG8_SCHED;
;             PG8_LDA(At, 1, 1); PG8_STAGE(PG8_SB(1, 0), b3, voffB); PG8_STAGE(PG8_SB(1, 1), b3 + hstepB, voffB); PG8_STAGE(PG8_SA(1, 0), a3, voffA);
;             PG8_WAIT_V(8); PG8_WAIT_L(0); PG8_BAR; PG8_MMA(1, 0, At, B0); PG8_MMA(1, 1, At, B1); PG8_BAR; PG8_SCHED;
.LBB0_631:
	s_cmp_gt_i32 s8, -1
	s_cselect_b64 s[26:27], -1, 0
	s_and_b64 s[26:27], s[24:25], s[26:27]
	s_lshl_b64 s[28:29], s[8:9], 10
	s_and_b64 s[26:27], s[26:27], exec
	s_cselect_b32 s31, s29, 0
	s_cselect_b32 s33, s28, 0
	s_ashr_i32 s23, s22, 31
	s_lshl_b64 s[26:27], s[22:23], 20
	v_readlane_b32 s28, v254, 36
	v_readlane_b32 s29, v254, 37
	s_add_u32 s1, s28, s26
	s_addc_u32 s5, s29, s27
	s_add_u32 s26, s1, s33
	s_addc_u32 s27, s5, s31
	s_and_b64 s[28:29], s[24:25], exec
	s_cselect_b32 s1, s27, s39
	s_cselect_b32 s5, s26, s38
	s_ashr_i32 s21, s20, 31
	s_lshl_b64 s[28:29], s[20:21], 20
	s_add_u32 s21, s2, s28
	s_addc_u32 s23, s3, s29
	s_add_u32 s28, s21, s33
	s_addc_u32 s29, s23, s31
	s_and_b64 s[36:37], s[24:25], exec
	s_cselect_b32 s21, s29, s41
	s_cselect_b32 s23, s28, s40
	s_cmp_gt_i32 s0, -1
	s_cselect_b64 s[36:37], -1, 0
	s_cmp_lt_i32 s0, 0
	s_cselect_b32 s31, 32, 8
	s_add_i32 s33, s31, -2
	s_add_u32 s38, s38, 0x80080
	s_addc_u32 s39, s39, 0
	s_add_u32 s48, s40, 0x100
	s_mov_b32 s42, 0
	s_addc_u32 s49, s41, 0
	ds_read_b128 v[104:107], v224
	ds_read_b128 v[108:111], v224 offset:1024
	ds_read_b128 v[120:123], v224 offset:2048
	ds_read_b128 v[124:127], v224 offset:3072
	ds_read_b128 v[136:139], v225
	ds_read_b128 v[140:143], v225 offset:1024
	ds_read_b128 v[152:155], v225 offset:2048
	ds_read_b128 v[156:159], v225 offset:3072
	s_add_i32 s50, s42, 2
	s_add_u32 s40, s38, 0xfff80080
	s_addc_u32 s41, s39, -1
	s_cmp_eq_u32 s33, s42
	s_cselect_b32 s42, s5, s40
	s_cselect_b32 s43, s1, s41
	s_cselect_b32 s41, s21, s49
	s_cselect_b32 s40, s23, s48
	v_lshl_add_u64 v[208:209], s[38:39], 0, v[202:203]
	s_add_i32 m0, s53, 0xc000
	ds_read_b128 v[160:163], v226
	ds_read_b128 v[164:167], v226 offset:1024
	ds_read_b128 v[168:171], v226 offset:2048
	ds_read_b128 v[172:175], v226 offset:3072
	ds_read_b128 v[176:179], v226 offset:4096
	ds_read_b128 v[180:183], v226 offset:5120
	ds_read_b128 v[184:187], v226 offset:6144
	ds_read_b128 v[188:191], v226 offset:7168
	global_load_lds_dwordx4 v[208:209], off
	v_lshl_add_u64 v[208:209], s[38:39], 0, v[204:205]
	s_add_i32 m0, s53, 0xe000
	s_nop 0
	global_load_lds_dwordx4 v[208:209], off
	s_waitcnt vmcnt(8)
	s_waitcnt lgkmcnt(0)
	s_barrier
	v_mfma_f32_16x16x32_bf16 v[148:151], v[104:107], v[160:163], 0
	v_mfma_f32_16x16x32_bf16 v[144:147], v[120:123], v[160:163], 0
	v_mfma_f32_16x16x32_bf16 v[116:119], v[104:107], v[168:171], 0
	v_mfma_f32_16x16x32_bf16 v[112:115], v[120:123], v[168:171], 0
	v_mfma_f32_16x16x32_bf16 v[92:95], v[104:107], v[176:179], 0
	v_mfma_f32_16x16x32_bf16 v[88:91], v[120:123], v[176:179], 0
	v_mfma_f32_16x16x32_bf16 v[76:79], v[104:107], v[184:187], 0
	v_mfma_f32_16x16x32_bf16 v[72:75], v[120:123], v[184:187], 0
	v_mfma_f32_16x16x32_bf16 v[148:151], v[108:111], v[164:167], v[148:151]
	v_mfma_f32_16x16x32_bf16 v[144:147], v[124:127], v[164:167], v[144:147]
	v_mfma_f32_16x16x32_bf16 v[116:119], v[108:111], v[172:175], v[116:119]
	v_mfma_f32_16x16x32_bf16 v[112:115], v[124:127], v[172:175], v[112:115]
	v_mfma_f32_16x16x32_bf16 v[92:95], v[108:111], v[180:183], v[92:95]
	v_mfma_f32_16x16x32_bf16 v[88:91], v[124:127], v[180:183], v[88:91]
	v_mfma_f32_16x16x32_bf16 v[76:79], v[108:111], v[188:191], v[76:79]
	v_mfma_f32_16x16x32_bf16 v[72:75], v[124:127], v[188:191], v[72:75]
	v_mfma_f32_16x16x32_bf16 v[132:135], v[136:139], v[160:163], 0
	v_mfma_f32_16x16x32_bf16 v[128:131], v[152:155], v[160:163], 0
	v_mfma_f32_16x16x32_bf16 v[100:103], v[136:139], v[168:171], 0
	v_mfma_f32_16x16x32_bf16 v[96:99], v[152:155], v[168:171], 0
	v_mfma_f32_16x16x32_bf16 v[84:87], v[136:139], v[176:179], 0
	v_mfma_f32_16x16x32_bf16 v[80:83], v[152:155], v[176:179], 0
	v_mfma_f32_16x16x32_bf16 v[68:71], v[136:139], v[184:187], 0
	v_mfma_f32_16x16x32_bf16 v[64:67], v[152:155], v[184:187], 0
	v_mfma_f32_16x16x32_bf16 v[132:135], v[140:143], v[164:167], v[132:135]
	v_mfma_f32_16x16x32_bf16 v[128:131], v[156:159], v[164:167], v[128:131]
	v_mfma_f32_16x16x32_bf16 v[100:103], v[140:143], v[172:175], v[100:103]
	v_mfma_f32_16x16x32_bf16 v[96:99], v[156:159], v[172:175], v[96:99]
	v_mfma_f32_16x16x32_bf16 v[84:87], v[140:143], v[180:183], v[84:87]
	v_mfma_f32_16x16x32_bf16 v[80:83], v[156:159], v[180:183], v[80:83]
	v_mfma_f32_16x16x32_bf16 v[68:71], v[140:143], v[188:191], v[68:71]
	v_mfma_f32_16x16x32_bf16 v[64:67], v[156:159], v[188:191], v[64:67]
	s_barrier
	s_add_i32 s51, s75, s52
	v_lshl_add_u64 v[208:209], s[40:41], 0, v[196:197]
	s_mov_b32 m0, s51
	ds_read_b128 v[160:163], v226 offset:16384
	ds_read_b128 v[164:167], v226 offset:17408
	ds_read_b128 v[168:171], v226 offset:18432
	ds_read_b128 v[172:175], v226 offset:19456
	ds_read_b128 v[176:179], v226 offset:20480
	ds_read_b128 v[180:183], v226 offset:21504
	ds_read_b128 v[184:187], v226 offset:22528
	ds_read_b128 v[188:191], v226 offset:23552
	global_load_lds_dwordx4 v[208:209], off
	s_add_i32 m0, s51, 0x2000
	s_add_u32 s70, s40, 0x80000
	v_lshl_add_u64 v[210:211], s[40:41], 0, v[200:201]
	s_addc_u32 s71, s41, 0
	s_add_i32 s51, s78, s52
	global_load_lds_dwordx4 v[210:211], off
	v_lshl_add_u64 v[212:213], s[70:71], 0, v[196:197]
	s_mov_b32 m0, s51
	v_lshl_add_u64 v[214:215], s[42:43], 0, v[198:199]
	global_load_lds_dwordx4 v[212:213], off
	v_lshl_add_u64 v[212:213], s[70:71], 0, v[200:201]
	s_add_i32 m0, s51, 0x2000
	s_nop 0
	global_load_lds_dwordx4 v[212:213], off
	v_lshl_add_u64 v[212:213], s[42:43], 0, v[194:195]
	s_mov_b32 m0, s53
	s_nop 0
	global_load_lds_dwordx4 v[212:213], off
	s_mov_b32 m0, s54
	s_nop 0
	global_load_lds_dwordx4 v[214:215], off
	s_waitcnt vmcnt(8)
	s_waitcnt lgkmcnt(0)
	s_barrier
; #define PG8_STAGE(bufoff, gbase, voff) do { _Pragma("unroll") for (int _i = 0; _i < 2; ++_i) \
;         __builtin_amdgcn_global_load_lds((const unsigned*)((const char*)(gbase) + (voff)[_i]), (LAS unsigned*)(lds + (bufoff) + ldsw + _i * 8192), 16, 0, 0); } while (0)
; #define PG8_LDA(dst, b, h) do { _Pragma("unroll") for (int m = 0; m < 4; ++m) _Pragma("unroll") for (int k = 0; k < 2; ++k) dst[m][k] = *(const LAS bf16x8*)(lds + PG8_SA(b, h) + aoff + m * 2048 + k * 1024); } while (0)
; #define PG8_LDB(dst, b, h) do { _Pragma("unroll") for (int n = 0; n < 2; ++n) _Pragma("unroll") for (int k = 0; k < 2; ++k) dst[n][k] = *(const LAS bf16x8*)(lds + PG8_SB(b, h) + boff + n * 2048 + k * 1024); } while (0)
; #define PG8_MMA(ai, bj, At, Bt) do { __builtin_amdgcn_s_setprio(1); _Pragma("unroll") for (int m = 0; m < 4; ++m) _Pragma("unroll") for (int n = 0; n < 2; ++n) _Pragma("unroll") for (int k = 0; k < 2; ++k) \
;         acc[ai][bj][m][n] = __builtin_amdgcn_mfma_f32_16x16x32_bf16(Bt[n][k], At[m][k], acc[ai][bj][m][n], 0, 0, 0); __builtin_amdgcn_s_setprio(0); } while (0)
; #define PG8_BAR __builtin_amdgcn_s_barrier()
; template <class Epi, class Sched = StaticOrder, class EpiSub = NoSub, bool FAST = false>
; __device__ __forceinline__ void gemm_phase(LAS unsigned char* lds, const Gemm g, const Sched& S, const Epi& E, const EpiSub& ES = EpiSub()) {
;     ...
;             PG8_LDB(B0, 0, 0); PG8_LDB(B1, 0, 1); PG8_SCHED; PG8_LDA(At, 0, 0); PG8_STAGE(PG8_SA(1, 1), a1 + hstepA, voffA);
;             PG8_WAIT_V(8); PG8_WAIT_L(0); PG8_BAR; PG8_MMA(0, 0, At, B0); PG8_MMA(0, 1, At, B1); PG8_BAR; PG8_SCHED;
;             PG8_LDA(At, 0, 1); PG8_STAGE(PG8_SB(0, 0), b2, voffB); PG8_STAGE(PG8_SB(0, 1), b2 + hstepB, voffB); PG8_STAGE(PG8_SA(0, 0), a2, voffA);
;             PG8_WAIT_V(8); PG8_WAIT_L(0); PG8_BAR; PG8_MMA(1, 0, At, B0); PG8_MMA(1, 1, At, B1); PG8_BAR; PG8_SCHED;
;             PG8_LDB(B0, 1, 0); PG8_LDB(B1, 1, 1); PG8_SCHED; PG8_LDA(At, 1, 0); PG8_STAGE(PG8_SA(0, 1), a2 + hstepA, voffA);
;             PG8_WAIT_V(8); PG8_WAIT_L(0); PG8_BAR; PG8_MMA(0, 0, At, B0); PG8_MMA(0, 1, At, B1); PG8_BAR; PG8_SCHED;
;             PG8_LDA(At, 1, 1); PG8_STAGE(PG8_SB(1, 0), b3, voffB); PG8_STAGE(PG8_SB(1, 1), b3 + hstepB, voffB); PG8_STAGE(PG8_SA(1, 0), a3, voffA);
;             PG8_WAIT_V(8); PG8_WAIT_L(0); PG8_BAR; PG8_MMA(1, 0, At, B0); PG8_MMA(1, 1, At, B1); PG8_BAR; PG8_SCHED;
	v_mfma_f32_16x16x32_bf16 v[60:63], v[104:107], v[160:163], 0
	v_mfma_f32_16x16x32_bf16 v[56:59], v[120:123], v[160:163], 0
	v_mfma_f32_16x16x32_bf16 v[44:47], v[104:107], v[168:171], 0
	v_mfma_f32_16x16x32_bf16 v[40:43], v[120:123], v[168:171], 0
	v_mfma_f32_16x16x32_bf16 v[28:31], v[104:107], v[176:179], 0
	v_mfma_f32_16x16x32_bf16 v[24:27], v[120:123], v[176:179], 0
	v_mfma_f32_16x16x32_bf16 v[12:15], v[104:107], v[184:187], 0
	v_mfma_f32_16x16x32_bf16 v[8:11], v[120:123], v[184:187], 0
	v_mfma_f32_16x16x32_bf16 v[60:63], v[108:111], v[164:167], v[60:63]
	v_mfma_f32_16x16x32_bf16 v[56:59], v[124:127], v[164:167], v[56:59]
	v_mfma_f32_16x16x32_bf16 v[44:47], v[108:111], v[172:175], v[44:47]
	v_mfma_f32_16x16x32_bf16 v[40:43], v[124:127], v[172:175], v[40:43]
	v_mfma_f32_16x16x32_bf16 v[28:31], v[108:111], v[180:183], v[28:31]
	v_mfma_f32_16x16x32_bf16 v[24:27], v[124:127], v[180:183], v[24:27]
	v_mfma_f32_16x16x32_bf16 v[12:15], v[108:111], v[188:191], v[12:15]
	v_mfma_f32_16x16x32_bf16 v[8:11], v[124:127], v[188:191], v[8:11]
	v_mfma_f32_16x16x32_bf16 v[52:55], v[136:139], v[160:163], 0
	v_mfma_f32_16x16x32_bf16 v[48:51], v[152:155], v[160:163], 0
	v_mfma_f32_16x16x32_bf16 v[36:39], v[136:139], v[168:171], 0
	v_mfma_f32_16x16x32_bf16 v[32:35], v[152:155], v[168:171], 0
	v_mfma_f32_16x16x32_bf16 v[20:23], v[136:139], v[176:179], 0
	v_mfma_f32_16x16x32_bf16 v[16:19], v[152:155], v[176:179], 0
	v_mfma_f32_16x16x32_bf16 v[4:7], v[136:139], v[184:187], 0
	v_mfma_f32_16x16x32_bf16 v[0:3], v[152:155], v[184:187], 0
	v_mfma_f32_16x16x32_bf16 v[52:55], v[140:143], v[164:167], v[52:55]
	v_mfma_f32_16x16x32_bf16 v[48:51], v[156:159], v[164:167], v[48:51]
	v_mfma_f32_16x16x32_bf16 v[36:39], v[140:143], v[172:175], v[36:39]
	v_mfma_f32_16x16x32_bf16 v[32:35], v[156:159], v[172:175], v[32:35]
	v_mfma_f32_16x16x32_bf16 v[20:23], v[140:143], v[180:183], v[20:23]
	v_mfma_f32_16x16x32_bf16 v[16:19], v[156:159], v[180:183], v[16:19]
	v_mfma_f32_16x16x32_bf16 v[4:7], v[140:143], v[188:191], v[4:7]
	v_mfma_f32_16x16x32_bf16 v[0:3], v[156:159], v[188:191], v[0:3]
	s_barrier
	s_add_i32 s51, 0, 0x18000
	s_add_i32 s70, 0, 0x1c000
	v_add_u32_e32 v124, s51, v221
	v_add_u32_e32 v156, s70, v221
	ds_read_b128 v[104:107], v124
	ds_read_b128 v[108:111], v124 offset:1024
	ds_read_b128 v[120:123], v124 offset:2048
	ds_read_b128 v[124:127], v124 offset:3072
	ds_read_b128 v[136:139], v156
	ds_read_b128 v[140:143], v156 offset:1024
	ds_read_b128 v[152:155], v156 offset:2048
	ds_read_b128 v[156:159], v156 offset:3072
	s_add_u32 s42, s42, 0x80000
	s_addc_u32 s43, s43, 0
	s_mov_b32 m0, s55
	v_lshl_add_u64 v[216:217], s[42:43], 0, v[194:195]
	ds_read_b128 v[160:163], v226 offset:32768
	ds_read_b128 v[164:167], v226 offset:33792
	ds_read_b128 v[168:171], v226 offset:34816
	ds_read_b128 v[172:175], v226 offset:35840
	ds_read_b128 v[176:179], v226 offset:36864
	ds_read_b128 v[180:183], v226 offset:37888
	ds_read_b128 v[184:187], v226 offset:38912
	ds_read_b128 v[188:191], v226 offset:39936
	global_load_lds_dwordx4 v[216:217], off
	v_lshl_add_u64 v[216:217], s[42:43], 0, v[198:199]
	s_mov_b32 m0, s56
	s_nop 0
	global_load_lds_dwordx4 v[216:217], off
	s_waitcnt vmcnt(8)
	s_waitcnt lgkmcnt(0)
	s_barrier
	v_mfma_f32_16x16x32_bf16 v[148:151], v[104:107], v[160:163], v[148:151]
	v_mfma_f32_16x16x32_bf16 v[144:147], v[120:123], v[160:163], v[144:147]
	v_mfma_f32_16x16x32_bf16 v[116:119], v[104:107], v[168:171], v[116:119]
	v_mfma_f32_16x16x32_bf16 v[112:115], v[120:123], v[168:171], v[112:115]
	v_mfma_f32_16x16x32_bf16 v[92:95], v[104:107], v[176:179], v[92:95]
	v_mfma_f32_16x16x32_bf16 v[88:91], v[120:123], v[176:179], v[88:91]
	v_mfma_f32_16x16x32_bf16 v[76:79], v[104:107], v[184:187], v[76:79]
	v_mfma_f32_16x16x32_bf16 v[72:75], v[120:123], v[184:187], v[72:75]
	v_mfma_f32_16x16x32_bf16 v[148:151], v[108:111], v[164:167], v[148:151]
	v_mfma_f32_16x16x32_bf16 v[144:147], v[124:127], v[164:167], v[144:147]
	v_mfma_f32_16x16x32_bf16 v[116:119], v[108:111], v[172:175], v[116:119]
	v_mfma_f32_16x16x32_bf16 v[112:115], v[124:127], v[172:175], v[112:115]
	v_mfma_f32_16x16x32_bf16 v[92:95], v[108:111], v[180:183], v[92:95]
	v_mfma_f32_16x16x32_bf16 v[88:91], v[124:127], v[180:183], v[88:91]
	v_mfma_f32_16x16x32_bf16 v[76:79], v[108:111], v[188:191], v[76:79]
	v_mfma_f32_16x16x32_bf16 v[72:75], v[124:127], v[188:191], v[72:75]
	v_mfma_f32_16x16x32_bf16 v[132:135], v[136:139], v[160:163], v[132:135]
	v_mfma_f32_16x16x32_bf16 v[128:131], v[152:155], v[160:163], v[128:131]
	v_mfma_f32_16x16x32_bf16 v[100:103], v[136:139], v[168:171], v[100:103]
	v_mfma_f32_16x16x32_bf16 v[96:99], v[152:155], v[168:171], v[96:99]
	v_mfma_f32_16x16x32_bf16 v[84:87], v[136:139], v[176:179], v[84:87]
	v_mfma_f32_16x16x32_bf16 v[80:83], v[152:155], v[176:179], v[80:83]
	v_mfma_f32_16x16x32_bf16 v[68:71], v[136:139], v[184:187], v[68:71]
	v_mfma_f32_16x16x32_bf16 v[64:67], v[152:155], v[184:187], v[64:67]
	v_mfma_f32_16x16x32_bf16 v[132:135], v[140:143], v[164:167], v[132:135]
	v_mfma_f32_16x16x32_bf16 v[128:131], v[156:159], v[164:167], v[128:131]
	v_mfma_f32_16x16x32_bf16 v[100:103], v[140:143], v[172:175], v[100:103]
	v_mfma_f32_16x16x32_bf16 v[96:99], v[156:159], v[172:175], v[96:99]
	v_mfma_f32_16x16x32_bf16 v[84:87], v[140:143], v[180:183], v[84:87]
	v_mfma_f32_16x16x32_bf16 v[80:83], v[156:159], v[180:183], v[80:83]
	v_mfma_f32_16x16x32_bf16 v[68:71], v[140:143], v[188:191], v[68:71]
	v_mfma_f32_16x16x32_bf16 v[64:67], v[156:159], v[188:191], v[64:67]
	s_barrier
; #define PG8_STAGE(bufoff, gbase, voff) do { _Pragma("unroll") for (int _i = 0; _i < 2; ++_i) \
;         __builtin_amdgcn_global_load_lds((const unsigned*)((const char*)(gbase) + (voff)[_i]), (LAS unsigned*)(lds + (bufoff) + ldsw + _i * 8192), 16, 0, 0); } while (0)
; #define PG8_LDA(dst, b, h) do { _Pragma("unroll") for (int m = 0; m < 4; ++m) _Pragma("unroll") for (int k = 0; k < 2; ++k) dst[m][k] = *(const LAS bf16x8*)(lds + PG8_SA(b, h) + aoff + m * 2048 + k * 1024); } while (0)
; #define PG8_LDB(dst, b, h) do { _Pragma("unroll") for (int n = 0; n < 2; ++n) _Pragma("unroll") for (int k = 0; k < 2; ++k) dst[n][k] = *(const LAS bf16x8*)(lds + PG8_SB(b, h) + boff + n * 2048 + k * 1024); } while (0)
; #define PG8_MMA(ai, bj, At, Bt) do { __builtin_amdgcn_s_setprio(1); _Pragma("unroll") for (int m = 0; m < 4; ++m) _Pragma("unroll") for (int n = 0; n < 2; ++n) _Pragma("unroll") for (int k = 0; k < 2; ++k) \
;         acc[ai][bj][m][n] = __builtin_amdgcn_mfma_f32_16x16x32_bf16(Bt[n][k], At[m][k], acc[ai][bj][m][n], 0, 0, 0); __builtin_amdgcn_s_setprio(0); } while (0)
; #define PG8_BAR __builtin_amdgcn_s_barrier()
; template <class Epi, class Sched = StaticOrder, class EpiSub = NoSub, bool FAST = false>
; __device__ __forceinline__ void gemm_phase(LAS unsigned char* lds, const Gemm g, const Sched& S, const Epi& E, const EpiSub& ES = EpiSub()) {
;     ...
;             PG8_LDB(B0, 0, 0); PG8_LDB(B1, 0, 1); PG8_SCHED; PG8_LDA(At, 0, 0); PG8_STAGE(PG8_SA(1, 1), a1 + hstepA, voffA);
;             PG8_WAIT_V(8); PG8_WAIT_L(0); PG8_BAR; PG8_MMA(0, 0, At, B0); PG8_MMA(0, 1, At, B1); PG8_BAR; PG8_SCHED;
;             PG8_LDA(At, 0, 1); PG8_STAGE(PG8_SB(0, 0), b2, voffB); PG8_STAGE(PG8_SB(0, 1), b2 + hstepB, voffB); PG8_STAGE(PG8_SA(0, 0), a2, voffA);
;             PG8_WAIT_V(8); PG8_WAIT_L(0); PG8_BAR; PG8_MMA(1, 0, At, B0); PG8_MMA(1, 1, At, B1); PG8_BAR; PG8_SCHED;
;             PG8_LDB(B0, 1, 0); PG8_LDB(B1, 1, 1); PG8_SCHED; PG8_LDA(At, 1, 0); PG8_STAGE(PG8_SA(0, 1), a2 + hstepA, voffA);
;             PG8_WAIT_V(8); PG8_WAIT_L(0); PG8_BAR; PG8_MMA(0, 0, At, B0); PG8_MMA(0, 1, At, B1); PG8_BAR; PG8_SCHED;
;             PG8_LDA(At, 1, 1); PG8_STAGE(PG8_SB(1, 0), b3, voffB); PG8_STAGE(PG8_SB(1, 1), b3 + hstepB, voffB); PG8_STAGE(PG8_SA(1, 0), a3, voffA);
;             PG8_WAIT_V(8); PG8_WAIT_L(0); PG8_BAR; PG8_MMA(1, 0, At, B0); PG8_MMA(1, 1, At, B1); PG8_BAR; PG8_SCHED;
	s_add_i32 s42, s51, s52
	v_lshl_add_u64 v[208:209], v[208:209], 0, s[12:13]
	s_mov_b32 m0, s42
	ds_read_b128 v[160:163], v226 offset:49152
	ds_read_b128 v[164:167], v226 offset:50176
	ds_read_b128 v[168:171], v226 offset:51200
	ds_read_b128 v[172:175], v226 offset:52224
	ds_read_b128 v[176:179], v226 offset:53248
	ds_read_b128 v[180:183], v226 offset:54272
	ds_read_b128 v[184:187], v226 offset:55296
	ds_read_b128 v[188:191], v226 offset:56320
	global_load_lds_dwordx4 v[208:209], off
	s_add_i32 m0, s42, 0x2000
	s_add_u32 s40, s40, 0x80080
	v_lshl_add_u64 v[208:209], v[210:211], 0, s[12:13]
	s_addc_u32 s41, s41, 0
	s_add_i32 s42, s70, s52
	global_load_lds_dwordx4 v[208:209], off
	v_lshl_add_u64 v[208:209], s[40:41], 0, v[196:197]
	s_mov_b32 m0, s42
	s_nop 0
	global_load_lds_dwordx4 v[208:209], off
	v_lshl_add_u64 v[208:209], s[40:41], 0, v[200:201]
	s_add_i32 m0, s42, 0x2000
	s_nop 0
	global_load_lds_dwordx4 v[208:209], off
	v_lshl_add_u64 v[208:209], v[212:213], 0, s[12:13]
	s_mov_b32 m0, s69
	s_nop 0
	global_load_lds_dwordx4 v[208:209], off
	v_lshl_add_u64 v[208:209], v[214:215], 0, s[12:13]
	s_mov_b32 m0, s74
	s_nop 0
	global_load_lds_dwordx4 v[208:209], off
	s_add_u32 s38, s38, 0x100
	s_addc_u32 s39, s39, 0
	s_add_u32 s48, s48, 0x100
	s_addc_u32 s49, s49, 0
	s_waitcnt vmcnt(8)
	s_waitcnt lgkmcnt(0)
	s_barrier
	v_mfma_f32_16x16x32_bf16 v[60:63], v[104:107], v[160:163], v[60:63]
	v_mfma_f32_16x16x32_bf16 v[56:59], v[120:123], v[160:163], v[56:59]
	v_mfma_f32_16x16x32_bf16 v[44:47], v[104:107], v[168:171], v[44:47]
	v_mfma_f32_16x16x32_bf16 v[40:43], v[120:123], v[168:171], v[40:43]
	v_mfma_f32_16x16x32_bf16 v[28:31], v[104:107], v[176:179], v[28:31]
	v_mfma_f32_16x16x32_bf16 v[24:27], v[120:123], v[176:179], v[24:27]
	v_mfma_f32_16x16x32_bf16 v[12:15], v[104:107], v[184:187], v[12:15]
	v_mfma_f32_16x16x32_bf16 v[8:11], v[120:123], v[184:187], v[8:11]
	v_mfma_f32_16x16x32_bf16 v[60:63], v[108:111], v[164:167], v[60:63]
	v_mfma_f32_16x16x32_bf16 v[56:59], v[124:127], v[164:167], v[56:59]
	v_mfma_f32_16x16x32_bf16 v[44:47], v[108:111], v[172:175], v[44:47]
	v_mfma_f32_16x16x32_bf16 v[40:43], v[124:127], v[172:175], v[40:43]
	v_mfma_f32_16x16x32_bf16 v[28:31], v[108:111], v[180:183], v[28:31]
	v_mfma_f32_16x16x32_bf16 v[24:27], v[124:127], v[180:183], v[24:27]
	v_mfma_f32_16x16x32_bf16 v[12:15], v[108:111], v[188:191], v[12:15]
	v_mfma_f32_16x16x32_bf16 v[8:11], v[124:127], v[188:191], v[8:11]
	v_mfma_f32_16x16x32_bf16 v[52:55], v[136:139], v[160:163], v[52:55]
	v_mfma_f32_16x16x32_bf16 v[48:51], v[152:155], v[160:163], v[48:51]
	v_mfma_f32_16x16x32_bf16 v[36:39], v[136:139], v[168:171], v[36:39]
	v_mfma_f32_16x16x32_bf16 v[32:35], v[152:155], v[168:171], v[32:35]
	v_mfma_f32_16x16x32_bf16 v[20:23], v[136:139], v[176:179], v[20:23]
	v_mfma_f32_16x16x32_bf16 v[16:19], v[152:155], v[176:179], v[16:19]
	v_mfma_f32_16x16x32_bf16 v[4:7], v[136:139], v[184:187], v[4:7]
	v_mfma_f32_16x16x32_bf16 v[0:3], v[152:155], v[184:187], v[0:3]
	v_mfma_f32_16x16x32_bf16 v[52:55], v[140:143], v[164:167], v[52:55]
	v_mfma_f32_16x16x32_bf16 v[48:51], v[156:159], v[164:167], v[48:51]
	v_mfma_f32_16x16x32_bf16 v[36:39], v[140:143], v[172:175], v[36:39]
	v_mfma_f32_16x16x32_bf16 v[32:35], v[156:159], v[172:175], v[32:35]
	v_mfma_f32_16x16x32_bf16 v[20:23], v[140:143], v[180:183], v[20:23]
	v_mfma_f32_16x16x32_bf16 v[16:19], v[156:159], v[180:183], v[16:19]
	v_mfma_f32_16x16x32_bf16 v[4:7], v[140:143], v[188:191], v[4:7]
	v_mfma_f32_16x16x32_bf16 v[0:3], v[156:159], v[188:191], v[0:3]
	s_barrier
	s_cmp_ge_u32 s50, s31
	s_mov_b32 s42, s50
	s_cbranch_scc1 .Lkpeel_632_exit
.LBB0_632:
	ds_read_b128 v[104:107], v224
	ds_read_b128 v[108:111], v224 offset:1024
	ds_read_b128 v[120:123], v224 offset:2048
	ds_read_b128 v[124:127], v224 offset:3072
	ds_read_b128 v[136:139], v225
	ds_read_b128 v[140:143], v225 offset:1024
	ds_read_b128 v[152:155], v225 offset:2048
	ds_read_b128 v[156:159], v225 offset:3072
	s_add_i32 s50, s42, 2
	s_add_u32 s40, s38, 0xfff80080
	s_addc_u32 s41, s39, -1
	s_cmp_eq_u32 s33, s42
	s_cselect_b32 s42, s5, s40
	s_cselect_b32 s43, s1, s41
	s_cselect_b32 s41, s21, s49
	s_cselect_b32 s40, s23, s48
	v_lshl_add_u64 v[208:209], s[38:39], 0, v[202:203]
	s_add_i32 m0, s53, 0xc000
	ds_read_b128 v[160:163], v226
	ds_read_b128 v[164:167], v226 offset:1024
	ds_read_b128 v[168:171], v226 offset:2048
	ds_read_b128 v[172:175], v226 offset:3072
	ds_read_b128 v[176:179], v226 offset:4096
	ds_read_b128 v[180:183], v226 offset:5120
	ds_read_b128 v[184:187], v226 offset:6144
	ds_read_b128 v[188:191], v226 offset:7168
	global_load_lds_dwordx4 v[208:209], off
	v_lshl_add_u64 v[208:209], s[38:39], 0, v[204:205]
	s_add_i32 m0, s53, 0xe000
	s_nop 0
	global_load_lds_dwordx4 v[208:209], off
	s_waitcnt vmcnt(8)
	s_waitcnt lgkmcnt(0)
	s_barrier
; #define PG8_STAGE(bufoff, gbase, voff) do { _Pragma("unroll") for (int _i = 0; _i < 2; ++_i) \
;         __builtin_amdgcn_global_load_lds((const unsigned*)((const char*)(gbase) + (voff)[_i]), (LAS unsigned*)(lds + (bufoff) + ldsw + _i * 8192), 16, 0, 0); } while (0)
; #define PG8_LDA(dst, b, h) do { _Pragma("unroll") for (int m = 0; m < 4; ++m) _Pragma("unroll") for (int k = 0; k < 2; ++k) dst[m][k] = *(const LAS bf16x8*)(lds + PG8_SA(b, h) + aoff + m * 2048 + k * 1024); } while (0)
; #define PG8_LDB(dst, b, h) do { _Pragma("unroll") for (int n = 0; n < 2; ++n) _Pragma("unroll") for (int k = 0; k < 2; ++k) dst[n][k] = *(const LAS bf16x8*)(lds + PG8_SB(b, h) + boff + n * 2048 + k * 1024); } while (0)
; #define PG8_MMA(ai, bj, At, Bt) do { __builtin_amdgcn_s_setprio(1); _Pragma("unroll") for (int m = 0; m < 4; ++m) _Pragma("unroll") for (int n = 0; n < 2; ++n) _Pragma("unroll") for (int k = 0; k < 2; ++k) \
;         acc[ai][bj][m][n] = __builtin_amdgcn_mfma_f32_16x16x32_bf16(Bt[n][k], At[m][k], acc[ai][bj][m][n], 0, 0, 0); __builtin_amdgcn_s_setprio(0); } while (0)
; #define PG8_BAR __builtin_amdgcn_s_barrier()
; template <class Epi, class Sched = StaticOrder, class EpiSub = NoSub, bool FAST = false>
; __device__ __forceinline__ void gemm_phase(LAS unsigned char* lds, const Gemm g, const Sched& S, const Epi& E, const EpiSub& ES = EpiSub()) {
;     ...
;             PG8_LDB(B0, 0, 0); PG8_LDB(B1, 0, 1); PG8_SCHED; PG8_LDA(At, 0, 0); PG8_STAGE(PG8_SA(1, 1), a1 + hstepA, voffA);
;             PG8_WAIT_V(8); PG8_WAIT_L(0); PG8_BAR; PG8_MMA(0, 0, At, B0); PG8_MMA(0, 1, At, B1); PG8_BAR; PG8_SCHED;
;             PG8_LDA(At, 0, 1); PG8_STAGE(PG8_SB(0, 0), b2, voffB); PG8_STAGE(PG8_SB(0, 1), b2 + hstepB, voffB); PG8_STAGE(PG8_SA(0, 0), a2, voffA);
;             PG8_WAIT_V(8); PG8_WAIT_L(0); PG8_BAR; PG8_MMA(1, 0, At, B0); PG8_MMA(1, 1, At, B1); PG8_BAR; PG8_SCHED;
;             PG8_LDB(B0, 1, 0); PG8_LDB(B1, 1, 1); PG8_SCHED; PG8_LDA(At, 1, 0); PG8_STAGE(PG8_SA(0, 1), a2 + hstepA, voffA);
;             PG8_WAIT_V(8); PG8_WAIT_L(0); PG8_BAR; PG8_MMA(0, 0, At, B0); PG8_MMA(0, 1, At, B1); PG8_BAR; PG8_SCHED;
;             PG8_LDA(At, 1, 1); PG8_STAGE(PG8_SB(1, 0), b3, voffB); PG8_STAGE(PG8_SB(1, 1), b3 + hstepB, voffB); PG8_STAGE(PG8_SA(1, 0), a3, voffA);
;             PG8_WAIT_V(8); PG8_WAIT_L(0); PG8_BAR; PG8_MMA(1, 0, At, B0); PG8_MMA(1, 1, At, B1); PG8_BAR; PG8_SCHED;
	v_mfma_f32_16x16x32_bf16 v[148:151], v[104:107], v[160:163], v[148:151]
	v_mfma_f32_16x16x32_bf16 v[144:147], v[120:123], v[160:163], v[144:147]
	v_mfma_f32_16x16x32_bf16 v[116:119], v[104:107], v[168:171], v[116:119]
	v_mfma_f32_16x16x32_bf16 v[112:115], v[120:123], v[168:171], v[112:115]
	v_mfma_f32_16x16x32_bf16 v[92:95], v[104:107], v[176:179], v[92:95]
	v_mfma_f32_16x16x32_bf16 v[88:91], v[120:123], v[176:179], v[88:91]
	v_mfma_f32_16x16x32_bf16 v[76:79], v[104:107], v[184:187], v[76:79]
	v_mfma_f32_16x16x32_bf16 v[72:75], v[120:123], v[184:187], v[72:75]
	v_mfma_f32_16x16x32_bf16 v[148:151], v[108:111], v[164:167], v[148:151]
	v_mfma_f32_16x16x32_bf16 v[144:147], v[124:127], v[164:167], v[144:147]
	v_mfma_f32_16x16x32_bf16 v[116:119], v[108:111], v[172:175], v[116:119]
	v_mfma_f32_16x16x32_bf16 v[112:115], v[124:127], v[172:175], v[112:115]
	v_mfma_f32_16x16x32_bf16 v[92:95], v[108:111], v[180:183], v[92:95]
	v_mfma_f32_16x16x32_bf16 v[88:91], v[124:127], v[180:183], v[88:91]
	v_mfma_f32_16x16x32_bf16 v[76:79], v[108:111], v[188:191], v[76:79]
	v_mfma_f32_16x16x32_bf16 v[72:75], v[124:127], v[188:191], v[72:75]
	v_mfma_f32_16x16x32_bf16 v[132:135], v[136:139], v[160:163], v[132:135]
	v_mfma_f32_16x16x32_bf16 v[128:131], v[152:155], v[160:163], v[128:131]
	v_mfma_f32_16x16x32_bf16 v[100:103], v[136:139], v[168:171], v[100:103]
	v_mfma_f32_16x16x32_bf16 v[96:99], v[152:155], v[168:171], v[96:99]
	v_mfma_f32_16x16x32_bf16 v[84:87], v[136:139], v[176:179], v[84:87]
	v_mfma_f32_16x16x32_bf16 v[80:83], v[152:155], v[176:179], v[80:83]
	v_mfma_f32_16x16x32_bf16 v[68:71], v[136:139], v[184:187], v[68:71]
	v_mfma_f32_16x16x32_bf16 v[64:67], v[152:155], v[184:187], v[64:67]
	v_mfma_f32_16x16x32_bf16 v[132:135], v[140:143], v[164:167], v[132:135]
	v_mfma_f32_16x16x32_bf16 v[128:131], v[156:159], v[164:167], v[128:131]
	v_mfma_f32_16x16x32_bf16 v[100:103], v[140:143], v[172:175], v[100:103]
	v_mfma_f32_16x16x32_bf16 v[96:99], v[156:159], v[172:175], v[96:99]
	v_mfma_f32_16x16x32_bf16 v[84:87], v[140:143], v[180:183], v[84:87]
	v_mfma_f32_16x16x32_bf16 v[80:83], v[156:159], v[180:183], v[80:83]
	v_mfma_f32_16x16x32_bf16 v[68:71], v[140:143], v[188:191], v[68:71]
	v_mfma_f32_16x16x32_bf16 v[64:67], v[156:159], v[188:191], v[64:67]
	s_barrier
	s_add_i32 s51, s75, s52
	v_lshl_add_u64 v[208:209], s[40:41], 0, v[196:197]
	s_mov_b32 m0, s51
	ds_read_b128 v[160:163], v226 offset:16384
	ds_read_b128 v[164:167], v226 offset:17408
	ds_read_b128 v[168:171], v226 offset:18432
	ds_read_b128 v[172:175], v226 offset:19456
	ds_read_b128 v[176:179], v226 offset:20480
	ds_read_b128 v[180:183], v226 offset:21504
	ds_read_b128 v[184:187], v226 offset:22528
	ds_read_b128 v[188:191], v226 offset:23552
	global_load_lds_dwordx4 v[208:209], off
	s_add_i32 m0, s51, 0x2000
	s_add_u32 s70, s40, 0x80000
	v_lshl_add_u64 v[210:211], s[40:41], 0, v[200:201]
	s_addc_u32 s71, s41, 0
	s_add_i32 s51, s78, s52
	global_load_lds_dwordx4 v[210:211], off
	v_lshl_add_u64 v[212:213], s[70:71], 0, v[196:197]
	s_mov_b32 m0, s51
	v_lshl_add_u64 v[214:215], s[42:43], 0, v[198:199]
	global_load_lds_dwordx4 v[212:213], off
	v_lshl_add_u64 v[212:213], s[70:71], 0, v[200:201]
	s_add_i32 m0, s51, 0x2000
	s_nop 0
	global_load_lds_dwordx4 v[212:213], off
	v_lshl_add_u64 v[212:213], s[42:43], 0, v[194:195]
	s_mov_b32 m0, s53
	s_nop 0
	global_load_lds_dwordx4 v[212:213], off
	s_mov_b32 m0, s54
	s_nop 0
	global_load_lds_dwordx4 v[214:215], off
	s_waitcnt vmcnt(8)
	s_waitcnt lgkmcnt(0)
	s_barrier
	v_mfma_f32_16x16x32_bf16 v[60:63], v[104:107], v[160:163], v[60:63]
	v_mfma_f32_16x16x32_bf16 v[56:59], v[120:123], v[160:163], v[56:59]
	v_mfma_f32_16x16x32_bf16 v[44:47], v[104:107], v[168:171], v[44:47]
	v_mfma_f32_16x16x32_bf16 v[40:43], v[120:123], v[168:171], v[40:43]
	v_mfma_f32_16x16x32_bf16 v[28:31], v[104:107], v[176:179], v[28:31]
	v_mfma_f32_16x16x32_bf16 v[24:27], v[120:123], v[176:179], v[24:27]
	v_mfma_f32_16x16x32_bf16 v[12:15], v[104:107], v[184:187], v[12:15]
	v_mfma_f32_16x16x32_bf16 v[8:11], v[120:123], v[184:187], v[8:11]
	v_mfma_f32_16x16x32_bf16 v[60:63], v[108:111], v[164:167], v[60:63]
	v_mfma_f32_16x16x32_bf16 v[56:59], v[124:127], v[164:167], v[56:59]
	v_mfma_f32_16x16x32_bf16 v[44:47], v[108:111], v[172:175], v[44:47]
	v_mfma_f32_16x16x32_bf16 v[40:43], v[124:127], v[172:175], v[40:43]
	v_mfma_f32_16x16x32_bf16 v[28:31], v[108:111], v[180:183], v[28:31]
	v_mfma_f32_16x16x32_bf16 v[24:27], v[124:127], v[180:183], v[24:27]
	v_mfma_f32_16x16x32_bf16 v[12:15], v[108:111], v[188:191], v[12:15]
	v_mfma_f32_16x16x32_bf16 v[8:11], v[124:127], v[188:191], v[8:11]
	v_mfma_f32_16x16x32_bf16 v[52:55], v[136:139], v[160:163], v[52:55]
	v_mfma_f32_16x16x32_bf16 v[48:51], v[152:155], v[160:163], v[48:51]
	v_mfma_f32_16x16x32_bf16 v[36:39], v[136:139], v[168:171], v[36:39]
	v_mfma_f32_16x16x32_bf16 v[32:35], v[152:155], v[168:171], v[32:35]
	v_mfma_f32_16x16x32_bf16 v[20:23], v[136:139], v[176:179], v[20:23]
	v_mfma_f32_16x16x32_bf16 v[16:19], v[152:155], v[176:179], v[16:19]
	v_mfma_f32_16x16x32_bf16 v[4:7], v[136:139], v[184:187], v[4:7]
	v_mfma_f32_16x16x32_bf16 v[0:3], v[152:155], v[184:187], v[0:3]
	v_mfma_f32_16x16x32_bf16 v[52:55], v[140:143], v[164:167], v[52:55]
	v_mfma_f32_16x16x32_bf16 v[48:51], v[156:159], v[164:167], v[48:51]
	v_mfma_f32_16x16x32_bf16 v[36:39], v[140:143], v[172:175], v[36:39]
	v_mfma_f32_16x16x32_bf16 v[32:35], v[156:159], v[172:175], v[32:35]
	v_mfma_f32_16x16x32_bf16 v[20:23], v[140:143], v[180:183], v[20:23]
	v_mfma_f32_16x16x32_bf16 v[16:19], v[156:159], v[180:183], v[16:19]
	v_mfma_f32_16x16x32_bf16 v[4:7], v[140:143], v[188:191], v[4:7]
	v_mfma_f32_16x16x32_bf16 v[0:3], v[156:159], v[188:191], v[0:3]
	s_barrier
; #define PG8_STAGE(bufoff, gbase, voff) do { _Pragma("unroll") for (int _i = 0; _i < 2; ++_i) \
;         __builtin_amdgcn_global_load_lds((const unsigned*)((const char*)(gbase) + (voff)[_i]), (LAS unsigned*)(lds + (bufoff) + ldsw + _i * 8192), 16, 0, 0); } while (0)
; #define PG8_LDA(dst, b, h) do { _Pragma("unroll") for (int m = 0; m < 4; ++m) _Pragma("unroll") for (int k = 0; k < 2; ++k) dst[m][k] = *(const LAS bf16x8*)(lds + PG8_SA(b, h) + aoff + m * 2048 + k * 1024); } while (0)
; #define PG8_LDB(dst, b, h) do { _Pragma("unroll") for (int n = 0; n < 2; ++n) _Pragma("unroll") for (int k = 0; k < 2; ++k) dst[n][k] = *(const LAS bf16x8*)(lds + PG8_SB(b, h) + boff + n * 2048 + k * 1024); } while (0)
; #define PG8_MMA(ai, bj, At, Bt) do { __builtin_amdgcn_s_setprio(1); _Pragma("unroll") for (int m = 0; m < 4; ++m) _Pragma("unroll") for (int n = 0; n < 2; ++n) _Pragma("unroll") for (int k = 0; k < 2; ++k) \
;         acc[ai][bj][m][n] = __builtin_amdgcn_mfma_f32_16x16x32_bf16(Bt[n][k], At[m][k], acc[ai][bj][m][n], 0, 0, 0); __builtin_amdgcn_s_setprio(0); } while (0)
; #define PG8_BAR __builtin_amdgcn_s_barrier()
; template <class Epi, class Sched = StaticOrder, class EpiSub = NoSub, bool FAST = false>
; __device__ __forceinline__ void gemm_phase(LAS unsigned char* lds, const Gemm g, const Sched& S, const Epi& E, const EpiSub& ES = EpiSub()) {
;     ...
;             PG8_LDB(B0, 0, 0); PG8_LDB(B1, 0, 1); PG8_SCHED; PG8_LDA(At, 0, 0); PG8_STAGE(PG8_SA(1, 1), a1 + hstepA, voffA);
;             PG8_WAIT_V(8); PG8_WAIT_L(0); PG8_BAR; PG8_MMA(0, 0, At, B0); PG8_MMA(0, 1, At, B1); PG8_BAR; PG8_SCHED;
;             PG8_LDA(At, 0, 1); PG8_STAGE(PG8_SB(0, 0), b2, voffB); PG8_STAGE(PG8_SB(0, 1), b2 + hstepB, voffB); PG8_STAGE(PG8_SA(0, 0), a2, voffA);
;             PG8_WAIT_V(8); PG8_WAIT_L(0); PG8_BAR; PG8_MMA(1, 0, At, B0); PG8_MMA(1, 1, At, B1); PG8_BAR; PG8_SCHED;
;             PG8_LDB(B0, 1, 0); PG8_LDB(B1, 1, 1); PG8_SCHED; PG8_LDA(At, 1, 0); PG8_STAGE(PG8_SA(0, 1), a2 + hstepA, voffA);
;             PG8_WAIT_V(8); PG8_WAIT_L(0); PG8_BAR; PG8_MMA(0, 0, At, B0); PG8_MMA(0, 1, At, B1); PG8_BAR; PG8_SCHED;
;             PG8_LDA(At, 1, 1); PG8_STAGE(PG8_SB(1, 0), b3, voffB); PG8_STAGE(PG8_SB(1, 1), b3 + hstepB, voffB); PG8_STAGE(PG8_SA(1, 0), a3, voffA);
;             PG8_WAIT_V(8); PG8_WAIT_L(0); PG8_BAR; PG8_MMA(1, 0, At, B0); PG8_MMA(1, 1, At, B1); PG8_BAR; PG8_SCHED;
	s_add_i32 s51, 0, 0x18000
	s_add_i32 s70, 0, 0x1c000
	v_add_u32_e32 v124, s51, v221
	v_add_u32_e32 v156, s70, v221
	ds_read_b128 v[104:107], v124
	ds_read_b128 v[108:111], v124 offset:1024
	ds_read_b128 v[120:123], v124 offset:2048
	ds_read_b128 v[124:127], v124 offset:3072
	ds_read_b128 v[136:139], v156
	ds_read_b128 v[140:143], v156 offset:1024
	ds_read_b128 v[152:155], v156 offset:2048
	ds_read_b128 v[156:159], v156 offset:3072
	s_add_u32 s42, s42, 0x80000
	s_addc_u32 s43, s43, 0
	s_mov_b32 m0, s55
	v_lshl_add_u64 v[216:217], s[42:43], 0, v[194:195]
	ds_read_b128 v[160:163], v226 offset:32768
	ds_read_b128 v[164:167], v226 offset:33792
	ds_read_b128 v[168:171], v226 offset:34816
	ds_read_b128 v[172:175], v226 offset:35840
	ds_read_b128 v[176:179], v226 offset:36864
	ds_read_b128 v[180:183], v226 offset:37888
	ds_read_b128 v[184:187], v226 offset:38912
	ds_read_b128 v[188:191], v226 offset:39936
	global_load_lds_dwordx4 v[216:217], off
	v_lshl_add_u64 v[216:217], s[42:43], 0, v[198:199]
	s_mov_b32 m0, s56
	s_nop 0
	global_load_lds_dwordx4 v[216:217], off
	s_waitcnt vmcnt(8)
	s_waitcnt lgkmcnt(0)
	s_barrier
	v_mfma_f32_16x16x32_bf16 v[148:151], v[104:107], v[160:163], v[148:151]
	v_mfma_f32_16x16x32_bf16 v[144:147], v[120:123], v[160:163], v[144:147]
	v_mfma_f32_16x16x32_bf16 v[116:119], v[104:107], v[168:171], v[116:119]
	v_mfma_f32_16x16x32_bf16 v[112:115], v[120:123], v[168:171], v[112:115]
	v_mfma_f32_16x16x32_bf16 v[92:95], v[104:107], v[176:179], v[92:95]
	v_mfma_f32_16x16x32_bf16 v[88:91], v[120:123], v[176:179], v[88:91]
	v_mfma_f32_16x16x32_bf16 v[76:79], v[104:107], v[184:187], v[76:79]
	v_mfma_f32_16x16x32_bf16 v[72:75], v[120:123], v[184:187], v[72:75]
	v_mfma_f32_16x16x32_bf16 v[148:151], v[108:111], v[164:167], v[148:151]
	v_mfma_f32_16x16x32_bf16 v[144:147], v[124:127], v[164:167], v[144:147]
	v_mfma_f32_16x16x32_bf16 v[116:119], v[108:111], v[172:175], v[116:119]
	v_mfma_f32_16x16x32_bf16 v[112:115], v[124:127], v[172:175], v[112:115]
	v_mfma_f32_16x16x32_bf16 v[92:95], v[108:111], v[180:183], v[92:95]
	v_mfma_f32_16x16x32_bf16 v[88:91], v[124:127], v[180:183], v[88:91]
	v_mfma_f32_16x16x32_bf16 v[76:79], v[108:111], v[188:191], v[76:79]
	v_mfma_f32_16x16x32_bf16 v[72:75], v[124:127], v[188:191], v[72:75]
	v_mfma_f32_16x16x32_bf16 v[132:135], v[136:139], v[160:163], v[132:135]
	v_mfma_f32_16x16x32_bf16 v[128:131], v[152:155], v[160:163], v[128:131]
	v_mfma_f32_16x16x32_bf16 v[100:103], v[136:139], v[168:171], v[100:103]
	v_mfma_f32_16x16x32_bf16 v[96:99], v[152:155], v[168:171], v[96:99]
	v_mfma_f32_16x16x32_bf16 v[84:87], v[136:139], v[176:179], v[84:87]
	v_mfma_f32_16x16x32_bf16 v[80:83], v[152:155], v[176:179], v[80:83]
	v_mfma_f32_16x16x32_bf16 v[68:71], v[136:139], v[184:187], v[68:71]
	v_mfma_f32_16x16x32_bf16 v[64:67], v[152:155], v[184:187], v[64:67]
	v_mfma_f32_16x16x32_bf16 v[132:135], v[140:143], v[164:167], v[132:135]
	v_mfma_f32_16x16x32_bf16 v[128:131], v[156:159], v[164:167], v[128:131]
	v_mfma_f32_16x16x32_bf16 v[100:103], v[140:143], v[172:175], v[100:103]
	v_mfma_f32_16x16x32_bf16 v[96:99], v[156:159], v[172:175], v[96:99]
	v_mfma_f32_16x16x32_bf16 v[84:87], v[140:143], v[180:183], v[84:87]
	v_mfma_f32_16x16x32_bf16 v[80:83], v[156:159], v[180:183], v[80:83]
	v_mfma_f32_16x16x32_bf16 v[68:71], v[140:143], v[188:191], v[68:71]
	v_mfma_f32_16x16x32_bf16 v[64:67], v[156:159], v[188:191], v[64:67]
	s_barrier
	s_add_i32 s42, s51, s52
	v_lshl_add_u64 v[208:209], v[208:209], 0, s[12:13]
	s_mov_b32 m0, s42
	ds_read_b128 v[160:163], v226 offset:49152
	ds_read_b128 v[164:167], v226 offset:50176
	ds_read_b128 v[168:171], v226 offset:51200
	ds_read_b128 v[172:175], v226 offset:52224
	ds_read_b128 v[176:179], v226 offset:53248
	ds_read_b128 v[180:183], v226 offset:54272
	ds_read_b128 v[184:187], v226 offset:55296
	ds_read_b128 v[188:191], v226 offset:56320
	global_load_lds_dwordx4 v[208:209], off
	s_add_i32 m0, s42, 0x2000
	s_add_u32 s40, s40, 0x80080
	v_lshl_add_u64 v[208:209], v[210:211], 0, s[12:13]
	s_addc_u32 s41, s41, 0
	s_add_i32 s42, s70, s52
	global_load_lds_dwordx4 v[208:209], off
	v_lshl_add_u64 v[208:209], s[40:41], 0, v[196:197]
	s_mov_b32 m0, s42
	s_nop 0
	global_load_lds_dwordx4 v[208:209], off
	v_lshl_add_u64 v[208:209], s[40:41], 0, v[200:201]
	s_add_i32 m0, s42, 0x2000
	s_nop 0
	global_load_lds_dwordx4 v[208:209], off
	v_lshl_add_u64 v[208:209], v[212:213], 0, s[12:13]
	s_mov_b32 m0, s69
	s_nop 0
	global_load_lds_dwordx4 v[208:209], off
	v_lshl_add_u64 v[208:209], v[214:215], 0, s[12:13]
	s_mov_b32 m0, s74
	s_nop 0
	global_load_lds_dwordx4 v[208:209], off
	s_add_u32 s38, s38, 0x100
	s_addc_u32 s39, s39, 0
	s_add_u32 s48, s48, 0x100
	s_addc_u32 s49, s49, 0
	s_waitcnt vmcnt(8)
	s_waitcnt lgkmcnt(0)
	s_barrier
	v_mfma_f32_16x16x32_bf16 v[60:63], v[104:107], v[160:163], v[60:63]
	v_mfma_f32_16x16x32_bf16 v[56:59], v[120:123], v[160:163], v[56:59]
	v_mfma_f32_16x16x32_bf16 v[44:47], v[104:107], v[168:171], v[44:47]
	v_mfma_f32_16x16x32_bf16 v[40:43], v[120:123], v[168:171], v[40:43]
	v_mfma_f32_16x16x32_bf16 v[28:31], v[104:107], v[176:179], v[28:31]
	v_mfma_f32_16x16x32_bf16 v[24:27], v[120:123], v[176:179], v[24:27]
	v_mfma_f32_16x16x32_bf16 v[12:15], v[104:107], v[184:187], v[12:15]
	v_mfma_f32_16x16x32_bf16 v[8:11], v[120:123], v[184:187], v[8:11]
	v_mfma_f32_16x16x32_bf16 v[60:63], v[108:111], v[164:167], v[60:63]
	v_mfma_f32_16x16x32_bf16 v[56:59], v[124:127], v[164:167], v[56:59]
	v_mfma_f32_16x16x32_bf16 v[44:47], v[108:111], v[172:175], v[44:47]
	v_mfma_f32_16x16x32_bf16 v[40:43], v[124:127], v[172:175], v[40:43]
	v_mfma_f32_16x16x32_bf16 v[28:31], v[108:111], v[180:183], v[28:31]
	v_mfma_f32_16x16x32_bf16 v[24:27], v[124:127], v[180:183], v[24:27]
	v_mfma_f32_16x16x32_bf16 v[12:15], v[108:111], v[188:191], v[12:15]
	v_mfma_f32_16x16x32_bf16 v[8:11], v[124:127], v[188:191], v[8:11]
	v_mfma_f32_16x16x32_bf16 v[52:55], v[136:139], v[160:163], v[52:55]
	v_mfma_f32_16x16x32_bf16 v[48:51], v[152:155], v[160:163], v[48:51]
	v_mfma_f32_16x16x32_bf16 v[36:39], v[136:139], v[168:171], v[36:39]
	v_mfma_f32_16x16x32_bf16 v[32:35], v[152:155], v[168:171], v[32:35]
	v_mfma_f32_16x16x32_bf16 v[20:23], v[136:139], v[176:179], v[20:23]
	v_mfma_f32_16x16x32_bf16 v[16:19], v[152:155], v[176:179], v[16:19]
	v_mfma_f32_16x16x32_bf16 v[4:7], v[136:139], v[184:187], v[4:7]
	v_mfma_f32_16x16x32_bf16 v[0:3], v[152:155], v[184:187], v[0:3]
	v_mfma_f32_16x16x32_bf16 v[52:55], v[140:143], v[164:167], v[52:55]
	v_mfma_f32_16x16x32_bf16 v[48:51], v[156:159], v[164:167], v[48:51]
	v_mfma_f32_16x16x32_bf16 v[36:39], v[140:143], v[172:175], v[36:39]
	v_mfma_f32_16x16x32_bf16 v[32:35], v[156:159], v[172:175], v[32:35]
	v_mfma_f32_16x16x32_bf16 v[20:23], v[140:143], v[180:183], v[20:23]
	v_mfma_f32_16x16x32_bf16 v[16:19], v[156:159], v[180:183], v[16:19]
	v_mfma_f32_16x16x32_bf16 v[4:7], v[140:143], v[188:191], v[4:7]
	v_mfma_f32_16x16x32_bf16 v[0:3], v[156:159], v[188:191], v[0:3]
	s_barrier
	s_cmp_ge_u32 s50, s31
	s_mov_b32 s42, s50
	s_cbranch_scc0 .LBB0_632

; #define PG8_STAGE(bufoff, gbase, voff) do { _Pragma("unroll") for (int _i = 0; _i < 2; ++_i) \
;         __builtin_amdgcn_global_load_lds((const unsigned*)((const char*)(gbase) + (voff)[_i]), (LAS unsigned*)(lds + (bufoff) + ldsw + _i * 8192), 16, 0, 0); } while (0)
; #define PG8_WAIT_V(n) asm volatile("s_waitcnt vmcnt(" #n ")" ::: "memory")
; #define PG8_BAR __builtin_amdgcn_s_barrier()
; template <class Epi, class Sched = StaticOrder, class EpiSub = NoSub, bool FAST = false>
; __device__ __forceinline__ void gemm_phase(LAS unsigned char* lds, const Gemm g, const Sched& S, const Epi& E, const EpiSub& ES = EpiSub()) {
;     ...
;         const size_t nko = (has_next && nxt.kb >= 0) ? nxt.kb * ksubB : 0;
;         const char* nA = has_next ? (const char*)g.A + (size_t)nxt.pm * tstepA + (size_t)nxt.pn * g.acs + nko : cA; const char* nB = has_next ? (const char*)g.Bt + (size_t)nxt.pn * tstepB + nko : cB;
;         const int nt = cur.kb < 0 ? ntMain : ntSub;
;         for (int t = 0; t < nt; t += 2) {
;             const bool last = (t == nt - 2);
;             const char* a1 = cA + (size_t)(t + 1) * kstep;
;             const char* a2 = last ? nA : cA + (size_t)(t + 2) * kstep; const char* b2 = last ? nB : cB + (size_t)(t + 2) * kstep;
;             const char* a3 = a2 + kstep; const char* b3 = b2 + kstep;
;             if constexpr (FAST && PG8_SP2) {
;             PG8_LDB(B0, 0, 0); PG8_LDB(B1, 0, 1); PG8_SCHED; PG8_LDA(At, 0, 0); PG8_STAGE(PG8_SA(1, 1), a1 + hstepA, voffA);
;             PG8_WAIT_V(8); PG8_WAIT_L(0); PG8_BAR; PG8_MMA(0, 0, At, B0); PG8_MMA(0, 1, At, B1); PG8_BAR; PG8_SCHED;
;             PG8_LDA(At, 0, 1); PG8_STAGE(PG8_SB(0, 0), b2, voffB); PG8_STAGE(PG8_SB(0, 1), b2 + hstepB, voffB); PG8_STAGE(PG8_SA(0, 0), a2, voffA);
;             PG8_WAIT_V(8); PG8_WAIT_L(0); PG8_BAR; PG8_MMA(1, 0, At, B0); PG8_MMA(1, 1, At, B1); PG8_BAR; PG8_SCHED;
;             PG8_LDB(B0, 1, 0); PG8_LDB(B1, 1, 1); PG8_SCHED; PG8_LDA(At, 1, 0); PG8_STAGE(PG8_SA(0, 1), a2 + hstepA, voffA);
;             PG8_WAIT_V(8); PG8_WAIT_L(0); PG8_BAR; PG8_MMA(0, 0, At, B0); PG8_MMA(0, 1, At, B1); PG8_BAR; PG8_SCHED;
;             PG8_LDA(At, 1, 1); PG8_STAGE(PG8_SB(1, 0), b3, voffB); PG8_STAGE(PG8_SB(1, 1), b3 + hstepB, voffB); PG8_STAGE(PG8_SA(1, 0), a3, voffA);
;             PG8_WAIT_V(8); PG8_WAIT_L(0); PG8_BAR; PG8_MMA(1, 0, At, B0); PG8_MMA(1, 1, At, B1); PG8_BAR; PG8_SCHED;
.LBB0_768:
	s_cmp_gt_i32 s6, -1
	s_cselect_b64 s[24:25], -1, 0
	s_and_b64 s[24:25], s[22:23], s[24:25]
	s_lshl_b64 s[26:27], s[6:7], 9
	s_and_b64 s[24:25], s[24:25], exec
	s_cselect_b32 s29, s27, 0
	s_cselect_b32 s30, s26, 0
	s_ashr_i32 s21, s20, 31
	s_lshl_b64 s[24:25], s[20:21], 20
	s_add_u32 s1, s84, s24
	s_addc_u32 s5, s85, s25
	s_add_u32 s24, s1, s30
	s_addc_u32 s25, s5, s29
	s_and_b64 s[26:27], s[22:23], exec
	s_cselect_b32 s1, s25, s39
	s_cselect_b32 s5, s24, s38
	s_ashr_i32 s19, s18, 31
	s_lshl_b64 s[26:27], s[18:19], 20
	s_add_u32 s19, s2, s26
	s_addc_u32 s21, s3, s27
	s_add_u32 s26, s19, s30
	s_addc_u32 s27, s21, s29
	s_and_b64 s[30:31], s[22:23], exec
	s_cselect_b32 s19, s27, s41
	s_cselect_b32 s21, s26, s40
	s_cmp_gt_i32 s4, -1
	s_cselect_b64 s[30:31], -1, 0
	s_cmp_lt_i32 s4, 0
	s_cselect_b32 s29, 32, 4
	s_add_i32 s33, s29, -2
	s_add_u32 s38, s38, 0x80080
	s_addc_u32 s39, s39, 0
	s_add_u32 s70, s40, 0x100
	s_mov_b32 s42, 0
	s_addc_u32 s71, s41, 0
	ds_read_b128 v[96:99], v215
	ds_read_b128 v[100:103], v215 offset:1024
	ds_read_b128 v[112:115], v215 offset:2048
	ds_read_b128 v[116:119], v215 offset:3072
	ds_read_b128 v[144:147], v216
	ds_read_b128 v[148:151], v216 offset:1024
	ds_read_b128 v[152:155], v216 offset:2048
	ds_read_b128 v[156:159], v216 offset:3072
	s_add_i32 s72, s42, 2
	s_add_u32 s40, s38, 0xfff80080
	s_addc_u32 s41, s39, -1
	s_cmp_eq_u32 s33, s42
	s_cselect_b32 s42, s5, s40
	s_cselect_b32 s43, s1, s41
	s_cselect_b32 s41, s19, s71
	s_cselect_b32 s40, s21, s70
	v_lshl_add_u64 v[208:209], s[38:39], 0, v[194:195]
	s_add_i32 m0, s48, 0xc000
	ds_read_b128 v[160:163], v217
	ds_read_b128 v[164:167], v217 offset:1024
	ds_read_b128 v[168:171], v217 offset:2048
	ds_read_b128 v[172:175], v217 offset:3072
	ds_read_b128 v[176:179], v217 offset:4096
	ds_read_b128 v[180:183], v217 offset:5120
	ds_read_b128 v[200:203], v217 offset:6144
	ds_read_b128 v[204:207], v217 offset:7168
	global_load_lds_dwordx4 v[208:209], off
	v_lshl_add_u64 v[208:209], s[38:39], 0, v[196:197]
	s_add_i32 m0, s48, 0xe000
	s_nop 0
	global_load_lds_dwordx4 v[208:209], off
	s_waitcnt vmcnt(8)
	s_waitcnt lgkmcnt(0)
	s_barrier
	v_mfma_f32_16x16x32_bf16 v[140:143], v[96:99], v[160:163], 0
	v_mfma_f32_16x16x32_bf16 v[136:139], v[112:115], v[160:163], 0
	v_mfma_f32_16x16x32_bf16 v[124:127], v[96:99], v[168:171], 0
	v_mfma_f32_16x16x32_bf16 v[120:123], v[112:115], v[168:171], 0
	v_mfma_f32_16x16x32_bf16 v[92:95], v[96:99], v[176:179], 0
	v_mfma_f32_16x16x32_bf16 v[88:91], v[112:115], v[176:179], 0
	v_mfma_f32_16x16x32_bf16 v[76:79], v[96:99], v[200:203], 0
	v_mfma_f32_16x16x32_bf16 v[72:75], v[112:115], v[200:203], 0
	v_mfma_f32_16x16x32_bf16 v[140:143], v[100:103], v[164:167], v[140:143]
	v_mfma_f32_16x16x32_bf16 v[136:139], v[116:119], v[164:167], v[136:139]
	v_mfma_f32_16x16x32_bf16 v[124:127], v[100:103], v[172:175], v[124:127]
	v_mfma_f32_16x16x32_bf16 v[120:123], v[116:119], v[172:175], v[120:123]
	v_mfma_f32_16x16x32_bf16 v[92:95], v[100:103], v[180:183], v[92:95]
	v_mfma_f32_16x16x32_bf16 v[88:91], v[116:119], v[180:183], v[88:91]
	v_mfma_f32_16x16x32_bf16 v[76:79], v[100:103], v[204:207], v[76:79]
	v_mfma_f32_16x16x32_bf16 v[72:75], v[116:119], v[204:207], v[72:75]
	v_mfma_f32_16x16x32_bf16 v[132:135], v[144:147], v[160:163], 0
	v_mfma_f32_16x16x32_bf16 v[128:131], v[152:155], v[160:163], 0
	v_mfma_f32_16x16x32_bf16 v[108:111], v[144:147], v[168:171], 0
	v_mfma_f32_16x16x32_bf16 v[104:107], v[152:155], v[168:171], 0
	v_mfma_f32_16x16x32_bf16 v[84:87], v[144:147], v[176:179], 0
	v_mfma_f32_16x16x32_bf16 v[80:83], v[152:155], v[176:179], 0
	v_mfma_f32_16x16x32_bf16 v[68:71], v[144:147], v[200:203], 0
	v_mfma_f32_16x16x32_bf16 v[64:67], v[152:155], v[200:203], 0
	v_mfma_f32_16x16x32_bf16 v[132:135], v[148:151], v[164:167], v[132:135]
	v_mfma_f32_16x16x32_bf16 v[128:131], v[156:159], v[164:167], v[128:131]
	v_mfma_f32_16x16x32_bf16 v[108:111], v[148:151], v[172:175], v[108:111]
	v_mfma_f32_16x16x32_bf16 v[104:107], v[156:159], v[172:175], v[104:107]
	v_mfma_f32_16x16x32_bf16 v[84:87], v[148:151], v[180:183], v[84:87]
	v_mfma_f32_16x16x32_bf16 v[80:83], v[156:159], v[180:183], v[80:83]
	v_mfma_f32_16x16x32_bf16 v[68:71], v[148:151], v[204:207], v[68:71]
	v_mfma_f32_16x16x32_bf16 v[64:67], v[156:159], v[204:207], v[64:67]
	s_barrier
	s_add_i32 s73, s58, s17
	v_lshl_add_u64 v[208:209], s[40:41], 0, v[186:187]
	s_mov_b32 m0, s73
	ds_read_b128 v[160:163], v217 offset:16384
	ds_read_b128 v[164:167], v217 offset:17408
	ds_read_b128 v[168:171], v217 offset:18432
	ds_read_b128 v[172:175], v217 offset:19456
	ds_read_b128 v[176:179], v217 offset:20480
	ds_read_b128 v[180:183], v217 offset:21504
	ds_read_b128 v[200:203], v217 offset:22528
	ds_read_b128 v[204:207], v217 offset:23552
	global_load_lds_dwordx4 v[208:209], off
	s_add_i32 m0, s73, 0x2000
	s_add_u32 s76, s40, 0x80000
	v_lshl_add_u64 v[210:211], s[40:41], 0, v[190:191]
	s_addc_u32 s77, s41, 0
	s_add_i32 s73, s59, s17
	global_load_lds_dwordx4 v[210:211], off
	v_lshl_add_u64 v[218:219], s[76:77], 0, v[186:187]
	s_mov_b32 m0, s73
	v_lshl_add_u64 v[220:221], s[42:43], 0, v[188:189]
	global_load_lds_dwordx4 v[218:219], off
	v_lshl_add_u64 v[218:219], s[76:77], 0, v[190:191]
	s_add_i32 m0, s73, 0x2000
	s_nop 0
	global_load_lds_dwordx4 v[218:219], off
	v_lshl_add_u64 v[218:219], s[42:43], 0, v[184:185]
	s_mov_b32 m0, s48
	s_nop 0
	global_load_lds_dwordx4 v[218:219], off
	s_mov_b32 m0, s49
	s_nop 0
	global_load_lds_dwordx4 v[220:221], off
	s_waitcnt vmcnt(8)
	s_waitcnt lgkmcnt(0)
	s_barrier
; #define PG8_STAGE(bufoff, gbase, voff) do { _Pragma("unroll") for (int _i = 0; _i < 2; ++_i) \
;         __builtin_amdgcn_global_load_lds((const unsigned*)((const char*)(gbase) + (voff)[_i]), (LAS unsigned*)(lds + (bufoff) + ldsw + _i * 8192), 16, 0, 0); } while (0)
; #define PG8_LDA(dst, b, h) do { _Pragma("unroll") for (int m = 0; m < 4; ++m) _Pragma("unroll") for (int k = 0; k < 2; ++k) dst[m][k] = *(const LAS bf16x8*)(lds + PG8_SA(b, h) + aoff + m * 2048 + k * 1024); } while (0)
; #define PG8_LDB(dst, b, h) do { _Pragma("unroll") for (int n = 0; n < 2; ++n) _Pragma("unroll") for (int k = 0; k < 2; ++k) dst[n][k] = *(const LAS bf16x8*)(lds + PG8_SB(b, h) + boff + n * 2048 + k * 1024); } while (0)
; #define PG8_MMA(ai, bj, At, Bt) do { __builtin_amdgcn_s_setprio(1); _Pragma("unroll") for (int m = 0; m < 4; ++m) _Pragma("unroll") for (int n = 0; n < 2; ++n) _Pragma("unroll") for (int k = 0; k < 2; ++k) \
;         acc[ai][bj][m][n] = __builtin_amdgcn_mfma_f32_16x16x32_bf16(Bt[n][k], At[m][k], acc[ai][bj][m][n], 0, 0, 0); __builtin_amdgcn_s_setprio(0); } while (0)
; #define PG8_BAR __builtin_amdgcn_s_barrier()
; template <class Epi, class Sched = StaticOrder, class EpiSub = NoSub, bool FAST = false>
; __device__ __forceinline__ void gemm_phase(LAS unsigned char* lds, const Gemm g, const Sched& S, const Epi& E, const EpiSub& ES = EpiSub()) {
;     ...
;             PG8_LDB(B0, 0, 0); PG8_LDB(B1, 0, 1); PG8_SCHED; PG8_LDA(At, 0, 0); PG8_STAGE(PG8_SA(1, 1), a1 + hstepA, voffA);
;             PG8_WAIT_V(8); PG8_WAIT_L(0); PG8_BAR; PG8_MMA(0, 0, At, B0); PG8_MMA(0, 1, At, B1); PG8_BAR; PG8_SCHED;
;             PG8_LDA(At, 0, 1); PG8_STAGE(PG8_SB(0, 0), b2, voffB); PG8_STAGE(PG8_SB(0, 1), b2 + hstepB, voffB); PG8_STAGE(PG8_SA(0, 0), a2, voffA);
;             PG8_WAIT_V(8); PG8_WAIT_L(0); PG8_BAR; PG8_MMA(1, 0, At, B0); PG8_MMA(1, 1, At, B1); PG8_BAR; PG8_SCHED;
;             PG8_LDB(B0, 1, 0); PG8_LDB(B1, 1, 1); PG8_SCHED; PG8_LDA(At, 1, 0); PG8_STAGE(PG8_SA(0, 1), a2 + hstepA, voffA);
;             PG8_WAIT_V(8); PG8_WAIT_L(0); PG8_BAR; PG8_MMA(0, 0, At, B0); PG8_MMA(0, 1, At, B1); PG8_BAR; PG8_SCHED;
;             PG8_LDA(At, 1, 1); PG8_STAGE(PG8_SB(1, 0), b3, voffB); PG8_STAGE(PG8_SB(1, 1), b3 + hstepB, voffB); PG8_STAGE(PG8_SA(1, 0), a3, voffA);
;             PG8_WAIT_V(8); PG8_WAIT_L(0); PG8_BAR; PG8_MMA(1, 0, At, B0); PG8_MMA(1, 1, At, B1); PG8_BAR; PG8_SCHED;
	v_mfma_f32_16x16x32_bf16 v[60:63], v[96:99], v[160:163], 0
	v_mfma_f32_16x16x32_bf16 v[56:59], v[112:115], v[160:163], 0
	v_mfma_f32_16x16x32_bf16 v[44:47], v[96:99], v[168:171], 0
	v_mfma_f32_16x16x32_bf16 v[40:43], v[112:115], v[168:171], 0
	v_mfma_f32_16x16x32_bf16 v[28:31], v[96:99], v[176:179], 0
	v_mfma_f32_16x16x32_bf16 v[24:27], v[112:115], v[176:179], 0
	v_mfma_f32_16x16x32_bf16 v[12:15], v[96:99], v[200:203], 0
	v_mfma_f32_16x16x32_bf16 v[8:11], v[112:115], v[200:203], 0
	v_mfma_f32_16x16x32_bf16 v[60:63], v[100:103], v[164:167], v[60:63]
	v_mfma_f32_16x16x32_bf16 v[56:59], v[116:119], v[164:167], v[56:59]
	v_mfma_f32_16x16x32_bf16 v[44:47], v[100:103], v[172:175], v[44:47]
	v_mfma_f32_16x16x32_bf16 v[40:43], v[116:119], v[172:175], v[40:43]
	v_mfma_f32_16x16x32_bf16 v[28:31], v[100:103], v[180:183], v[28:31]
	v_mfma_f32_16x16x32_bf16 v[24:27], v[116:119], v[180:183], v[24:27]
	v_mfma_f32_16x16x32_bf16 v[12:15], v[100:103], v[204:207], v[12:15]
	v_mfma_f32_16x16x32_bf16 v[8:11], v[116:119], v[204:207], v[8:11]
	v_mfma_f32_16x16x32_bf16 v[52:55], v[144:147], v[160:163], 0
	v_mfma_f32_16x16x32_bf16 v[48:51], v[152:155], v[160:163], 0
	v_mfma_f32_16x16x32_bf16 v[36:39], v[144:147], v[168:171], 0
	v_mfma_f32_16x16x32_bf16 v[32:35], v[152:155], v[168:171], 0
	v_mfma_f32_16x16x32_bf16 v[20:23], v[144:147], v[176:179], 0
	v_mfma_f32_16x16x32_bf16 v[16:19], v[152:155], v[176:179], 0
	v_mfma_f32_16x16x32_bf16 v[4:7], v[144:147], v[200:203], 0
	v_mfma_f32_16x16x32_bf16 v[0:3], v[152:155], v[200:203], 0
	v_mfma_f32_16x16x32_bf16 v[52:55], v[148:151], v[164:167], v[52:55]
	v_mfma_f32_16x16x32_bf16 v[48:51], v[156:159], v[164:167], v[48:51]
	v_mfma_f32_16x16x32_bf16 v[36:39], v[148:151], v[172:175], v[36:39]
	v_mfma_f32_16x16x32_bf16 v[32:35], v[156:159], v[172:175], v[32:35]
	v_mfma_f32_16x16x32_bf16 v[20:23], v[148:151], v[180:183], v[20:23]
	v_mfma_f32_16x16x32_bf16 v[16:19], v[156:159], v[180:183], v[16:19]
	v_mfma_f32_16x16x32_bf16 v[4:7], v[148:151], v[204:207], v[4:7]
	v_mfma_f32_16x16x32_bf16 v[0:3], v[156:159], v[204:207], v[0:3]
	s_barrier
	s_add_i32 s73, 0, 0x18000
	s_add_i32 s76, 0, 0x1c000
	v_add_u32_e32 v116, s73, v212
	v_add_u32_e32 v156, s76, v212
	ds_read_b128 v[96:99], v116
	ds_read_b128 v[100:103], v116 offset:1024
	ds_read_b128 v[112:115], v116 offset:2048
	ds_read_b128 v[116:119], v116 offset:3072
	ds_read_b128 v[144:147], v156
	ds_read_b128 v[148:151], v156 offset:1024
	ds_read_b128 v[152:155], v156 offset:2048
	ds_read_b128 v[156:159], v156 offset:3072
	s_add_u32 s42, s42, 0x80000
	s_addc_u32 s43, s43, 0
	s_mov_b32 m0, s50
	v_lshl_add_u64 v[222:223], s[42:43], 0, v[184:185]
	ds_read_b128 v[160:163], v217 offset:32768
	ds_read_b128 v[164:167], v217 offset:33792
	ds_read_b128 v[168:171], v217 offset:34816
	ds_read_b128 v[172:175], v217 offset:35840
	ds_read_b128 v[176:179], v217 offset:36864
	ds_read_b128 v[180:183], v217 offset:37888
	ds_read_b128 v[200:203], v217 offset:38912
	ds_read_b128 v[204:207], v217 offset:39936
	global_load_lds_dwordx4 v[222:223], off
	v_lshl_add_u64 v[222:223], s[42:43], 0, v[188:189]
	s_mov_b32 m0, s51
	s_nop 0
	global_load_lds_dwordx4 v[222:223], off
	s_waitcnt vmcnt(8)
	s_waitcnt lgkmcnt(0)
	s_barrier
	v_mfma_f32_16x16x32_bf16 v[140:143], v[96:99], v[160:163], v[140:143]
	v_mfma_f32_16x16x32_bf16 v[136:139], v[112:115], v[160:163], v[136:139]
	v_mfma_f32_16x16x32_bf16 v[124:127], v[96:99], v[168:171], v[124:127]
	v_mfma_f32_16x16x32_bf16 v[120:123], v[112:115], v[168:171], v[120:123]
	v_mfma_f32_16x16x32_bf16 v[92:95], v[96:99], v[176:179], v[92:95]
	v_mfma_f32_16x16x32_bf16 v[88:91], v[112:115], v[176:179], v[88:91]
	v_mfma_f32_16x16x32_bf16 v[76:79], v[96:99], v[200:203], v[76:79]
	v_mfma_f32_16x16x32_bf16 v[72:75], v[112:115], v[200:203], v[72:75]
	v_mfma_f32_16x16x32_bf16 v[140:143], v[100:103], v[164:167], v[140:143]
	v_mfma_f32_16x16x32_bf16 v[136:139], v[116:119], v[164:167], v[136:139]
	v_mfma_f32_16x16x32_bf16 v[124:127], v[100:103], v[172:175], v[124:127]
	v_mfma_f32_16x16x32_bf16 v[120:123], v[116:119], v[172:175], v[120:123]
	v_mfma_f32_16x16x32_bf16 v[92:95], v[100:103], v[180:183], v[92:95]
	v_mfma_f32_16x16x32_bf16 v[88:91], v[116:119], v[180:183], v[88:91]
	v_mfma_f32_16x16x32_bf16 v[76:79], v[100:103], v[204:207], v[76:79]
	v_mfma_f32_16x16x32_bf16 v[72:75], v[116:119], v[204:207], v[72:75]
	v_mfma_f32_16x16x32_bf16 v[132:135], v[144:147], v[160:163], v[132:135]
	v_mfma_f32_16x16x32_bf16 v[128:131], v[152:155], v[160:163], v[128:131]
	v_mfma_f32_16x16x32_bf16 v[108:111], v[144:147], v[168:171], v[108:111]
	v_mfma_f32_16x16x32_bf16 v[104:107], v[152:155], v[168:171], v[104:107]
	v_mfma_f32_16x16x32_bf16 v[84:87], v[144:147], v[176:179], v[84:87]
	v_mfma_f32_16x16x32_bf16 v[80:83], v[152:155], v[176:179], v[80:83]
	v_mfma_f32_16x16x32_bf16 v[68:71], v[144:147], v[200:203], v[68:71]
	v_mfma_f32_16x16x32_bf16 v[64:67], v[152:155], v[200:203], v[64:67]
	v_mfma_f32_16x16x32_bf16 v[132:135], v[148:151], v[164:167], v[132:135]
	v_mfma_f32_16x16x32_bf16 v[128:131], v[156:159], v[164:167], v[128:131]
	v_mfma_f32_16x16x32_bf16 v[108:111], v[148:151], v[172:175], v[108:111]
	v_mfma_f32_16x16x32_bf16 v[104:107], v[156:159], v[172:175], v[104:107]
	v_mfma_f32_16x16x32_bf16 v[84:87], v[148:151], v[180:183], v[84:87]
	v_mfma_f32_16x16x32_bf16 v[80:83], v[156:159], v[180:183], v[80:83]
	v_mfma_f32_16x16x32_bf16 v[68:71], v[148:151], v[204:207], v[68:71]
	v_mfma_f32_16x16x32_bf16 v[64:67], v[156:159], v[204:207], v[64:67]
	s_barrier
; #define PG8_STAGE(bufoff, gbase, voff) do { _Pragma("unroll") for (int _i = 0; _i < 2; ++_i) \
;         __builtin_amdgcn_global_load_lds((const unsigned*)((const char*)(gbase) + (voff)[_i]), (LAS unsigned*)(lds + (bufoff) + ldsw + _i * 8192), 16, 0, 0); } while (0)
; #define PG8_LDA(dst, b, h) do { _Pragma("unroll") for (int m = 0; m < 4; ++m) _Pragma("unroll") for (int k = 0; k < 2; ++k) dst[m][k] = *(const LAS bf16x8*)(lds + PG8_SA(b, h) + aoff + m * 2048 + k * 1024); } while (0)
; #define PG8_LDB(dst, b, h) do { _Pragma("unroll") for (int n = 0; n < 2; ++n) _Pragma("unroll") for (int k = 0; k < 2; ++k) dst[n][k] = *(const LAS bf16x8*)(lds + PG8_SB(b, h) + boff + n * 2048 + k * 1024); } while (0)
; #define PG8_MMA(ai, bj, At, Bt) do { __builtin_amdgcn_s_setprio(1); _Pragma("unroll") for (int m = 0; m < 4; ++m) _Pragma("unroll") for (int n = 0; n < 2; ++n) _Pragma("unroll") for (int k = 0; k < 2; ++k) \
;         acc[ai][bj][m][n] = __builtin_amdgcn_mfma_f32_16x16x32_bf16(Bt[n][k], At[m][k], acc[ai][bj][m][n], 0, 0, 0); __builtin_amdgcn_s_setprio(0); } while (0)
; #define PG8_BAR __builtin_amdgcn_s_barrier()
; template <class Epi, class Sched = StaticOrder, class EpiSub = NoSub, bool FAST = false>
; __device__ __forceinline__ void gemm_phase(LAS unsigned char* lds, const Gemm g, const Sched& S, const Epi& E, const EpiSub& ES = EpiSub()) {
;     ...
;             PG8_LDB(B0, 0, 0); PG8_LDB(B1, 0, 1); PG8_SCHED; PG8_LDA(At, 0, 0); PG8_STAGE(PG8_SA(1, 1), a1 + hstepA, voffA);
;             PG8_WAIT_V(8); PG8_WAIT_L(0); PG8_BAR; PG8_MMA(0, 0, At, B0); PG8_MMA(0, 1, At, B1); PG8_BAR; PG8_SCHED;
;             PG8_LDA(At, 0, 1); PG8_STAGE(PG8_SB(0, 0), b2, voffB); PG8_STAGE(PG8_SB(0, 1), b2 + hstepB, voffB); PG8_STAGE(PG8_SA(0, 0), a2, voffA);
;             PG8_WAIT_V(8); PG8_WAIT_L(0); PG8_BAR; PG8_MMA(1, 0, At, B0); PG8_MMA(1, 1, At, B1); PG8_BAR; PG8_SCHED;
;             PG8_LDB(B0, 1, 0); PG8_LDB(B1, 1, 1); PG8_SCHED; PG8_LDA(At, 1, 0); PG8_STAGE(PG8_SA(0, 1), a2 + hstepA, voffA);
;             PG8_WAIT_V(8); PG8_WAIT_L(0); PG8_BAR; PG8_MMA(0, 0, At, B0); PG8_MMA(0, 1, At, B1); PG8_BAR; PG8_SCHED;
;             PG8_LDA(At, 1, 1); PG8_STAGE(PG8_SB(1, 0), b3, voffB); PG8_STAGE(PG8_SB(1, 1), b3 + hstepB, voffB); PG8_STAGE(PG8_SA(1, 0), a3, voffA);
;             PG8_WAIT_V(8); PG8_WAIT_L(0); PG8_BAR; PG8_MMA(1, 0, At, B0); PG8_MMA(1, 1, At, B1); PG8_BAR; PG8_SCHED;
	s_add_i32 s42, s73, s17
	v_lshl_add_u64 v[208:209], v[208:209], 0, s[12:13]
	s_mov_b32 m0, s42
	ds_read_b128 v[160:163], v217 offset:49152
	ds_read_b128 v[164:167], v217 offset:50176
	ds_read_b128 v[168:171], v217 offset:51200
	ds_read_b128 v[172:175], v217 offset:52224
	ds_read_b128 v[176:179], v217 offset:53248
	ds_read_b128 v[180:183], v217 offset:54272
	ds_read_b128 v[200:203], v217 offset:55296
	ds_read_b128 v[204:207], v217 offset:56320
	global_load_lds_dwordx4 v[208:209], off
	s_add_i32 m0, s42, 0x2000
	s_add_u32 s40, s40, 0x80080
	v_lshl_add_u64 v[208:209], v[210:211], 0, s[12:13]
	s_addc_u32 s41, s41, 0
	s_add_i32 s42, s76, s17
	global_load_lds_dwordx4 v[208:209], off
	v_lshl_add_u64 v[208:209], s[40:41], 0, v[186:187]
	s_mov_b32 m0, s42
	s_nop 0
	global_load_lds_dwordx4 v[208:209], off
	v_lshl_add_u64 v[208:209], s[40:41], 0, v[190:191]
	s_add_i32 m0, s42, 0x2000
	s_nop 0
	global_load_lds_dwordx4 v[208:209], off
	v_lshl_add_u64 v[208:209], v[218:219], 0, s[12:13]
	s_mov_b32 m0, s55
	s_nop 0
	global_load_lds_dwordx4 v[208:209], off
	v_lshl_add_u64 v[208:209], v[220:221], 0, s[12:13]
	s_mov_b32 m0, s56
	s_nop 0
	global_load_lds_dwordx4 v[208:209], off
	s_add_u32 s38, s38, 0x100
	s_addc_u32 s39, s39, 0
	s_add_u32 s70, s70, 0x100
	s_addc_u32 s71, s71, 0
	s_waitcnt vmcnt(8)
	s_waitcnt lgkmcnt(0)
	s_barrier
	v_mfma_f32_16x16x32_bf16 v[60:63], v[96:99], v[160:163], v[60:63]
	v_mfma_f32_16x16x32_bf16 v[56:59], v[112:115], v[160:163], v[56:59]
	v_mfma_f32_16x16x32_bf16 v[44:47], v[96:99], v[168:171], v[44:47]
	v_mfma_f32_16x16x32_bf16 v[40:43], v[112:115], v[168:171], v[40:43]
	v_mfma_f32_16x16x32_bf16 v[28:31], v[96:99], v[176:179], v[28:31]
	v_mfma_f32_16x16x32_bf16 v[24:27], v[112:115], v[176:179], v[24:27]
	v_mfma_f32_16x16x32_bf16 v[12:15], v[96:99], v[200:203], v[12:15]
	v_mfma_f32_16x16x32_bf16 v[8:11], v[112:115], v[200:203], v[8:11]
	v_mfma_f32_16x16x32_bf16 v[60:63], v[100:103], v[164:167], v[60:63]
	v_mfma_f32_16x16x32_bf16 v[56:59], v[116:119], v[164:167], v[56:59]
	v_mfma_f32_16x16x32_bf16 v[44:47], v[100:103], v[172:175], v[44:47]
	v_mfma_f32_16x16x32_bf16 v[40:43], v[116:119], v[172:175], v[40:43]
	v_mfma_f32_16x16x32_bf16 v[28:31], v[100:103], v[180:183], v[28:31]
	v_mfma_f32_16x16x32_bf16 v[24:27], v[116:119], v[180:183], v[24:27]
	v_mfma_f32_16x16x32_bf16 v[12:15], v[100:103], v[204:207], v[12:15]
	v_mfma_f32_16x16x32_bf16 v[8:11], v[116:119], v[204:207], v[8:11]
	v_mfma_f32_16x16x32_bf16 v[52:55], v[144:147], v[160:163], v[52:55]
	v_mfma_f32_16x16x32_bf16 v[48:51], v[152:155], v[160:163], v[48:51]
	v_mfma_f32_16x16x32_bf16 v[36:39], v[144:147], v[168:171], v[36:39]
	v_mfma_f32_16x16x32_bf16 v[32:35], v[152:155], v[168:171], v[32:35]
	v_mfma_f32_16x16x32_bf16 v[20:23], v[144:147], v[176:179], v[20:23]
	v_mfma_f32_16x16x32_bf16 v[16:19], v[152:155], v[176:179], v[16:19]
	v_mfma_f32_16x16x32_bf16 v[4:7], v[144:147], v[200:203], v[4:7]
	v_mfma_f32_16x16x32_bf16 v[0:3], v[152:155], v[200:203], v[0:3]
	v_mfma_f32_16x16x32_bf16 v[52:55], v[148:151], v[164:167], v[52:55]
	v_mfma_f32_16x16x32_bf16 v[48:51], v[156:159], v[164:167], v[48:51]
	v_mfma_f32_16x16x32_bf16 v[36:39], v[148:151], v[172:175], v[36:39]
	v_mfma_f32_16x16x32_bf16 v[32:35], v[156:159], v[172:175], v[32:35]
	v_mfma_f32_16x16x32_bf16 v[20:23], v[148:151], v[180:183], v[20:23]
	v_mfma_f32_16x16x32_bf16 v[16:19], v[156:159], v[180:183], v[16:19]
	v_mfma_f32_16x16x32_bf16 v[4:7], v[148:151], v[204:207], v[4:7]
	v_mfma_f32_16x16x32_bf16 v[0:3], v[156:159], v[204:207], v[0:3]
	s_barrier
	s_cmp_ge_u32 s72, s29
	s_mov_b32 s42, s72
	s_cbranch_scc1 .Lkpeel_769_exit
.LBB0_769:
	ds_read_b128 v[96:99], v215
	ds_read_b128 v[100:103], v215 offset:1024
	ds_read_b128 v[112:115], v215 offset:2048
	ds_read_b128 v[116:119], v215 offset:3072
	ds_read_b128 v[144:147], v216
	ds_read_b128 v[148:151], v216 offset:1024
	ds_read_b128 v[152:155], v216 offset:2048
	ds_read_b128 v[156:159], v216 offset:3072
	s_add_i32 s72, s42, 2
	s_add_u32 s40, s38, 0xfff80080
	s_addc_u32 s41, s39, -1
	s_cmp_eq_u32 s33, s42
	s_cselect_b32 s42, s5, s40
	s_cselect_b32 s43, s1, s41
	s_cselect_b32 s41, s19, s71
	s_cselect_b32 s40, s21, s70
	v_lshl_add_u64 v[208:209], s[38:39], 0, v[194:195]
	s_add_i32 m0, s48, 0xc000
	ds_read_b128 v[160:163], v217
	ds_read_b128 v[164:167], v217 offset:1024
	ds_read_b128 v[168:171], v217 offset:2048
	ds_read_b128 v[172:175], v217 offset:3072
	ds_read_b128 v[176:179], v217 offset:4096
	ds_read_b128 v[180:183], v217 offset:5120
	ds_read_b128 v[200:203], v217 offset:6144
	ds_read_b128 v[204:207], v217 offset:7168
	global_load_lds_dwordx4 v[208:209], off
	v_lshl_add_u64 v[208:209], s[38:39], 0, v[196:197]
	s_add_i32 m0, s48, 0xe000
	s_nop 0
	global_load_lds_dwordx4 v[208:209], off
	s_waitcnt vmcnt(8)
	s_waitcnt lgkmcnt(0)
	s_barrier
; #define PG8_STAGE(bufoff, gbase, voff) do { _Pragma("unroll") for (int _i = 0; _i < 2; ++_i) \
;         __builtin_amdgcn_global_load_lds((const unsigned*)((const char*)(gbase) + (voff)[_i]), (LAS unsigned*)(lds + (bufoff) + ldsw + _i * 8192), 16, 0, 0); } while (0)
; #define PG8_LDA(dst, b, h) do { _Pragma("unroll") for (int m = 0; m < 4; ++m) _Pragma("unroll") for (int k = 0; k < 2; ++k) dst[m][k] = *(const LAS bf16x8*)(lds + PG8_SA(b, h) + aoff + m * 2048 + k * 1024); } while (0)
; #define PG8_LDB(dst, b, h) do { _Pragma("unroll") for (int n = 0; n < 2; ++n) _Pragma("unroll") for (int k = 0; k < 2; ++k) dst[n][k] = *(const LAS bf16x8*)(lds + PG8_SB(b, h) + boff + n * 2048 + k * 1024); } while (0)
; #define PG8_MMA(ai, bj, At, Bt) do { __builtin_amdgcn_s_setprio(1); _Pragma("unroll") for (int m = 0; m < 4; ++m) _Pragma("unroll") for (int n = 0; n < 2; ++n) _Pragma("unroll") for (int k = 0; k < 2; ++k) \
;         acc[ai][bj][m][n] = __builtin_amdgcn_mfma_f32_16x16x32_bf16(Bt[n][k], At[m][k], acc[ai][bj][m][n], 0, 0, 0); __builtin_amdgcn_s_setprio(0); } while (0)
; #define PG8_BAR __builtin_amdgcn_s_barrier()
; template <class Epi, class Sched = StaticOrder, class EpiSub = NoSub, bool FAST = false>
; __device__ __forceinline__ void gemm_phase(LAS unsigned char* lds, const Gemm g, const Sched& S, const Epi& E, const EpiSub& ES = EpiSub()) {
;     ...
;             PG8_LDB(B0, 0, 0); PG8_LDB(B1, 0, 1); PG8_SCHED; PG8_LDA(At, 0, 0); PG8_STAGE(PG8_SA(1, 1), a1 + hstepA, voffA);
;             PG8_WAIT_V(8); PG8_WAIT_L(0); PG8_BAR; PG8_MMA(0, 0, At, B0); PG8_MMA(0, 1, At, B1); PG8_BAR; PG8_SCHED;
;             PG8_LDA(At, 0, 1); PG8_STAGE(PG8_SB(0, 0), b2, voffB); PG8_STAGE(PG8_SB(0, 1), b2 + hstepB, voffB); PG8_STAGE(PG8_SA(0, 0), a2, voffA);
;             PG8_WAIT_V(8); PG8_WAIT_L(0); PG8_BAR; PG8_MMA(1, 0, At, B0); PG8_MMA(1, 1, At, B1); PG8_BAR; PG8_SCHED;
;             PG8_LDB(B0, 1, 0); PG8_LDB(B1, 1, 1); PG8_SCHED; PG8_LDA(At, 1, 0); PG8_STAGE(PG8_SA(0, 1), a2 + hstepA, voffA);
;             PG8_WAIT_V(8); PG8_WAIT_L(0); PG8_BAR; PG8_MMA(0, 0, At, B0); PG8_MMA(0, 1, At, B1); PG8_BAR; PG8_SCHED;
;             PG8_LDA(At, 1, 1); PG8_STAGE(PG8_SB(1, 0), b3, voffB); PG8_STAGE(PG8_SB(1, 1), b3 + hstepB, voffB); PG8_STAGE(PG8_SA(1, 0), a3, voffA);
;             PG8_WAIT_V(8); PG8_WAIT_L(0); PG8_BAR; PG8_MMA(1, 0, At, B0); PG8_MMA(1, 1, At, B1); PG8_BAR; PG8_SCHED;
	v_mfma_f32_16x16x32_bf16 v[140:143], v[96:99], v[160:163], v[140:143]
	v_mfma_f32_16x16x32_bf16 v[136:139], v[112:115], v[160:163], v[136:139]
	v_mfma_f32_16x16x32_bf16 v[124:127], v[96:99], v[168:171], v[124:127]
	v_mfma_f32_16x16x32_bf16 v[120:123], v[112:115], v[168:171], v[120:123]
	v_mfma_f32_16x16x32_bf16 v[92:95], v[96:99], v[176:179], v[92:95]
	v_mfma_f32_16x16x32_bf16 v[88:91], v[112:115], v[176:179], v[88:91]
	v_mfma_f32_16x16x32_bf16 v[76:79], v[96:99], v[200:203], v[76:79]
	v_mfma_f32_16x16x32_bf16 v[72:75], v[112:115], v[200:203], v[72:75]
	v_mfma_f32_16x16x32_bf16 v[140:143], v[100:103], v[164:167], v[140:143]
	v_mfma_f32_16x16x32_bf16 v[136:139], v[116:119], v[164:167], v[136:139]
	v_mfma_f32_16x16x32_bf16 v[124:127], v[100:103], v[172:175], v[124:127]
	v_mfma_f32_16x16x32_bf16 v[120:123], v[116:119], v[172:175], v[120:123]
	v_mfma_f32_16x16x32_bf16 v[92:95], v[100:103], v[180:183], v[92:95]
	v_mfma_f32_16x16x32_bf16 v[88:91], v[116:119], v[180:183], v[88:91]
	v_mfma_f32_16x16x32_bf16 v[76:79], v[100:103], v[204:207], v[76:79]
	v_mfma_f32_16x16x32_bf16 v[72:75], v[116:119], v[204:207], v[72:75]
	v_mfma_f32_16x16x32_bf16 v[132:135], v[144:147], v[160:163], v[132:135]
	v_mfma_f32_16x16x32_bf16 v[128:131], v[152:155], v[160:163], v[128:131]
	v_mfma_f32_16x16x32_bf16 v[108:111], v[144:147], v[168:171], v[108:111]
	v_mfma_f32_16x16x32_bf16 v[104:107], v[152:155], v[168:171], v[104:107]
	v_mfma_f32_16x16x32_bf16 v[84:87], v[144:147], v[176:179], v[84:87]
	v_mfma_f32_16x16x32_bf16 v[80:83], v[152:155], v[176:179], v[80:83]
	v_mfma_f32_16x16x32_bf16 v[68:71], v[144:147], v[200:203], v[68:71]
	v_mfma_f32_16x16x32_bf16 v[64:67], v[152:155], v[200:203], v[64:67]
	v_mfma_f32_16x16x32_bf16 v[132:135], v[148:151], v[164:167], v[132:135]
	v_mfma_f32_16x16x32_bf16 v[128:131], v[156:159], v[164:167], v[128:131]
	v_mfma_f32_16x16x32_bf16 v[108:111], v[148:151], v[172:175], v[108:111]
	v_mfma_f32_16x16x32_bf16 v[104:107], v[156:159], v[172:175], v[104:107]
	v_mfma_f32_16x16x32_bf16 v[84:87], v[148:151], v[180:183], v[84:87]
	v_mfma_f32_16x16x32_bf16 v[80:83], v[156:159], v[180:183], v[80:83]
	v_mfma_f32_16x16x32_bf16 v[68:71], v[148:151], v[204:207], v[68:71]
	v_mfma_f32_16x16x32_bf16 v[64:67], v[156:159], v[204:207], v[64:67]
	s_barrier
	s_add_i32 s73, s58, s17
	v_lshl_add_u64 v[208:209], s[40:41], 0, v[186:187]
	s_mov_b32 m0, s73
	ds_read_b128 v[160:163], v217 offset:16384
	ds_read_b128 v[164:167], v217 offset:17408
	ds_read_b128 v[168:171], v217 offset:18432
	ds_read_b128 v[172:175], v217 offset:19456
	ds_read_b128 v[176:179], v217 offset:20480
	ds_read_b128 v[180:183], v217 offset:21504
	ds_read_b128 v[200:203], v217 offset:22528
	ds_read_b128 v[204:207], v217 offset:23552
	global_load_lds_dwordx4 v[208:209], off
	s_add_i32 m0, s73, 0x2000
	s_add_u32 s76, s40, 0x80000
	v_lshl_add_u64 v[210:211], s[40:41], 0, v[190:191]
	s_addc_u32 s77, s41, 0
	s_add_i32 s73, s59, s17
	global_load_lds_dwordx4 v[210:211], off
	v_lshl_add_u64 v[218:219], s[76:77], 0, v[186:187]
	s_mov_b32 m0, s73
	v_lshl_add_u64 v[220:221], s[42:43], 0, v[188:189]
	global_load_lds_dwordx4 v[218:219], off
	v_lshl_add_u64 v[218:219], s[76:77], 0, v[190:191]
	s_add_i32 m0, s73, 0x2000
	s_nop 0
	global_load_lds_dwordx4 v[218:219], off
	v_lshl_add_u64 v[218:219], s[42:43], 0, v[184:185]
	s_mov_b32 m0, s48
	s_nop 0
	global_load_lds_dwordx4 v[218:219], off
	s_mov_b32 m0, s49
	s_nop 0
	global_load_lds_dwordx4 v[220:221], off
	s_waitcnt vmcnt(8)
	s_waitcnt lgkmcnt(0)
	s_barrier
	v_mfma_f32_16x16x32_bf16 v[60:63], v[96:99], v[160:163], v[60:63]
	v_mfma_f32_16x16x32_bf16 v[56:59], v[112:115], v[160:163], v[56:59]
	v_mfma_f32_16x16x32_bf16 v[44:47], v[96:99], v[168:171], v[44:47]
	v_mfma_f32_16x16x32_bf16 v[40:43], v[112:115], v[168:171], v[40:43]
	v_mfma_f32_16x16x32_bf16 v[28:31], v[96:99], v[176:179], v[28:31]
	v_mfma_f32_16x16x32_bf16 v[24:27], v[112:115], v[176:179], v[24:27]
	v_mfma_f32_16x16x32_bf16 v[12:15], v[96:99], v[200:203], v[12:15]
	v_mfma_f32_16x16x32_bf16 v[8:11], v[112:115], v[200:203], v[8:11]
	v_mfma_f32_16x16x32_bf16 v[60:63], v[100:103], v[164:167], v[60:63]
	v_mfma_f32_16x16x32_bf16 v[56:59], v[116:119], v[164:167], v[56:59]
	v_mfma_f32_16x16x32_bf16 v[44:47], v[100:103], v[172:175], v[44:47]
	v_mfma_f32_16x16x32_bf16 v[40:43], v[116:119], v[172:175], v[40:43]
	v_mfma_f32_16x16x32_bf16 v[28:31], v[100:103], v[180:183], v[28:31]
	v_mfma_f32_16x16x32_bf16 v[24:27], v[116:119], v[180:183], v[24:27]
	v_mfma_f32_16x16x32_bf16 v[12:15], v[100:103], v[204:207], v[12:15]
	v_mfma_f32_16x16x32_bf16 v[8:11], v[116:119], v[204:207], v[8:11]
	v_mfma_f32_16x16x32_bf16 v[52:55], v[144:147], v[160:163], v[52:55]
	v_mfma_f32_16x16x32_bf16 v[48:51], v[152:155], v[160:163], v[48:51]
	v_mfma_f32_16x16x32_bf16 v[36:39], v[144:147], v[168:171], v[36:39]
	v_mfma_f32_16x16x32_bf16 v[32:35], v[152:155], v[168:171], v[32:35]
	v_mfma_f32_16x16x32_bf16 v[20:23], v[144:147], v[176:179], v[20:23]
	v_mfma_f32_16x16x32_bf16 v[16:19], v[152:155], v[176:179], v[16:19]
	v_mfma_f32_16x16x32_bf16 v[4:7], v[144:147], v[200:203], v[4:7]
	v_mfma_f32_16x16x32_bf16 v[0:3], v[152:155], v[200:203], v[0:3]
	v_mfma_f32_16x16x32_bf16 v[52:55], v[148:151], v[164:167], v[52:55]
	v_mfma_f32_16x16x32_bf16 v[48:51], v[156:159], v[164:167], v[48:51]
	v_mfma_f32_16x16x32_bf16 v[36:39], v[148:151], v[172:175], v[36:39]
	v_mfma_f32_16x16x32_bf16 v[32:35], v[156:159], v[172:175], v[32:35]
	v_mfma_f32_16x16x32_bf16 v[20:23], v[148:151], v[180:183], v[20:23]
	v_mfma_f32_16x16x32_bf16 v[16:19], v[156:159], v[180:183], v[16:19]
	v_mfma_f32_16x16x32_bf16 v[4:7], v[148:151], v[204:207], v[4:7]
	v_mfma_f32_16x16x32_bf16 v[0:3], v[156:159], v[204:207], v[0:3]
	s_barrier
; #define PG8_STAGE(bufoff, gbase, voff) do { _Pragma("unroll") for (int _i = 0; _i < 2; ++_i) \
;         __builtin_amdgcn_global_load_lds((const unsigned*)((const char*)(gbase) + (voff)[_i]), (LAS unsigned*)(lds + (bufoff) + ldsw + _i * 8192), 16, 0, 0); } while (0)
; #define PG8_LDA(dst, b, h) do { _Pragma("unroll") for (int m = 0; m < 4; ++m) _Pragma("unroll") for (int k = 0; k < 2; ++k) dst[m][k] = *(const LAS bf16x8*)(lds + PG8_SA(b, h) + aoff + m * 2048 + k * 1024); } while (0)
; #define PG8_LDB(dst, b, h) do { _Pragma("unroll") for (int n = 0; n < 2; ++n) _Pragma("unroll") for (int k = 0; k < 2; ++k) dst[n][k] = *(const LAS bf16x8*)(lds + PG8_SB(b, h) + boff + n * 2048 + k * 1024); } while (0)
; #define PG8_MMA(ai, bj, At, Bt) do { __builtin_amdgcn_s_setprio(1); _Pragma("unroll") for (int m = 0; m < 4; ++m) _Pragma("unroll") for (int n = 0; n < 2; ++n) _Pragma("unroll") for (int k = 0; k < 2; ++k) \
;         acc[ai][bj][m][n] = __builtin_amdgcn_mfma_f32_16x16x32_bf16(Bt[n][k], At[m][k], acc[ai][bj][m][n], 0, 0, 0); __builtin_amdgcn_s_setprio(0); } while (0)
; #define PG8_BAR __builtin_amdgcn_s_barrier()
; template <class Epi, class Sched = StaticOrder, class EpiSub = NoSub, bool FAST = false>
; __device__ __forceinline__ void gemm_phase(LAS unsigned char* lds, const Gemm g, const Sched& S, const Epi& E, const EpiSub& ES = EpiSub()) {
;     ...
;             PG8_LDB(B0, 0, 0); PG8_LDB(B1, 0, 1); PG8_SCHED; PG8_LDA(At, 0, 0); PG8_STAGE(PG8_SA(1, 1), a1 + hstepA, voffA);
;             PG8_WAIT_V(8); PG8_WAIT_L(0); PG8_BAR; PG8_MMA(0, 0, At, B0); PG8_MMA(0, 1, At, B1); PG8_BAR; PG8_SCHED;
;             PG8_LDA(At, 0, 1); PG8_STAGE(PG8_SB(0, 0), b2, voffB); PG8_STAGE(PG8_SB(0, 1), b2 + hstepB, voffB); PG8_STAGE(PG8_SA(0, 0), a2, voffA);
;             PG8_WAIT_V(8); PG8_WAIT_L(0); PG8_BAR; PG8_MMA(1, 0, At, B0); PG8_MMA(1, 1, At, B1); PG8_BAR; PG8_SCHED;
;             PG8_LDB(B0, 1, 0); PG8_LDB(B1, 1, 1); PG8_SCHED; PG8_LDA(At, 1, 0); PG8_STAGE(PG8_SA(0, 1), a2 + hstepA, voffA);
;             PG8_WAIT_V(8); PG8_WAIT_L(0); PG8_BAR; PG8_MMA(0, 0, At, B0); PG8_MMA(0, 1, At, B1); PG8_BAR; PG8_SCHED;
;             PG8_LDA(At, 1, 1); PG8_STAGE(PG8_SB(1, 0), b3, voffB); PG8_STAGE(PG8_SB(1, 1), b3 + hstepB, voffB); PG8_STAGE(PG8_SA(1, 0), a3, voffA);
;             PG8_WAIT_V(8); PG8_WAIT_L(0); PG8_BAR; PG8_MMA(1, 0, At, B0); PG8_MMA(1, 1, At, B1); PG8_BAR; PG8_SCHED;
	s_add_i32 s73, 0, 0x18000
	s_add_i32 s76, 0, 0x1c000
	v_add_u32_e32 v116, s73, v212
	v_add_u32_e32 v156, s76, v212
	ds_read_b128 v[96:99], v116
	ds_read_b128 v[100:103], v116 offset:1024
	ds_read_b128 v[112:115], v116 offset:2048
	ds_read_b128 v[116:119], v116 offset:3072
	ds_read_b128 v[144:147], v156
	ds_read_b128 v[148:151], v156 offset:1024
	ds_read_b128 v[152:155], v156 offset:2048
	ds_read_b128 v[156:159], v156 offset:3072
	s_add_u32 s42, s42, 0x80000
	s_addc_u32 s43, s43, 0
	s_mov_b32 m0, s50
	v_lshl_add_u64 v[222:223], s[42:43], 0, v[184:185]
	ds_read_b128 v[160:163], v217 offset:32768
	ds_read_b128 v[164:167], v217 offset:33792
	ds_read_b128 v[168:171], v217 offset:34816
	ds_read_b128 v[172:175], v217 offset:35840
	ds_read_b128 v[176:179], v217 offset:36864
	ds_read_b128 v[180:183], v217 offset:37888
	ds_read_b128 v[200:203], v217 offset:38912
	ds_read_b128 v[204:207], v217 offset:39936
	global_load_lds_dwordx4 v[222:223], off
	v_lshl_add_u64 v[222:223], s[42:43], 0, v[188:189]
	s_mov_b32 m0, s51
	s_nop 0
	global_load_lds_dwordx4 v[222:223], off
	s_waitcnt vmcnt(8)
	s_waitcnt lgkmcnt(0)
	s_barrier
	v_mfma_f32_16x16x32_bf16 v[140:143], v[96:99], v[160:163], v[140:143]
	v_mfma_f32_16x16x32_bf16 v[136:139], v[112:115], v[160:163], v[136:139]
	v_mfma_f32_16x16x32_bf16 v[124:127], v[96:99], v[168:171], v[124:127]
	v_mfma_f32_16x16x32_bf16 v[120:123], v[112:115], v[168:171], v[120:123]
	v_mfma_f32_16x16x32_bf16 v[92:95], v[96:99], v[176:179], v[92:95]
	v_mfma_f32_16x16x32_bf16 v[88:91], v[112:115], v[176:179], v[88:91]
	v_mfma_f32_16x16x32_bf16 v[76:79], v[96:99], v[200:203], v[76:79]
	v_mfma_f32_16x16x32_bf16 v[72:75], v[112:115], v[200:203], v[72:75]
	v_mfma_f32_16x16x32_bf16 v[140:143], v[100:103], v[164:167], v[140:143]
	v_mfma_f32_16x16x32_bf16 v[136:139], v[116:119], v[164:167], v[136:139]
	v_mfma_f32_16x16x32_bf16 v[124:127], v[100:103], v[172:175], v[124:127]
	v_mfma_f32_16x16x32_bf16 v[120:123], v[116:119], v[172:175], v[120:123]
	v_mfma_f32_16x16x32_bf16 v[92:95], v[100:103], v[180:183], v[92:95]
	v_mfma_f32_16x16x32_bf16 v[88:91], v[116:119], v[180:183], v[88:91]
	v_mfma_f32_16x16x32_bf16 v[76:79], v[100:103], v[204:207], v[76:79]
	v_mfma_f32_16x16x32_bf16 v[72:75], v[116:119], v[204:207], v[72:75]
	v_mfma_f32_16x16x32_bf16 v[132:135], v[144:147], v[160:163], v[132:135]
	v_mfma_f32_16x16x32_bf16 v[128:131], v[152:155], v[160:163], v[128:131]
	v_mfma_f32_16x16x32_bf16 v[108:111], v[144:147], v[168:171], v[108:111]
	v_mfma_f32_16x16x32_bf16 v[104:107], v[152:155], v[168:171], v[104:107]
	v_mfma_f32_16x16x32_bf16 v[84:87], v[144:147], v[176:179], v[84:87]
	v_mfma_f32_16x16x32_bf16 v[80:83], v[152:155], v[176:179], v[80:83]
	v_mfma_f32_16x16x32_bf16 v[68:71], v[144:147], v[200:203], v[68:71]
	v_mfma_f32_16x16x32_bf16 v[64:67], v[152:155], v[200:203], v[64:67]
	v_mfma_f32_16x16x32_bf16 v[132:135], v[148:151], v[164:167], v[132:135]
	v_mfma_f32_16x16x32_bf16 v[128:131], v[156:159], v[164:167], v[128:131]
	v_mfma_f32_16x16x32_bf16 v[108:111], v[148:151], v[172:175], v[108:111]
	v_mfma_f32_16x16x32_bf16 v[104:107], v[156:159], v[172:175], v[104:107]
	v_mfma_f32_16x16x32_bf16 v[84:87], v[148:151], v[180:183], v[84:87]
	v_mfma_f32_16x16x32_bf16 v[80:83], v[156:159], v[180:183], v[80:83]
	v_mfma_f32_16x16x32_bf16 v[68:71], v[148:151], v[204:207], v[68:71]
	v_mfma_f32_16x16x32_bf16 v[64:67], v[156:159], v[204:207], v[64:67]
	s_barrier
	s_add_i32 s42, s73, s17
	v_lshl_add_u64 v[208:209], v[208:209], 0, s[12:13]
	s_mov_b32 m0, s42
	ds_read_b128 v[160:163], v217 offset:49152
	ds_read_b128 v[164:167], v217 offset:50176
	ds_read_b128 v[168:171], v217 offset:51200
	ds_read_b128 v[172:175], v217 offset:52224
	ds_read_b128 v[176:179], v217 offset:53248
	ds_read_b128 v[180:183], v217 offset:54272
	ds_read_b128 v[200:203], v217 offset:55296
	ds_read_b128 v[204:207], v217 offset:56320
	global_load_lds_dwordx4 v[208:209], off
	s_add_i32 m0, s42, 0x2000
	s_add_u32 s40, s40, 0x80080
	v_lshl_add_u64 v[208:209], v[210:211], 0, s[12:13]
	s_addc_u32 s41, s41, 0
	s_add_i32 s42, s76, s17
	global_load_lds_dwordx4 v[208:209], off
	v_lshl_add_u64 v[208:209], s[40:41], 0, v[186:187]
	s_mov_b32 m0, s42
	s_nop 0
	global_load_lds_dwordx4 v[208:209], off
	v_lshl_add_u64 v[208:209], s[40:41], 0, v[190:191]
	s_add_i32 m0, s42, 0x2000
	s_nop 0
	global_load_lds_dwordx4 v[208:209], off
	v_lshl_add_u64 v[208:209], v[218:219], 0, s[12:13]
	s_mov_b32 m0, s55
	s_nop 0
	global_load_lds_dwordx4 v[208:209], off
	v_lshl_add_u64 v[208:209], v[220:221], 0, s[12:13]
	s_mov_b32 m0, s56
	s_nop 0
	global_load_lds_dwordx4 v[208:209], off
	s_add_u32 s38, s38, 0x100
	s_addc_u32 s39, s39, 0
	s_add_u32 s70, s70, 0x100
	s_addc_u32 s71, s71, 0
	s_waitcnt vmcnt(8)
	s_waitcnt lgkmcnt(0)
	s_barrier
	v_mfma_f32_16x16x32_bf16 v[60:63], v[96:99], v[160:163], v[60:63]
	v_mfma_f32_16x16x32_bf16 v[56:59], v[112:115], v[160:163], v[56:59]
	v_mfma_f32_16x16x32_bf16 v[44:47], v[96:99], v[168:171], v[44:47]
	v_mfma_f32_16x16x32_bf16 v[40:43], v[112:115], v[168:171], v[40:43]
	v_mfma_f32_16x16x32_bf16 v[28:31], v[96:99], v[176:179], v[28:31]
	v_mfma_f32_16x16x32_bf16 v[24:27], v[112:115], v[176:179], v[24:27]
	v_mfma_f32_16x16x32_bf16 v[12:15], v[96:99], v[200:203], v[12:15]
	v_mfma_f32_16x16x32_bf16 v[8:11], v[112:115], v[200:203], v[8:11]
	v_mfma_f32_16x16x32_bf16 v[60:63], v[100:103], v[164:167], v[60:63]
	v_mfma_f32_16x16x32_bf16 v[56:59], v[116:119], v[164:167], v[56:59]
	v_mfma_f32_16x16x32_bf16 v[44:47], v[100:103], v[172:175], v[44:47]
	v_mfma_f32_16x16x32_bf16 v[40:43], v[116:119], v[172:175], v[40:43]
	v_mfma_f32_16x16x32_bf16 v[28:31], v[100:103], v[180:183], v[28:31]
	v_mfma_f32_16x16x32_bf16 v[24:27], v[116:119], v[180:183], v[24:27]
	v_mfma_f32_16x16x32_bf16 v[12:15], v[100:103], v[204:207], v[12:15]
	v_mfma_f32_16x16x32_bf16 v[8:11], v[116:119], v[204:207], v[8:11]
	v_mfma_f32_16x16x32_bf16 v[52:55], v[144:147], v[160:163], v[52:55]
	v_mfma_f32_16x16x32_bf16 v[48:51], v[152:155], v[160:163], v[48:51]
	v_mfma_f32_16x16x32_bf16 v[36:39], v[144:147], v[168:171], v[36:39]
	v_mfma_f32_16x16x32_bf16 v[32:35], v[152:155], v[168:171], v[32:35]
	v_mfma_f32_16x16x32_bf16 v[20:23], v[144:147], v[176:179], v[20:23]
	v_mfma_f32_16x16x32_bf16 v[16:19], v[152:155], v[176:179], v[16:19]
	v_mfma_f32_16x16x32_bf16 v[4:7], v[144:147], v[200:203], v[4:7]
	v_mfma_f32_16x16x32_bf16 v[0:3], v[152:155], v[200:203], v[0:3]
	v_mfma_f32_16x16x32_bf16 v[52:55], v[148:151], v[164:167], v[52:55]
	v_mfma_f32_16x16x32_bf16 v[48:51], v[156:159], v[164:167], v[48:51]
	v_mfma_f32_16x16x32_bf16 v[36:39], v[148:151], v[172:175], v[36:39]
	v_mfma_f32_16x16x32_bf16 v[32:35], v[156:159], v[172:175], v[32:35]
	v_mfma_f32_16x16x32_bf16 v[20:23], v[148:151], v[180:183], v[20:23]
	v_mfma_f32_16x16x32_bf16 v[16:19], v[156:159], v[180:183], v[16:19]
	v_mfma_f32_16x16x32_bf16 v[4:7], v[148:151], v[204:207], v[4:7]
	v_mfma_f32_16x16x32_bf16 v[0:3], v[156:159], v[204:207], v[0:3]
	s_barrier
	s_cmp_ge_u32 s72, s29
	s_mov_b32 s42, s72
	s_cbranch_scc0 .LBB0_769

; #define PG8_STAGE(bufoff, gbase, voff) do { _Pragma("unroll") for (int _i = 0; _i < 2; ++_i) \
;         __builtin_amdgcn_global_load_lds((const unsigned*)((const char*)(gbase) + (voff)[_i]), (LAS unsigned*)(lds + (bufoff) + ldsw + _i * 8192), 16, 0, 0); } while (0)
; #define PG8_LDA(dst, b, h) do { _Pragma("unroll") for (int m = 0; m < 4; ++m) _Pragma("unroll") for (int k = 0; k < 2; ++k) dst[m][k] = *(const LAS bf16x8*)(lds + PG8_SA(b, h) + aoff + m * 2048 + k * 1024); } while (0)
; #define PG8_LDB(dst, b, h) do { _Pragma("unroll") for (int n = 0; n < 2; ++n) _Pragma("unroll") for (int k = 0; k < 2; ++k) dst[n][k] = *(const LAS bf16x8*)(lds + PG8_SB(b, h) + boff + n * 2048 + k * 1024); } while (0)
; #define PG8_WAIT_V(n) asm volatile("s_waitcnt vmcnt(" #n ")" ::: "memory")
; #define PG8_BAR __builtin_amdgcn_s_barrier()
; template <class Epi, class Sched = StaticOrder, class EpiSub = NoSub, bool FAST = false>
; __device__ __forceinline__ void gemm_phase(LAS unsigned char* lds, const Gemm g, const Sched& S, const Epi& E, const EpiSub& ES = EpiSub()) {
;     ...
;         const bool has_next = S.next(ui + 1, nxt);
;         const size_t nko = (has_next && nxt.kb >= 0) ? nxt.kb * ksubB : 0;
;         const char* nA = has_next ? (const char*)g.A + (size_t)nxt.pm * tstepA + (size_t)nxt.pn * g.acs + nko : cA; const char* nB = has_next ? (const char*)g.Bt + (size_t)nxt.pn * tstepB + nko : cB;
;         const int nt = cur.kb < 0 ? ntMain : ntSub;
;         for (int t = 0; t < nt; t += 2) {
;             const bool last = (t == nt - 2);
;             const char* a1 = cA + (size_t)(t + 1) * kstep;
;             const char* a2 = last ? nA : cA + (size_t)(t + 2) * kstep; const char* b2 = last ? nB : cB + (size_t)(t + 2) * kstep;
;             const char* a3 = a2 + kstep; const char* b3 = b2 + kstep;
;             if constexpr (FAST && PG8_SP2) {
;             PG8_LDB(B0, 0, 0); PG8_LDB(B1, 0, 1); PG8_SCHED; PG8_LDA(At, 0, 0); PG8_STAGE(PG8_SA(1, 1), a1 + hstepA, voffA);
;             PG8_WAIT_V(8); PG8_WAIT_L(0); PG8_BAR; PG8_MMA(0, 0, At, B0); PG8_MMA(0, 1, At, B1); PG8_BAR; PG8_SCHED;
;             PG8_LDA(At, 0, 1); PG8_STAGE(PG8_SB(0, 0), b2, voffB); PG8_STAGE(PG8_SB(0, 1), b2 + hstepB, voffB); PG8_STAGE(PG8_SA(0, 0), a2, voffA);
;             PG8_WAIT_V(8); PG8_WAIT_L(0); PG8_BAR; PG8_MMA(1, 0, At, B0); PG8_MMA(1, 1, At, B1); PG8_BAR; PG8_SCHED;
.LBB0_984:
	s_ashr_i32 s15, s14, 31
	s_lshl_b64 s[16:17], s[14:15], 20
	v_readlane_b32 s18, v254, 36
	v_readlane_b32 s19, v254, 37
	s_add_u32 s16, s18, s16
	s_addc_u32 s17, s19, s17
	s_and_b64 s[18:19], s[0:1], exec
	s_cselect_b32 s15, s17, s23
	s_cselect_b32 s45, s16, s22
	s_ashr_i32 s13, s12, 31
	s_lshl_b64 s[18:19], s[12:13], 20
	s_add_u32 s18, s2, s18
	s_addc_u32 s19, s3, s19
	s_and_b64 s[26:27], s[0:1], exec
	s_cselect_b32 s13, s19, s25
	s_cselect_b32 s46, s18, s24
	s_add_u32 s22, s22, 0x80080
	s_addc_u32 s23, s23, 0
	s_add_u32 s47, s24, 0x100
	s_addc_u32 s48, s25, 0
	s_mov_b32 s49, -2
	ds_read_b128 v[150:153], v147
	ds_read_b128 v[154:157], v147 offset:1024
	ds_read_b128 v[158:161], v147 offset:2048
	ds_read_b128 v[162:165], v147 offset:3072
	ds_read_b128 v[166:169], v148
	ds_read_b128 v[170:173], v148 offset:1024
	ds_read_b128 v[174:177], v148 offset:2048
	ds_read_b128 v[178:181], v148 offset:3072
	s_add_u32 s24, s22, 0xfff80080
	s_addc_u32 s25, s23, -1
	s_cmp_eq_u32 s49, 28
	s_cselect_b32 s27, s15, s25
	s_cselect_b32 s26, s45, s24
	s_cselect_b32 s25, s13, s48
	s_cselect_b32 s24, s46, s47
	v_lshl_add_u64 v[190:191], s[22:23], 0, v[136:137]
	s_add_i32 m0, s21, 0xc000
	ds_read_b128 v[182:185], v149
	ds_read_b128 v[186:189], v149 offset:1024
	ds_read_b128 v[194:197], v149 offset:2048
	ds_read_b128 v[198:201], v149 offset:3072
	ds_read_b128 v[202:205], v149 offset:4096
	ds_read_b128 v[206:209], v149 offset:5120
	ds_read_b128 v[210:213], v149 offset:6144
	ds_read_b128 v[214:217], v149 offset:7168
	global_load_lds_dwordx4 v[190:191], off
	v_lshl_add_u64 v[190:191], s[22:23], 0, v[138:139]
	s_add_i32 m0, s21, 0xe000
	s_nop 0
	global_load_lds_dwordx4 v[190:191], off
	s_waitcnt vmcnt(8)
	s_waitcnt lgkmcnt(0)
	s_barrier
	v_mfma_f32_16x16x32_bf16 v[124:127], v[150:153], v[182:185], 0
	v_mfma_f32_16x16x32_bf16 v[116:119], v[158:161], v[182:185], 0
	v_mfma_f32_16x16x32_bf16 v[108:111], v[150:153], v[194:197], 0
	v_mfma_f32_16x16x32_bf16 v[100:103], v[158:161], v[194:197], 0
	v_mfma_f32_16x16x32_bf16 v[92:95], v[150:153], v[202:205], 0
	v_mfma_f32_16x16x32_bf16 v[84:87], v[158:161], v[202:205], 0
	v_mfma_f32_16x16x32_bf16 v[76:79], v[150:153], v[210:213], 0
	v_mfma_f32_16x16x32_bf16 v[68:71], v[158:161], v[210:213], 0
	v_mfma_f32_16x16x32_bf16 v[124:127], v[154:157], v[186:189], v[124:127]
	v_mfma_f32_16x16x32_bf16 v[116:119], v[162:165], v[186:189], v[116:119]
	v_mfma_f32_16x16x32_bf16 v[108:111], v[154:157], v[198:201], v[108:111]
	v_mfma_f32_16x16x32_bf16 v[100:103], v[162:165], v[198:201], v[100:103]
	v_mfma_f32_16x16x32_bf16 v[92:95], v[154:157], v[206:209], v[92:95]
	v_mfma_f32_16x16x32_bf16 v[84:87], v[162:165], v[206:209], v[84:87]
	v_mfma_f32_16x16x32_bf16 v[76:79], v[154:157], v[214:217], v[76:79]
	v_mfma_f32_16x16x32_bf16 v[68:71], v[162:165], v[214:217], v[68:71]
	v_mfma_f32_16x16x32_bf16 v[120:123], v[166:169], v[182:185], 0
	v_mfma_f32_16x16x32_bf16 v[112:115], v[174:177], v[182:185], 0
	v_mfma_f32_16x16x32_bf16 v[104:107], v[166:169], v[194:197], 0
	v_mfma_f32_16x16x32_bf16 v[96:99], v[174:177], v[194:197], 0
	v_mfma_f32_16x16x32_bf16 v[88:91], v[166:169], v[202:205], 0
	v_mfma_f32_16x16x32_bf16 v[80:83], v[174:177], v[202:205], 0
	v_mfma_f32_16x16x32_bf16 v[72:75], v[166:169], v[210:213], 0
	v_mfma_f32_16x16x32_bf16 v[64:67], v[174:177], v[210:213], 0
	v_mfma_f32_16x16x32_bf16 v[120:123], v[170:173], v[186:189], v[120:123]
	v_mfma_f32_16x16x32_bf16 v[112:115], v[178:181], v[186:189], v[112:115]
	v_mfma_f32_16x16x32_bf16 v[104:107], v[170:173], v[198:201], v[104:107]
	v_mfma_f32_16x16x32_bf16 v[96:99], v[178:181], v[198:201], v[96:99]
	v_mfma_f32_16x16x32_bf16 v[88:91], v[170:173], v[206:209], v[88:91]
	v_mfma_f32_16x16x32_bf16 v[80:83], v[178:181], v[206:209], v[80:83]
	v_mfma_f32_16x16x32_bf16 v[72:75], v[170:173], v[214:217], v[72:75]
	v_mfma_f32_16x16x32_bf16 v[64:67], v[178:181], v[214:217], v[64:67]
	s_barrier
	s_add_i32 s50, s42, s28
	v_lshl_add_u64 v[190:191], s[24:25], 0, v[130:131]
	s_mov_b32 m0, s50
	ds_read_b128 v[182:185], v149 offset:16384
	ds_read_b128 v[186:189], v149 offset:17408
	ds_read_b128 v[194:197], v149 offset:18432
	ds_read_b128 v[198:201], v149 offset:19456
	ds_read_b128 v[202:205], v149 offset:20480
	ds_read_b128 v[206:209], v149 offset:21504
	ds_read_b128 v[210:213], v149 offset:22528
	ds_read_b128 v[214:217], v149 offset:23552
	global_load_lds_dwordx4 v[190:191], off
	s_add_i32 m0, s50, 0x2000
	s_add_u32 s50, s24, 0x80000
	v_lshl_add_u64 v[218:219], s[24:25], 0, v[134:135]
	s_addc_u32 s51, s25, 0
	s_add_i32 s52, s43, s28
	global_load_lds_dwordx4 v[218:219], off
	v_lshl_add_u64 v[220:221], s[50:51], 0, v[130:131]
	s_mov_b32 m0, s52
	v_lshl_add_u64 v[222:223], s[26:27], 0, v[132:133]
	global_load_lds_dwordx4 v[220:221], off
	v_lshl_add_u64 v[220:221], s[50:51], 0, v[134:135]
	s_add_i32 m0, s52, 0x2000
	s_nop 0
	global_load_lds_dwordx4 v[220:221], off
	v_lshl_add_u64 v[220:221], s[26:27], 0, v[128:129]
	s_mov_b32 m0, s21
	s_nop 0
	global_load_lds_dwordx4 v[220:221], off
	s_mov_b32 m0, s31
	s_nop 0
	global_load_lds_dwordx4 v[222:223], off
	s_waitcnt vmcnt(8)
	s_waitcnt lgkmcnt(0)
	s_barrier
; #define PG8_STAGE(bufoff, gbase, voff) do { _Pragma("unroll") for (int _i = 0; _i < 2; ++_i) \
;         __builtin_amdgcn_global_load_lds((const unsigned*)((const char*)(gbase) + (voff)[_i]), (LAS unsigned*)(lds + (bufoff) + ldsw + _i * 8192), 16, 0, 0); } while (0)
; #define PG8_LDA(dst, b, h) do { _Pragma("unroll") for (int m = 0; m < 4; ++m) _Pragma("unroll") for (int k = 0; k < 2; ++k) dst[m][k] = *(const LAS bf16x8*)(lds + PG8_SA(b, h) + aoff + m * 2048 + k * 1024); } while (0)
; #define PG8_LDB(dst, b, h) do { _Pragma("unroll") for (int n = 0; n < 2; ++n) _Pragma("unroll") for (int k = 0; k < 2; ++k) dst[n][k] = *(const LAS bf16x8*)(lds + PG8_SB(b, h) + boff + n * 2048 + k * 1024); } while (0)
; #define PG8_MMA(ai, bj, At, Bt) do { __builtin_amdgcn_s_setprio(1); _Pragma("unroll") for (int m = 0; m < 4; ++m) _Pragma("unroll") for (int n = 0; n < 2; ++n) _Pragma("unroll") for (int k = 0; k < 2; ++k) \
;         acc[ai][bj][m][n] = __builtin_amdgcn_mfma_f32_16x16x32_bf16(Bt[n][k], At[m][k], acc[ai][bj][m][n], 0, 0, 0); __builtin_amdgcn_s_setprio(0); } while (0)
; #define PG8_WAIT_V(n) asm volatile("s_waitcnt vmcnt(" #n ")" ::: "memory")
; #define PG8_WAIT_L(n) asm volatile("s_waitcnt lgkmcnt(" #n ")" ::: "memory")
; #define PG8_BAR __builtin_amdgcn_s_barrier()
; #define PG8_SCHED __builtin_amdgcn_sched_barrier(0)
; template <class Epi, class Sched = StaticOrder, class EpiSub = NoSub, bool FAST = false>
; __device__ __forceinline__ void gemm_phase(LAS unsigned char* lds, const Gemm g, const Sched& S, const Epi& E, const EpiSub& ES = EpiSub()) {
;     ...
;             PG8_LDA(At, 0, 1); PG8_STAGE(PG8_SB(0, 0), b2, voffB); PG8_STAGE(PG8_SB(0, 1), b2 + hstepB, voffB); PG8_STAGE(PG8_SA(0, 0), a2, voffA);
;             PG8_WAIT_V(8); PG8_WAIT_L(0); PG8_BAR; PG8_MMA(1, 0, At, B0); PG8_MMA(1, 1, At, B1); PG8_BAR; PG8_SCHED;
;             PG8_LDB(B0, 1, 0); PG8_LDB(B1, 1, 1); PG8_SCHED; PG8_LDA(At, 1, 0); PG8_STAGE(PG8_SA(0, 1), a2 + hstepA, voffA);
;             PG8_WAIT_V(8); PG8_WAIT_L(0); PG8_BAR; PG8_MMA(0, 0, At, B0); PG8_MMA(0, 1, At, B1); PG8_BAR; PG8_SCHED;
;             PG8_LDA(At, 1, 1); PG8_STAGE(PG8_SB(1, 0), b3, voffB); PG8_STAGE(PG8_SB(1, 1), b3 + hstepB, voffB); PG8_STAGE(PG8_SA(1, 0), a3, voffA);
	v_mfma_f32_16x16x32_bf16 v[60:63], v[150:153], v[182:185], 0
	v_mfma_f32_16x16x32_bf16 v[52:55], v[158:161], v[182:185], 0
	v_mfma_f32_16x16x32_bf16 v[44:47], v[150:153], v[194:197], 0
	v_mfma_f32_16x16x32_bf16 v[36:39], v[158:161], v[194:197], 0
	v_mfma_f32_16x16x32_bf16 v[28:31], v[150:153], v[202:205], 0
	v_mfma_f32_16x16x32_bf16 v[20:23], v[158:161], v[202:205], 0
	v_mfma_f32_16x16x32_bf16 v[12:15], v[150:153], v[210:213], 0
	v_mfma_f32_16x16x32_bf16 v[4:7], v[158:161], v[210:213], 0
	v_mfma_f32_16x16x32_bf16 v[60:63], v[154:157], v[186:189], v[60:63]
	v_mfma_f32_16x16x32_bf16 v[52:55], v[162:165], v[186:189], v[52:55]
	v_mfma_f32_16x16x32_bf16 v[44:47], v[154:157], v[198:201], v[44:47]
	v_mfma_f32_16x16x32_bf16 v[36:39], v[162:165], v[198:201], v[36:39]
	v_mfma_f32_16x16x32_bf16 v[28:31], v[154:157], v[206:209], v[28:31]
	v_mfma_f32_16x16x32_bf16 v[20:23], v[162:165], v[206:209], v[20:23]
	v_mfma_f32_16x16x32_bf16 v[12:15], v[154:157], v[214:217], v[12:15]
	v_mfma_f32_16x16x32_bf16 v[4:7], v[162:165], v[214:217], v[4:7]
	v_mfma_f32_16x16x32_bf16 v[56:59], v[166:169], v[182:185], 0
	v_mfma_f32_16x16x32_bf16 v[48:51], v[174:177], v[182:185], 0
	v_mfma_f32_16x16x32_bf16 v[40:43], v[166:169], v[194:197], 0
	v_mfma_f32_16x16x32_bf16 v[32:35], v[174:177], v[194:197], 0
	v_mfma_f32_16x16x32_bf16 v[24:27], v[166:169], v[202:205], 0
	v_mfma_f32_16x16x32_bf16 v[16:19], v[174:177], v[202:205], 0
	v_mfma_f32_16x16x32_bf16 v[8:11], v[166:169], v[210:213], 0
	v_mfma_f32_16x16x32_bf16 v[0:3], v[174:177], v[210:213], 0
	v_mfma_f32_16x16x32_bf16 v[56:59], v[170:173], v[186:189], v[56:59]
	v_mfma_f32_16x16x32_bf16 v[48:51], v[178:181], v[186:189], v[48:51]
	v_mfma_f32_16x16x32_bf16 v[40:43], v[170:173], v[198:201], v[40:43]
	v_mfma_f32_16x16x32_bf16 v[32:35], v[178:181], v[198:201], v[32:35]
	v_mfma_f32_16x16x32_bf16 v[24:27], v[170:173], v[206:209], v[24:27]
	v_mfma_f32_16x16x32_bf16 v[16:19], v[178:181], v[206:209], v[16:19]
	v_mfma_f32_16x16x32_bf16 v[8:11], v[170:173], v[214:217], v[8:11]
	v_mfma_f32_16x16x32_bf16 v[0:3], v[178:181], v[214:217], v[0:3]
	s_barrier
	s_add_i32 s50, 0, 0x18000
	s_add_i32 s51, 0, 0x1c000
	v_add_u32_e32 v162, s50, v145
	v_add_u32_e32 v178, s51, v145
	ds_read_b128 v[150:153], v162
	ds_read_b128 v[154:157], v162 offset:1024
	ds_read_b128 v[158:161], v162 offset:2048
	ds_read_b128 v[162:165], v162 offset:3072
	ds_read_b128 v[166:169], v178
	ds_read_b128 v[170:173], v178 offset:1024
	ds_read_b128 v[174:177], v178 offset:2048
	ds_read_b128 v[178:181], v178 offset:3072
	s_add_u32 s26, s26, 0x80000
	s_addc_u32 s27, s27, 0
	s_mov_b32 m0, s36
	v_lshl_add_u64 v[224:225], s[26:27], 0, v[128:129]
	ds_read_b128 v[182:185], v149 offset:32768
	ds_read_b128 v[186:189], v149 offset:33792
	ds_read_b128 v[194:197], v149 offset:34816
	ds_read_b128 v[198:201], v149 offset:35840
	ds_read_b128 v[202:205], v149 offset:36864
	ds_read_b128 v[206:209], v149 offset:37888
	ds_read_b128 v[210:213], v149 offset:38912
	ds_read_b128 v[214:217], v149 offset:39936
	global_load_lds_dwordx4 v[224:225], off
	v_lshl_add_u64 v[224:225], s[26:27], 0, v[132:133]
	s_mov_b32 m0, s37
	s_nop 0
	global_load_lds_dwordx4 v[224:225], off
	s_waitcnt vmcnt(8)
	s_waitcnt lgkmcnt(0)
	s_barrier
	v_mfma_f32_16x16x32_bf16 v[124:127], v[150:153], v[182:185], v[124:127]
	v_mfma_f32_16x16x32_bf16 v[116:119], v[158:161], v[182:185], v[116:119]
	v_mfma_f32_16x16x32_bf16 v[108:111], v[150:153], v[194:197], v[108:111]
	v_mfma_f32_16x16x32_bf16 v[100:103], v[158:161], v[194:197], v[100:103]
	v_mfma_f32_16x16x32_bf16 v[92:95], v[150:153], v[202:205], v[92:95]
	v_mfma_f32_16x16x32_bf16 v[84:87], v[158:161], v[202:205], v[84:87]
	v_mfma_f32_16x16x32_bf16 v[76:79], v[150:153], v[210:213], v[76:79]
	v_mfma_f32_16x16x32_bf16 v[68:71], v[158:161], v[210:213], v[68:71]
	v_mfma_f32_16x16x32_bf16 v[124:127], v[154:157], v[186:189], v[124:127]
	v_mfma_f32_16x16x32_bf16 v[116:119], v[162:165], v[186:189], v[116:119]
	v_mfma_f32_16x16x32_bf16 v[108:111], v[154:157], v[198:201], v[108:111]
	v_mfma_f32_16x16x32_bf16 v[100:103], v[162:165], v[198:201], v[100:103]
	v_mfma_f32_16x16x32_bf16 v[92:95], v[154:157], v[206:209], v[92:95]
	v_mfma_f32_16x16x32_bf16 v[84:87], v[162:165], v[206:209], v[84:87]
	v_mfma_f32_16x16x32_bf16 v[76:79], v[154:157], v[214:217], v[76:79]
	v_mfma_f32_16x16x32_bf16 v[68:71], v[162:165], v[214:217], v[68:71]
	v_mfma_f32_16x16x32_bf16 v[120:123], v[166:169], v[182:185], v[120:123]
	v_mfma_f32_16x16x32_bf16 v[112:115], v[174:177], v[182:185], v[112:115]
	v_mfma_f32_16x16x32_bf16 v[104:107], v[166:169], v[194:197], v[104:107]
	v_mfma_f32_16x16x32_bf16 v[96:99], v[174:177], v[194:197], v[96:99]
	v_mfma_f32_16x16x32_bf16 v[88:91], v[166:169], v[202:205], v[88:91]
	v_mfma_f32_16x16x32_bf16 v[80:83], v[174:177], v[202:205], v[80:83]
	v_mfma_f32_16x16x32_bf16 v[72:75], v[166:169], v[210:213], v[72:75]
	v_mfma_f32_16x16x32_bf16 v[64:67], v[174:177], v[210:213], v[64:67]
	v_mfma_f32_16x16x32_bf16 v[120:123], v[170:173], v[186:189], v[120:123]
	v_mfma_f32_16x16x32_bf16 v[112:115], v[178:181], v[186:189], v[112:115]
	v_mfma_f32_16x16x32_bf16 v[104:107], v[170:173], v[198:201], v[104:107]
	v_mfma_f32_16x16x32_bf16 v[96:99], v[178:181], v[198:201], v[96:99]
	v_mfma_f32_16x16x32_bf16 v[88:91], v[170:173], v[206:209], v[88:91]
	v_mfma_f32_16x16x32_bf16 v[80:83], v[178:181], v[206:209], v[80:83]
	v_mfma_f32_16x16x32_bf16 v[72:75], v[170:173], v[214:217], v[72:75]
	v_mfma_f32_16x16x32_bf16 v[64:67], v[178:181], v[214:217], v[64:67]
	s_barrier
; #define PG8_STAGE(bufoff, gbase, voff) do { _Pragma("unroll") for (int _i = 0; _i < 2; ++_i) \
;         __builtin_amdgcn_global_load_lds((const unsigned*)((const char*)(gbase) + (voff)[_i]), (LAS unsigned*)(lds + (bufoff) + ldsw + _i * 8192), 16, 0, 0); } while (0)
; #define PG8_LDA(dst, b, h) do { _Pragma("unroll") for (int m = 0; m < 4; ++m) _Pragma("unroll") for (int k = 0; k < 2; ++k) dst[m][k] = *(const LAS bf16x8*)(lds + PG8_SA(b, h) + aoff + m * 2048 + k * 1024); } while (0)
; #define PG8_LDB(dst, b, h) do { _Pragma("unroll") for (int n = 0; n < 2; ++n) _Pragma("unroll") for (int k = 0; k < 2; ++k) dst[n][k] = *(const LAS bf16x8*)(lds + PG8_SB(b, h) + boff + n * 2048 + k * 1024); } while (0)
; template <class Epi, class Sched = StaticOrder, class EpiSub = NoSub, bool FAST = false>
; __device__ __forceinline__ void gemm_phase(LAS unsigned char* lds, const Gemm g, const Sched& S, const Epi& E, const EpiSub& ES = EpiSub()) {
;     ...
;         for (int t = 0; t < nt; t += 2) {
;             const bool last = (t == nt - 2);
;             const char* a1 = cA + (size_t)(t + 1) * kstep;
;             const char* a2 = last ? nA : cA + (size_t)(t + 2) * kstep; const char* b2 = last ? nB : cB + (size_t)(t + 2) * kstep;
;             const char* a3 = a2 + kstep; const char* b3 = b2 + kstep;
;             if constexpr (FAST && PG8_SP2) {
;             PG8_LDB(B0, 0, 0); PG8_LDB(B1, 0, 1); PG8_SCHED; PG8_LDA(At, 0, 0); PG8_STAGE(PG8_SA(1, 1), a1 + hstepA, voffA);
;             PG8_WAIT_V(8); PG8_WAIT_L(0); PG8_BAR; PG8_MMA(0, 0, At, B0); PG8_MMA(0, 1, At, B1); PG8_BAR; PG8_SCHED;
;             PG8_LDA(At, 0, 1); PG8_STAGE(PG8_SB(0, 0), b2, voffB); PG8_STAGE(PG8_SB(0, 1), b2 + hstepB, voffB); PG8_STAGE(PG8_SA(0, 0), a2, voffA);
;             PG8_WAIT_V(8); PG8_WAIT_L(0); PG8_BAR; PG8_MMA(1, 0, At, B0); PG8_MMA(1, 1, At, B1); PG8_BAR; PG8_SCHED;
;             PG8_LDB(B0, 1, 0); PG8_LDB(B1, 1, 1); PG8_SCHED; PG8_LDA(At, 1, 0); PG8_STAGE(PG8_SA(0, 1), a2 + hstepA, voffA);
;             PG8_WAIT_V(8); PG8_WAIT_L(0); PG8_BAR; PG8_MMA(0, 0, At, B0); PG8_MMA(0, 1, At, B1); PG8_BAR; PG8_SCHED;
;             PG8_LDA(At, 1, 1); PG8_STAGE(PG8_SB(1, 0), b3, voffB); PG8_STAGE(PG8_SB(1, 1), b3 + hstepB, voffB); PG8_STAGE(PG8_SA(1, 0), a3, voffA);
;             PG8_WAIT_V(8); PG8_WAIT_L(0); PG8_BAR; PG8_MMA(1, 0, At, B0); PG8_MMA(1, 1, At, B1); PG8_BAR; PG8_SCHED;
	s_add_i32 s26, s50, s28
	v_lshl_add_u64 v[190:191], v[190:191], 0, s[8:9]
	s_mov_b32 m0, s26
	ds_read_b128 v[182:185], v149 offset:49152
	ds_read_b128 v[186:189], v149 offset:50176
	ds_read_b128 v[194:197], v149 offset:51200
	ds_read_b128 v[198:201], v149 offset:52224
	ds_read_b128 v[202:205], v149 offset:53248
	ds_read_b128 v[206:209], v149 offset:54272
	ds_read_b128 v[210:213], v149 offset:55296
	ds_read_b128 v[214:217], v149 offset:56320
	global_load_lds_dwordx4 v[190:191], off
	s_add_i32 m0, s26, 0x2000
	s_add_u32 s24, s24, 0x80080
	v_lshl_add_u64 v[190:191], v[218:219], 0, s[8:9]
	s_addc_u32 s25, s25, 0
	s_add_i32 s26, s51, s28
	global_load_lds_dwordx4 v[190:191], off
	v_lshl_add_u64 v[190:191], s[24:25], 0, v[130:131]
	s_mov_b32 m0, s26
	s_nop 0
	global_load_lds_dwordx4 v[190:191], off
	v_lshl_add_u64 v[190:191], s[24:25], 0, v[134:135]
	s_add_i32 m0, s26, 0x2000
	s_nop 0
	global_load_lds_dwordx4 v[190:191], off
	v_lshl_add_u64 v[190:191], v[220:221], 0, s[8:9]
	s_mov_b32 m0, s40
	s_nop 0
	global_load_lds_dwordx4 v[190:191], off
	v_lshl_add_u64 v[190:191], v[222:223], 0, s[8:9]
	s_mov_b32 m0, s41
	s_nop 0
	global_load_lds_dwordx4 v[190:191], off
	s_add_i32 s49, s49, 2
	s_add_u32 s22, s22, 0x100
	s_addc_u32 s23, s23, 0
	s_add_u32 s47, s47, 0x100
	s_addc_u32 s48, s48, 0
	s_waitcnt vmcnt(8)
	s_waitcnt lgkmcnt(0)
	s_barrier
	v_mfma_f32_16x16x32_bf16 v[60:63], v[150:153], v[182:185], v[60:63]
	v_mfma_f32_16x16x32_bf16 v[52:55], v[158:161], v[182:185], v[52:55]
	v_mfma_f32_16x16x32_bf16 v[44:47], v[150:153], v[194:197], v[44:47]
	v_mfma_f32_16x16x32_bf16 v[36:39], v[158:161], v[194:197], v[36:39]
	v_mfma_f32_16x16x32_bf16 v[28:31], v[150:153], v[202:205], v[28:31]
	v_mfma_f32_16x16x32_bf16 v[20:23], v[158:161], v[202:205], v[20:23]
	v_mfma_f32_16x16x32_bf16 v[12:15], v[150:153], v[210:213], v[12:15]
	v_mfma_f32_16x16x32_bf16 v[4:7], v[158:161], v[210:213], v[4:7]
	v_mfma_f32_16x16x32_bf16 v[60:63], v[154:157], v[186:189], v[60:63]
	v_mfma_f32_16x16x32_bf16 v[52:55], v[162:165], v[186:189], v[52:55]
	v_mfma_f32_16x16x32_bf16 v[44:47], v[154:157], v[198:201], v[44:47]
	v_mfma_f32_16x16x32_bf16 v[36:39], v[162:165], v[198:201], v[36:39]
	v_mfma_f32_16x16x32_bf16 v[28:31], v[154:157], v[206:209], v[28:31]
	v_mfma_f32_16x16x32_bf16 v[20:23], v[162:165], v[206:209], v[20:23]
	v_mfma_f32_16x16x32_bf16 v[12:15], v[154:157], v[214:217], v[12:15]
	v_mfma_f32_16x16x32_bf16 v[4:7], v[162:165], v[214:217], v[4:7]
	v_mfma_f32_16x16x32_bf16 v[56:59], v[166:169], v[182:185], v[56:59]
	v_mfma_f32_16x16x32_bf16 v[48:51], v[174:177], v[182:185], v[48:51]
	v_mfma_f32_16x16x32_bf16 v[40:43], v[166:169], v[194:197], v[40:43]
	v_mfma_f32_16x16x32_bf16 v[32:35], v[174:177], v[194:197], v[32:35]
	v_mfma_f32_16x16x32_bf16 v[24:27], v[166:169], v[202:205], v[24:27]
	v_mfma_f32_16x16x32_bf16 v[16:19], v[174:177], v[202:205], v[16:19]
	v_mfma_f32_16x16x32_bf16 v[8:11], v[166:169], v[210:213], v[8:11]
	v_mfma_f32_16x16x32_bf16 v[0:3], v[174:177], v[210:213], v[0:3]
	v_mfma_f32_16x16x32_bf16 v[56:59], v[170:173], v[186:189], v[56:59]
	v_mfma_f32_16x16x32_bf16 v[48:51], v[178:181], v[186:189], v[48:51]
	v_mfma_f32_16x16x32_bf16 v[40:43], v[170:173], v[198:201], v[40:43]
	v_mfma_f32_16x16x32_bf16 v[32:35], v[178:181], v[198:201], v[32:35]
	v_mfma_f32_16x16x32_bf16 v[24:27], v[170:173], v[206:209], v[24:27]
	v_mfma_f32_16x16x32_bf16 v[16:19], v[178:181], v[206:209], v[16:19]
	v_mfma_f32_16x16x32_bf16 v[8:11], v[170:173], v[214:217], v[8:11]
	v_mfma_f32_16x16x32_bf16 v[0:3], v[178:181], v[214:217], v[0:3]
	s_barrier
	s_cmp_gt_u32 s49, 29
	s_cbranch_scc1 .Lkpeel_985_exit
.LBB0_985:
	ds_read_b128 v[150:153], v147
	ds_read_b128 v[154:157], v147 offset:1024
	ds_read_b128 v[158:161], v147 offset:2048
	ds_read_b128 v[162:165], v147 offset:3072
	ds_read_b128 v[166:169], v148
	ds_read_b128 v[170:173], v148 offset:1024
	ds_read_b128 v[174:177], v148 offset:2048
	ds_read_b128 v[178:181], v148 offset:3072
	s_add_u32 s24, s22, 0xfff80080
	s_addc_u32 s25, s23, -1
	s_cmp_eq_u32 s49, 28
	s_cselect_b32 s27, s15, s25
	s_cselect_b32 s26, s45, s24
	s_cselect_b32 s25, s13, s48
	s_cselect_b32 s24, s46, s47
	v_lshl_add_u64 v[190:191], s[22:23], 0, v[136:137]
	s_add_i32 m0, s21, 0xc000
	ds_read_b128 v[182:185], v149
	ds_read_b128 v[186:189], v149 offset:1024
	ds_read_b128 v[194:197], v149 offset:2048
	ds_read_b128 v[198:201], v149 offset:3072
	ds_read_b128 v[202:205], v149 offset:4096
	ds_read_b128 v[206:209], v149 offset:5120
	ds_read_b128 v[210:213], v149 offset:6144
	ds_read_b128 v[214:217], v149 offset:7168
	global_load_lds_dwordx4 v[190:191], off
	v_lshl_add_u64 v[190:191], s[22:23], 0, v[138:139]
	s_add_i32 m0, s21, 0xe000
	s_nop 0
	global_load_lds_dwordx4 v[190:191], off
	s_waitcnt vmcnt(8)
	s_waitcnt lgkmcnt(0)
	s_barrier
; #define PG8_STAGE(bufoff, gbase, voff) do { _Pragma("unroll") for (int _i = 0; _i < 2; ++_i) \
;         __builtin_amdgcn_global_load_lds((const unsigned*)((const char*)(gbase) + (voff)[_i]), (LAS unsigned*)(lds + (bufoff) + ldsw + _i * 8192), 16, 0, 0); } while (0)
; #define PG8_LDA(dst, b, h) do { _Pragma("unroll") for (int m = 0; m < 4; ++m) _Pragma("unroll") for (int k = 0; k < 2; ++k) dst[m][k] = *(const LAS bf16x8*)(lds + PG8_SA(b, h) + aoff + m * 2048 + k * 1024); } while (0)
; #define PG8_LDB(dst, b, h) do { _Pragma("unroll") for (int n = 0; n < 2; ++n) _Pragma("unroll") for (int k = 0; k < 2; ++k) dst[n][k] = *(const LAS bf16x8*)(lds + PG8_SB(b, h) + boff + n * 2048 + k * 1024); } while (0)
; #define PG8_MMA(ai, bj, At, Bt) do { __builtin_amdgcn_s_setprio(1); _Pragma("unroll") for (int m = 0; m < 4; ++m) _Pragma("unroll") for (int n = 0; n < 2; ++n) _Pragma("unroll") for (int k = 0; k < 2; ++k) \
;         acc[ai][bj][m][n] = __builtin_amdgcn_mfma_f32_16x16x32_bf16(Bt[n][k], At[m][k], acc[ai][bj][m][n], 0, 0, 0); __builtin_amdgcn_s_setprio(0); } while (0)
; #define PG8_WAIT_V(n) asm volatile("s_waitcnt vmcnt(" #n ")" ::: "memory")
; #define PG8_WAIT_L(n) asm volatile("s_waitcnt lgkmcnt(" #n ")" ::: "memory")
; #define PG8_BAR __builtin_amdgcn_s_barrier()
; #define PG8_SCHED __builtin_amdgcn_sched_barrier(0)
; template <class Epi, class Sched = StaticOrder, class EpiSub = NoSub, bool FAST = false>
; __device__ __forceinline__ void gemm_phase(LAS unsigned char* lds, const Gemm g, const Sched& S, const Epi& E, const EpiSub& ES = EpiSub()) {
;     ...
;             PG8_WAIT_V(8); PG8_WAIT_L(0); PG8_BAR; PG8_MMA(0, 0, At, B0); PG8_MMA(0, 1, At, B1); PG8_BAR; PG8_SCHED;
;             PG8_LDA(At, 0, 1); PG8_STAGE(PG8_SB(0, 0), b2, voffB); PG8_STAGE(PG8_SB(0, 1), b2 + hstepB, voffB); PG8_STAGE(PG8_SA(0, 0), a2, voffA);
;             PG8_WAIT_V(8); PG8_WAIT_L(0); PG8_BAR; PG8_MMA(1, 0, At, B0); PG8_MMA(1, 1, At, B1); PG8_BAR; PG8_SCHED;
;             PG8_LDB(B0, 1, 0); PG8_LDB(B1, 1, 1); PG8_SCHED; PG8_LDA(At, 1, 0); PG8_STAGE(PG8_SA(0, 1), a2 + hstepA, voffA);
;             PG8_WAIT_V(8); PG8_WAIT_L(0); PG8_BAR; PG8_MMA(0, 0, At, B0); PG8_MMA(0, 1, At, B1); PG8_BAR; PG8_SCHED;
;             PG8_LDA(At, 1, 1); PG8_STAGE(PG8_SB(1, 0), b3, voffB); PG8_STAGE(PG8_SB(1, 1), b3 + hstepB, voffB); PG8_STAGE(PG8_SA(1, 0), a3, voffA);
	v_mfma_f32_16x16x32_bf16 v[124:127], v[150:153], v[182:185], v[124:127]
	v_mfma_f32_16x16x32_bf16 v[116:119], v[158:161], v[182:185], v[116:119]
	v_mfma_f32_16x16x32_bf16 v[108:111], v[150:153], v[194:197], v[108:111]
	v_mfma_f32_16x16x32_bf16 v[100:103], v[158:161], v[194:197], v[100:103]
	v_mfma_f32_16x16x32_bf16 v[92:95], v[150:153], v[202:205], v[92:95]
	v_mfma_f32_16x16x32_bf16 v[84:87], v[158:161], v[202:205], v[84:87]
	v_mfma_f32_16x16x32_bf16 v[76:79], v[150:153], v[210:213], v[76:79]
	v_mfma_f32_16x16x32_bf16 v[68:71], v[158:161], v[210:213], v[68:71]
	v_mfma_f32_16x16x32_bf16 v[124:127], v[154:157], v[186:189], v[124:127]
	v_mfma_f32_16x16x32_bf16 v[116:119], v[162:165], v[186:189], v[116:119]
	v_mfma_f32_16x16x32_bf16 v[108:111], v[154:157], v[198:201], v[108:111]
	v_mfma_f32_16x16x32_bf16 v[100:103], v[162:165], v[198:201], v[100:103]
	v_mfma_f32_16x16x32_bf16 v[92:95], v[154:157], v[206:209], v[92:95]
	v_mfma_f32_16x16x32_bf16 v[84:87], v[162:165], v[206:209], v[84:87]
	v_mfma_f32_16x16x32_bf16 v[76:79], v[154:157], v[214:217], v[76:79]
	v_mfma_f32_16x16x32_bf16 v[68:71], v[162:165], v[214:217], v[68:71]
	v_mfma_f32_16x16x32_bf16 v[120:123], v[166:169], v[182:185], v[120:123]
	v_mfma_f32_16x16x32_bf16 v[112:115], v[174:177], v[182:185], v[112:115]
	v_mfma_f32_16x16x32_bf16 v[104:107], v[166:169], v[194:197], v[104:107]
	v_mfma_f32_16x16x32_bf16 v[96:99], v[174:177], v[194:197], v[96:99]
	v_mfma_f32_16x16x32_bf16 v[88:91], v[166:169], v[202:205], v[88:91]
	v_mfma_f32_16x16x32_bf16 v[80:83], v[174:177], v[202:205], v[80:83]
	v_mfma_f32_16x16x32_bf16 v[72:75], v[166:169], v[210:213], v[72:75]
	v_mfma_f32_16x16x32_bf16 v[64:67], v[174:177], v[210:213], v[64:67]
	v_mfma_f32_16x16x32_bf16 v[120:123], v[170:173], v[186:189], v[120:123]
	v_mfma_f32_16x16x32_bf16 v[112:115], v[178:181], v[186:189], v[112:115]
	v_mfma_f32_16x16x32_bf16 v[104:107], v[170:173], v[198:201], v[104:107]
	v_mfma_f32_16x16x32_bf16 v[96:99], v[178:181], v[198:201], v[96:99]
	v_mfma_f32_16x16x32_bf16 v[88:91], v[170:173], v[206:209], v[88:91]
	v_mfma_f32_16x16x32_bf16 v[80:83], v[178:181], v[206:209], v[80:83]
	v_mfma_f32_16x16x32_bf16 v[72:75], v[170:173], v[214:217], v[72:75]
	v_mfma_f32_16x16x32_bf16 v[64:67], v[178:181], v[214:217], v[64:67]
	s_barrier
	s_add_i32 s50, s42, s28
	v_lshl_add_u64 v[190:191], s[24:25], 0, v[130:131]
	s_mov_b32 m0, s50
	ds_read_b128 v[182:185], v149 offset:16384
	ds_read_b128 v[186:189], v149 offset:17408
	ds_read_b128 v[194:197], v149 offset:18432
	ds_read_b128 v[198:201], v149 offset:19456
	ds_read_b128 v[202:205], v149 offset:20480
	ds_read_b128 v[206:209], v149 offset:21504
	ds_read_b128 v[210:213], v149 offset:22528
	ds_read_b128 v[214:217], v149 offset:23552
	global_load_lds_dwordx4 v[190:191], off
	s_add_i32 m0, s50, 0x2000
	s_add_u32 s50, s24, 0x80000
	v_lshl_add_u64 v[218:219], s[24:25], 0, v[134:135]
	s_addc_u32 s51, s25, 0
	s_add_i32 s52, s43, s28
	global_load_lds_dwordx4 v[218:219], off
	v_lshl_add_u64 v[220:221], s[50:51], 0, v[130:131]
	s_mov_b32 m0, s52
	v_lshl_add_u64 v[222:223], s[26:27], 0, v[132:133]
	global_load_lds_dwordx4 v[220:221], off
	v_lshl_add_u64 v[220:221], s[50:51], 0, v[134:135]
	s_add_i32 m0, s52, 0x2000
	s_nop 0
	global_load_lds_dwordx4 v[220:221], off
	v_lshl_add_u64 v[220:221], s[26:27], 0, v[128:129]
	s_mov_b32 m0, s21
	s_nop 0
	global_load_lds_dwordx4 v[220:221], off
	s_mov_b32 m0, s31
	s_nop 0
	global_load_lds_dwordx4 v[222:223], off
	s_waitcnt vmcnt(8)
	s_waitcnt lgkmcnt(0)
	s_barrier
	v_mfma_f32_16x16x32_bf16 v[60:63], v[150:153], v[182:185], v[60:63]
	v_mfma_f32_16x16x32_bf16 v[52:55], v[158:161], v[182:185], v[52:55]
	v_mfma_f32_16x16x32_bf16 v[44:47], v[150:153], v[194:197], v[44:47]
	v_mfma_f32_16x16x32_bf16 v[36:39], v[158:161], v[194:197], v[36:39]
	v_mfma_f32_16x16x32_bf16 v[28:31], v[150:153], v[202:205], v[28:31]
	v_mfma_f32_16x16x32_bf16 v[20:23], v[158:161], v[202:205], v[20:23]
	v_mfma_f32_16x16x32_bf16 v[12:15], v[150:153], v[210:213], v[12:15]
	v_mfma_f32_16x16x32_bf16 v[4:7], v[158:161], v[210:213], v[4:7]
	v_mfma_f32_16x16x32_bf16 v[60:63], v[154:157], v[186:189], v[60:63]
	v_mfma_f32_16x16x32_bf16 v[52:55], v[162:165], v[186:189], v[52:55]
	v_mfma_f32_16x16x32_bf16 v[44:47], v[154:157], v[198:201], v[44:47]
	v_mfma_f32_16x16x32_bf16 v[36:39], v[162:165], v[198:201], v[36:39]
	v_mfma_f32_16x16x32_bf16 v[28:31], v[154:157], v[206:209], v[28:31]
	v_mfma_f32_16x16x32_bf16 v[20:23], v[162:165], v[206:209], v[20:23]
	v_mfma_f32_16x16x32_bf16 v[12:15], v[154:157], v[214:217], v[12:15]
	v_mfma_f32_16x16x32_bf16 v[4:7], v[162:165], v[214:217], v[4:7]
	v_mfma_f32_16x16x32_bf16 v[56:59], v[166:169], v[182:185], v[56:59]
	v_mfma_f32_16x16x32_bf16 v[48:51], v[174:177], v[182:185], v[48:51]
	v_mfma_f32_16x16x32_bf16 v[40:43], v[166:169], v[194:197], v[40:43]
	v_mfma_f32_16x16x32_bf16 v[32:35], v[174:177], v[194:197], v[32:35]
	v_mfma_f32_16x16x32_bf16 v[24:27], v[166:169], v[202:205], v[24:27]
	v_mfma_f32_16x16x32_bf16 v[16:19], v[174:177], v[202:205], v[16:19]
	v_mfma_f32_16x16x32_bf16 v[8:11], v[166:169], v[210:213], v[8:11]
	v_mfma_f32_16x16x32_bf16 v[0:3], v[174:177], v[210:213], v[0:3]
	v_mfma_f32_16x16x32_bf16 v[56:59], v[170:173], v[186:189], v[56:59]
	v_mfma_f32_16x16x32_bf16 v[48:51], v[178:181], v[186:189], v[48:51]
	v_mfma_f32_16x16x32_bf16 v[40:43], v[170:173], v[198:201], v[40:43]
	v_mfma_f32_16x16x32_bf16 v[32:35], v[178:181], v[198:201], v[32:35]
	v_mfma_f32_16x16x32_bf16 v[24:27], v[170:173], v[206:209], v[24:27]
	v_mfma_f32_16x16x32_bf16 v[16:19], v[178:181], v[206:209], v[16:19]
	v_mfma_f32_16x16x32_bf16 v[8:11], v[170:173], v[214:217], v[8:11]
	v_mfma_f32_16x16x32_bf16 v[0:3], v[178:181], v[214:217], v[0:3]
	s_barrier
; #define PG8_STAGE(bufoff, gbase, voff) do { _Pragma("unroll") for (int _i = 0; _i < 2; ++_i) \
;         __builtin_amdgcn_global_load_lds((const unsigned*)((const char*)(gbase) + (voff)[_i]), (LAS unsigned*)(lds + (bufoff) + ldsw + _i * 8192), 16, 0, 0); } while (0)
; #define PG8_LDA(dst, b, h) do { _Pragma("unroll") for (int m = 0; m < 4; ++m) _Pragma("unroll") for (int k = 0; k < 2; ++k) dst[m][k] = *(const LAS bf16x8*)(lds + PG8_SA(b, h) + aoff + m * 2048 + k * 1024); } while (0)
; #define PG8_LDB(dst, b, h) do { _Pragma("unroll") for (int n = 0; n < 2; ++n) _Pragma("unroll") for (int k = 0; k < 2; ++k) dst[n][k] = *(const LAS bf16x8*)(lds + PG8_SB(b, h) + boff + n * 2048 + k * 1024); } while (0)
; #define PG8_MMA(ai, bj, At, Bt) do { __builtin_amdgcn_s_setprio(1); _Pragma("unroll") for (int m = 0; m < 4; ++m) _Pragma("unroll") for (int n = 0; n < 2; ++n) _Pragma("unroll") for (int k = 0; k < 2; ++k) \
;         acc[ai][bj][m][n] = __builtin_amdgcn_mfma_f32_16x16x32_bf16(Bt[n][k], At[m][k], acc[ai][bj][m][n], 0, 0, 0); __builtin_amdgcn_s_setprio(0); } while (0)
; #define PG8_WAIT_V(n) asm volatile("s_waitcnt vmcnt(" #n ")" ::: "memory")
; #define PG8_WAIT_L(n) asm volatile("s_waitcnt lgkmcnt(" #n ")" ::: "memory")
; #define PG8_BAR __builtin_amdgcn_s_barrier()
; #define PG8_SCHED __builtin_amdgcn_sched_barrier(0)
; template <class Epi, class Sched = StaticOrder, class EpiSub = NoSub, bool FAST = false>
; __device__ __forceinline__ void gemm_phase(LAS unsigned char* lds, const Gemm g, const Sched& S, const Epi& E, const EpiSub& ES = EpiSub()) {
;     ...
;             PG8_LDB(B0, 1, 0); PG8_LDB(B1, 1, 1); PG8_SCHED; PG8_LDA(At, 1, 0); PG8_STAGE(PG8_SA(0, 1), a2 + hstepA, voffA);
;             PG8_WAIT_V(8); PG8_WAIT_L(0); PG8_BAR; PG8_MMA(0, 0, At, B0); PG8_MMA(0, 1, At, B1); PG8_BAR; PG8_SCHED;
;             PG8_LDA(At, 1, 1); PG8_STAGE(PG8_SB(1, 0), b3, voffB); PG8_STAGE(PG8_SB(1, 1), b3 + hstepB, voffB); PG8_STAGE(PG8_SA(1, 0), a3, voffA);
;             PG8_WAIT_V(8); PG8_WAIT_L(0); PG8_BAR; PG8_MMA(1, 0, At, B0); PG8_MMA(1, 1, At, B1); PG8_BAR; PG8_SCHED;
	s_add_i32 s50, 0, 0x18000
	s_add_i32 s51, 0, 0x1c000
	v_add_u32_e32 v162, s50, v145
	v_add_u32_e32 v178, s51, v145
	ds_read_b128 v[150:153], v162
	ds_read_b128 v[154:157], v162 offset:1024
	ds_read_b128 v[158:161], v162 offset:2048
	ds_read_b128 v[162:165], v162 offset:3072
	ds_read_b128 v[166:169], v178
	ds_read_b128 v[170:173], v178 offset:1024
	ds_read_b128 v[174:177], v178 offset:2048
	ds_read_b128 v[178:181], v178 offset:3072
	s_add_u32 s26, s26, 0x80000
	s_addc_u32 s27, s27, 0
	s_mov_b32 m0, s36
	v_lshl_add_u64 v[224:225], s[26:27], 0, v[128:129]
	ds_read_b128 v[182:185], v149 offset:32768
	ds_read_b128 v[186:189], v149 offset:33792
	ds_read_b128 v[194:197], v149 offset:34816
	ds_read_b128 v[198:201], v149 offset:35840
	ds_read_b128 v[202:205], v149 offset:36864
	ds_read_b128 v[206:209], v149 offset:37888
	ds_read_b128 v[210:213], v149 offset:38912
	ds_read_b128 v[214:217], v149 offset:39936
	global_load_lds_dwordx4 v[224:225], off
	v_lshl_add_u64 v[224:225], s[26:27], 0, v[132:133]
	s_mov_b32 m0, s37
	s_nop 0
	global_load_lds_dwordx4 v[224:225], off
	s_waitcnt vmcnt(8)
	s_waitcnt lgkmcnt(0)
	s_barrier
	v_mfma_f32_16x16x32_bf16 v[124:127], v[150:153], v[182:185], v[124:127]
	v_mfma_f32_16x16x32_bf16 v[116:119], v[158:161], v[182:185], v[116:119]
	v_mfma_f32_16x16x32_bf16 v[108:111], v[150:153], v[194:197], v[108:111]
	v_mfma_f32_16x16x32_bf16 v[100:103], v[158:161], v[194:197], v[100:103]
	v_mfma_f32_16x16x32_bf16 v[92:95], v[150:153], v[202:205], v[92:95]
	v_mfma_f32_16x16x32_bf16 v[84:87], v[158:161], v[202:205], v[84:87]
	v_mfma_f32_16x16x32_bf16 v[76:79], v[150:153], v[210:213], v[76:79]
	v_mfma_f32_16x16x32_bf16 v[68:71], v[158:161], v[210:213], v[68:71]
	v_mfma_f32_16x16x32_bf16 v[124:127], v[154:157], v[186:189], v[124:127]
	v_mfma_f32_16x16x32_bf16 v[116:119], v[162:165], v[186:189], v[116:119]
	v_mfma_f32_16x16x32_bf16 v[108:111], v[154:157], v[198:201], v[108:111]
	v_mfma_f32_16x16x32_bf16 v[100:103], v[162:165], v[198:201], v[100:103]
	v_mfma_f32_16x16x32_bf16 v[92:95], v[154:157], v[206:209], v[92:95]
	v_mfma_f32_16x16x32_bf16 v[84:87], v[162:165], v[206:209], v[84:87]
	v_mfma_f32_16x16x32_bf16 v[76:79], v[154:157], v[214:217], v[76:79]
	v_mfma_f32_16x16x32_bf16 v[68:71], v[162:165], v[214:217], v[68:71]
	v_mfma_f32_16x16x32_bf16 v[120:123], v[166:169], v[182:185], v[120:123]
	v_mfma_f32_16x16x32_bf16 v[112:115], v[174:177], v[182:185], v[112:115]
	v_mfma_f32_16x16x32_bf16 v[104:107], v[166:169], v[194:197], v[104:107]
	v_mfma_f32_16x16x32_bf16 v[96:99], v[174:177], v[194:197], v[96:99]
	v_mfma_f32_16x16x32_bf16 v[88:91], v[166:169], v[202:205], v[88:91]
	v_mfma_f32_16x16x32_bf16 v[80:83], v[174:177], v[202:205], v[80:83]
	v_mfma_f32_16x16x32_bf16 v[72:75], v[166:169], v[210:213], v[72:75]
	v_mfma_f32_16x16x32_bf16 v[64:67], v[174:177], v[210:213], v[64:67]
	v_mfma_f32_16x16x32_bf16 v[120:123], v[170:173], v[186:189], v[120:123]
	v_mfma_f32_16x16x32_bf16 v[112:115], v[178:181], v[186:189], v[112:115]
	v_mfma_f32_16x16x32_bf16 v[104:107], v[170:173], v[198:201], v[104:107]
	v_mfma_f32_16x16x32_bf16 v[96:99], v[178:181], v[198:201], v[96:99]
	v_mfma_f32_16x16x32_bf16 v[88:91], v[170:173], v[206:209], v[88:91]
	v_mfma_f32_16x16x32_bf16 v[80:83], v[178:181], v[206:209], v[80:83]
	v_mfma_f32_16x16x32_bf16 v[72:75], v[170:173], v[214:217], v[72:75]
	v_mfma_f32_16x16x32_bf16 v[64:67], v[178:181], v[214:217], v[64:67]
	s_barrier
	s_add_i32 s26, s50, s28
	v_lshl_add_u64 v[190:191], v[190:191], 0, s[8:9]
	s_mov_b32 m0, s26
	ds_read_b128 v[182:185], v149 offset:49152
	ds_read_b128 v[186:189], v149 offset:50176
	ds_read_b128 v[194:197], v149 offset:51200
	ds_read_b128 v[198:201], v149 offset:52224
	ds_read_b128 v[202:205], v149 offset:53248
	ds_read_b128 v[206:209], v149 offset:54272
	ds_read_b128 v[210:213], v149 offset:55296
	ds_read_b128 v[214:217], v149 offset:56320
	global_load_lds_dwordx4 v[190:191], off
	s_add_i32 m0, s26, 0x2000
	s_add_u32 s24, s24, 0x80080
	v_lshl_add_u64 v[190:191], v[218:219], 0, s[8:9]
	s_addc_u32 s25, s25, 0
	s_add_i32 s26, s51, s28
	global_load_lds_dwordx4 v[190:191], off
	v_lshl_add_u64 v[190:191], s[24:25], 0, v[130:131]
	s_mov_b32 m0, s26
	s_nop 0
	global_load_lds_dwordx4 v[190:191], off
	v_lshl_add_u64 v[190:191], s[24:25], 0, v[134:135]
	s_add_i32 m0, s26, 0x2000
	s_nop 0
	global_load_lds_dwordx4 v[190:191], off
	v_lshl_add_u64 v[190:191], v[220:221], 0, s[8:9]
	s_mov_b32 m0, s40
	s_nop 0
	global_load_lds_dwordx4 v[190:191], off
	v_lshl_add_u64 v[190:191], v[222:223], 0, s[8:9]
	s_mov_b32 m0, s41
	s_nop 0
	global_load_lds_dwordx4 v[190:191], off
	s_add_i32 s49, s49, 2
	s_add_u32 s22, s22, 0x100
	s_addc_u32 s23, s23, 0
	s_add_u32 s47, s47, 0x100
	s_addc_u32 s48, s48, 0
	s_waitcnt vmcnt(8)
	s_waitcnt lgkmcnt(0)
	s_barrier
	v_mfma_f32_16x16x32_bf16 v[60:63], v[150:153], v[182:185], v[60:63]
	v_mfma_f32_16x16x32_bf16 v[52:55], v[158:161], v[182:185], v[52:55]
	v_mfma_f32_16x16x32_bf16 v[44:47], v[150:153], v[194:197], v[44:47]
	v_mfma_f32_16x16x32_bf16 v[36:39], v[158:161], v[194:197], v[36:39]
	v_mfma_f32_16x16x32_bf16 v[28:31], v[150:153], v[202:205], v[28:31]
	v_mfma_f32_16x16x32_bf16 v[20:23], v[158:161], v[202:205], v[20:23]
	v_mfma_f32_16x16x32_bf16 v[12:15], v[150:153], v[210:213], v[12:15]
	v_mfma_f32_16x16x32_bf16 v[4:7], v[158:161], v[210:213], v[4:7]
	v_mfma_f32_16x16x32_bf16 v[60:63], v[154:157], v[186:189], v[60:63]
	v_mfma_f32_16x16x32_bf16 v[52:55], v[162:165], v[186:189], v[52:55]
	v_mfma_f32_16x16x32_bf16 v[44:47], v[154:157], v[198:201], v[44:47]
	v_mfma_f32_16x16x32_bf16 v[36:39], v[162:165], v[198:201], v[36:39]
	v_mfma_f32_16x16x32_bf16 v[28:31], v[154:157], v[206:209], v[28:31]
	v_mfma_f32_16x16x32_bf16 v[20:23], v[162:165], v[206:209], v[20:23]
	v_mfma_f32_16x16x32_bf16 v[12:15], v[154:157], v[214:217], v[12:15]
	v_mfma_f32_16x16x32_bf16 v[4:7], v[162:165], v[214:217], v[4:7]
	v_mfma_f32_16x16x32_bf16 v[56:59], v[166:169], v[182:185], v[56:59]
	v_mfma_f32_16x16x32_bf16 v[48:51], v[174:177], v[182:185], v[48:51]
	v_mfma_f32_16x16x32_bf16 v[40:43], v[166:169], v[194:197], v[40:43]
	v_mfma_f32_16x16x32_bf16 v[32:35], v[174:177], v[194:197], v[32:35]
	v_mfma_f32_16x16x32_bf16 v[24:27], v[166:169], v[202:205], v[24:27]
	v_mfma_f32_16x16x32_bf16 v[16:19], v[174:177], v[202:205], v[16:19]
	v_mfma_f32_16x16x32_bf16 v[8:11], v[166:169], v[210:213], v[8:11]
	v_mfma_f32_16x16x32_bf16 v[0:3], v[174:177], v[210:213], v[0:3]
	v_mfma_f32_16x16x32_bf16 v[56:59], v[170:173], v[186:189], v[56:59]
	v_mfma_f32_16x16x32_bf16 v[48:51], v[178:181], v[186:189], v[48:51]
	v_mfma_f32_16x16x32_bf16 v[40:43], v[170:173], v[198:201], v[40:43]
	v_mfma_f32_16x16x32_bf16 v[32:35], v[178:181], v[198:201], v[32:35]
	v_mfma_f32_16x16x32_bf16 v[24:27], v[170:173], v[206:209], v[24:27]
	v_mfma_f32_16x16x32_bf16 v[16:19], v[178:181], v[206:209], v[16:19]
	v_mfma_f32_16x16x32_bf16 v[8:11], v[170:173], v[214:217], v[8:11]
	v_mfma_f32_16x16x32_bf16 v[0:3], v[178:181], v[214:217], v[0:3]
	s_barrier
	s_cmp_gt_u32 s49, 29
	s_cbranch_scc0 .LBB0_985

; #define PG8_STAGE(bufoff, gbase, voff) do { _Pragma("unroll") for (int _i = 0; _i < 2; ++_i) \
;         __builtin_amdgcn_global_load_lds((const unsigned*)((const char*)(gbase) + (voff)[_i]), (LAS unsigned*)(lds + (bufoff) + ldsw + _i * 8192), 16, 0, 0); } while (0)
; #define PG8_LDA(dst, b, h) do { _Pragma("unroll") for (int m = 0; m < 4; ++m) _Pragma("unroll") for (int k = 0; k < 2; ++k) dst[m][k] = *(const LAS bf16x8*)(lds + PG8_SA(b, h) + aoff + m * 2048 + k * 1024); } while (0)
; #define PG8_LDB(dst, b, h) do { _Pragma("unroll") for (int n = 0; n < 2; ++n) _Pragma("unroll") for (int k = 0; k < 2; ++k) dst[n][k] = *(const LAS bf16x8*)(lds + PG8_SB(b, h) + boff + n * 2048 + k * 1024); } while (0)
; #define PG8_WAIT_V(n) asm volatile("s_waitcnt vmcnt(" #n ")" ::: "memory")
; #define PG8_WAIT_L(n) asm volatile("s_waitcnt lgkmcnt(" #n ")" ::: "memory")
; #define PG8_BAR __builtin_amdgcn_s_barrier()
; template <class Epi, class Sched = StaticOrder, class EpiSub = NoSub, bool FAST = false>
; __device__ __forceinline__ void gemm_phase(LAS unsigned char* lds, const Gemm g, const Sched& S, const Epi& E, const EpiSub& ES = EpiSub()) {
;     ...
;         const size_t nko = (has_next && nxt.kb >= 0) ? nxt.kb * ksubB : 0;
;         const char* nA = has_next ? (const char*)g.A + (size_t)nxt.pm * tstepA + (size_t)nxt.pn * g.acs + nko : cA; const char* nB = has_next ? (const char*)g.Bt + (size_t)nxt.pn * tstepB + nko : cB;
;         const int nt = cur.kb < 0 ? ntMain : ntSub;
;         for (int t = 0; t < nt; t += 2) {
;             const bool last = (t == nt - 2);
;             const char* a1 = cA + (size_t)(t + 1) * kstep;
;             const char* a2 = last ? nA : cA + (size_t)(t + 2) * kstep; const char* b2 = last ? nB : cB + (size_t)(t + 2) * kstep;
;             const char* a3 = a2 + kstep; const char* b3 = b2 + kstep;
;             if constexpr (FAST && PG8_SP2) {
;             PG8_LDB(B0, 0, 0); PG8_LDB(B1, 0, 1); PG8_SCHED; PG8_LDA(At, 0, 0); PG8_STAGE(PG8_SA(1, 1), a1 + hstepA, voffA);
;             PG8_WAIT_V(8); PG8_WAIT_L(0); PG8_BAR; PG8_MMA(0, 0, At, B0); PG8_MMA(0, 1, At, B1); PG8_BAR; PG8_SCHED;
;             PG8_LDA(At, 0, 1); PG8_STAGE(PG8_SB(0, 0), b2, voffB); PG8_STAGE(PG8_SB(0, 1), b2 + hstepB, voffB); PG8_STAGE(PG8_SA(0, 0), a2, voffA);
;             PG8_WAIT_V(8); PG8_WAIT_L(0); PG8_BAR; PG8_MMA(1, 0, At, B0); PG8_MMA(1, 1, At, B1); PG8_BAR; PG8_SCHED;
.LBB0_1078:
	s_cmp_gt_i32 s8, -1
	s_cselect_b64 s[4:5], -1, 0
	s_cmp_lt_i32 s8, 0
	s_cselect_b32 s70, 0x58, 22
	s_add_i32 s71, s70, -2
	s_add_u32 s42, s42, 0x160080
	s_addc_u32 s43, s43, 0
	s_add_u32 s83, s44, 0x100
	s_mov_b32 s46, 0
	s_addc_u32 s84, s45, 0
	ds_read_b128 v[96:99], v201
	ds_read_b128 v[100:103], v201 offset:1024
	ds_read_b128 v[108:111], v201 offset:2048
	ds_read_b128 v[116:119], v201 offset:3072
	ds_read_b128 v[144:147], v202
	ds_read_b128 v[148:151], v202 offset:1024
	ds_read_b128 v[152:155], v202 offset:2048
	ds_read_b128 v[156:159], v202 offset:3072
	s_add_i32 s85, s46, 2
	s_add_u32 s44, s42, 0xffea0080
	s_addc_u32 s45, s43, -1
	s_cmp_eq_u32 s71, s46
	s_cselect_b32 s46, s38, s44
	s_cselect_b32 s47, s39, s45
	s_cselect_b32 s45, s41, s84
	s_cselect_b32 s44, s40, s83
	v_lshl_add_u64 v[190:191], s[42:43], 0, v[176:177]
	s_add_i32 m0, s48, 0xc000
	ds_read_b128 v[160:163], v203
	ds_read_b128 v[164:167], v203 offset:1024
	ds_read_b128 v[182:185], v203 offset:2048
	ds_read_b128 v[186:189], v203 offset:3072
	ds_read_b128 v[194:197], v203 offset:4096
	ds_read_b128 v[204:207], v203 offset:5120
	ds_read_b128 v[208:211], v203 offset:6144
	ds_read_b128 v[212:215], v203 offset:7168
	global_load_lds_dwordx4 v[190:191], off
	v_lshl_add_u64 v[190:191], s[42:43], 0, v[178:179]
	s_add_i32 m0, s48, 0xe000
	s_nop 0
	global_load_lds_dwordx4 v[190:191], off
	s_waitcnt vmcnt(8)
	s_waitcnt lgkmcnt(0)
	s_barrier
	v_mfma_f32_16x16x32_bf16 v[140:143], v[96:99], v[160:163], 0
	v_mfma_f32_16x16x32_bf16 v[136:139], v[108:111], v[160:163], 0
	v_mfma_f32_16x16x32_bf16 v[124:127], v[96:99], v[182:185], 0
	v_mfma_f32_16x16x32_bf16 v[120:123], v[108:111], v[182:185], 0
	v_mfma_f32_16x16x32_bf16 v[92:95], v[96:99], v[194:197], 0
	v_mfma_f32_16x16x32_bf16 v[88:91], v[108:111], v[194:197], 0
	v_mfma_f32_16x16x32_bf16 v[76:79], v[96:99], v[208:211], 0
	v_mfma_f32_16x16x32_bf16 v[72:75], v[108:111], v[208:211], 0
	v_mfma_f32_16x16x32_bf16 v[140:143], v[100:103], v[164:167], v[140:143]
	v_mfma_f32_16x16x32_bf16 v[136:139], v[116:119], v[164:167], v[136:139]
	v_mfma_f32_16x16x32_bf16 v[124:127], v[100:103], v[186:189], v[124:127]
	v_mfma_f32_16x16x32_bf16 v[120:123], v[116:119], v[186:189], v[120:123]
	v_mfma_f32_16x16x32_bf16 v[92:95], v[100:103], v[204:207], v[92:95]
	v_mfma_f32_16x16x32_bf16 v[88:91], v[116:119], v[204:207], v[88:91]
	v_mfma_f32_16x16x32_bf16 v[76:79], v[100:103], v[212:215], v[76:79]
	v_mfma_f32_16x16x32_bf16 v[72:75], v[116:119], v[212:215], v[72:75]
	v_mfma_f32_16x16x32_bf16 v[132:135], v[144:147], v[160:163], 0
	v_mfma_f32_16x16x32_bf16 v[128:131], v[152:155], v[160:163], 0
	v_mfma_f32_16x16x32_bf16 v[112:115], v[144:147], v[182:185], 0
	v_mfma_f32_16x16x32_bf16 v[104:107], v[152:155], v[182:185], 0
	v_mfma_f32_16x16x32_bf16 v[84:87], v[144:147], v[194:197], 0
	v_mfma_f32_16x16x32_bf16 v[80:83], v[152:155], v[194:197], 0
	v_mfma_f32_16x16x32_bf16 v[68:71], v[144:147], v[208:211], 0
	v_mfma_f32_16x16x32_bf16 v[64:67], v[152:155], v[208:211], 0
	v_mfma_f32_16x16x32_bf16 v[132:135], v[148:151], v[164:167], v[132:135]
	v_mfma_f32_16x16x32_bf16 v[128:131], v[156:159], v[164:167], v[128:131]
	v_mfma_f32_16x16x32_bf16 v[112:115], v[148:151], v[186:189], v[112:115]
	v_mfma_f32_16x16x32_bf16 v[104:107], v[156:159], v[186:189], v[104:107]
	v_mfma_f32_16x16x32_bf16 v[84:87], v[148:151], v[204:207], v[84:87]
	v_mfma_f32_16x16x32_bf16 v[80:83], v[156:159], v[204:207], v[80:83]
	v_mfma_f32_16x16x32_bf16 v[68:71], v[148:151], v[212:215], v[68:71]
	v_mfma_f32_16x16x32_bf16 v[64:67], v[156:159], v[212:215], v[64:67]
	s_barrier
	s_add_i32 s86, s58, s27
	v_lshl_add_u64 v[190:191], s[44:45], 0, v[170:171]
	s_mov_b32 m0, s86
	ds_read_b128 v[160:163], v203 offset:16384
	ds_read_b128 v[164:167], v203 offset:17408
	ds_read_b128 v[182:185], v203 offset:18432
	ds_read_b128 v[186:189], v203 offset:19456
	ds_read_b128 v[194:197], v203 offset:20480
	ds_read_b128 v[204:207], v203 offset:21504
	ds_read_b128 v[208:211], v203 offset:22528
	ds_read_b128 v[212:215], v203 offset:23552
	global_load_lds_dwordx4 v[190:191], off
	s_add_i32 m0, s86, 0x2000
	s_add_u32 s86, s44, 0x160000
	v_lshl_add_u64 v[216:217], s[44:45], 0, v[174:175]
	s_addc_u32 s87, s45, 0
	s_add_i32 s88, s59, s27
	global_load_lds_dwordx4 v[216:217], off
	v_lshl_add_u64 v[218:219], s[86:87], 0, v[170:171]
	s_mov_b32 m0, s88
	v_lshl_add_u64 v[220:221], s[46:47], 0, v[172:173]
	global_load_lds_dwordx4 v[218:219], off
	v_lshl_add_u64 v[218:219], s[86:87], 0, v[174:175]
	s_add_i32 m0, s88, 0x2000
	s_nop 0
	global_load_lds_dwordx4 v[218:219], off
	v_lshl_add_u64 v[218:219], s[46:47], 0, v[168:169]
	s_mov_b32 m0, s48
	s_nop 0
	global_load_lds_dwordx4 v[218:219], off
	s_mov_b32 m0, s49
	s_nop 0
	global_load_lds_dwordx4 v[220:221], off
	s_waitcnt vmcnt(8)
	s_waitcnt lgkmcnt(0)
	s_barrier
; #define PG8_STAGE(bufoff, gbase, voff) do { _Pragma("unroll") for (int _i = 0; _i < 2; ++_i) \
;         __builtin_amdgcn_global_load_lds((const unsigned*)((const char*)(gbase) + (voff)[_i]), (LAS unsigned*)(lds + (bufoff) + ldsw + _i * 8192), 16, 0, 0); } while (0)
; #define PG8_LDA(dst, b, h) do { _Pragma("unroll") for (int m = 0; m < 4; ++m) _Pragma("unroll") for (int k = 0; k < 2; ++k) dst[m][k] = *(const LAS bf16x8*)(lds + PG8_SA(b, h) + aoff + m * 2048 + k * 1024); } while (0)
; #define PG8_LDB(dst, b, h) do { _Pragma("unroll") for (int n = 0; n < 2; ++n) _Pragma("unroll") for (int k = 0; k < 2; ++k) dst[n][k] = *(const LAS bf16x8*)(lds + PG8_SB(b, h) + boff + n * 2048 + k * 1024); } while (0)
; #define PG8_MMA(ai, bj, At, Bt) do { __builtin_amdgcn_s_setprio(1); _Pragma("unroll") for (int m = 0; m < 4; ++m) _Pragma("unroll") for (int n = 0; n < 2; ++n) _Pragma("unroll") for (int k = 0; k < 2; ++k) \
;         acc[ai][bj][m][n] = __builtin_amdgcn_mfma_f32_16x16x32_bf16(Bt[n][k], At[m][k], acc[ai][bj][m][n], 0, 0, 0); __builtin_amdgcn_s_setprio(0); } while (0)
; #define PG8_WAIT_V(n) asm volatile("s_waitcnt vmcnt(" #n ")" ::: "memory")
; #define PG8_WAIT_L(n) asm volatile("s_waitcnt lgkmcnt(" #n ")" ::: "memory")
; #define PG8_BAR __builtin_amdgcn_s_barrier()
; #define PG8_SCHED __builtin_amdgcn_sched_barrier(0)
; template <class Epi, class Sched = StaticOrder, class EpiSub = NoSub, bool FAST = false>
; __device__ __forceinline__ void gemm_phase(LAS unsigned char* lds, const Gemm g, const Sched& S, const Epi& E, const EpiSub& ES = EpiSub()) {
;     ...
;             PG8_WAIT_V(8); PG8_WAIT_L(0); PG8_BAR; PG8_MMA(1, 0, At, B0); PG8_MMA(1, 1, At, B1); PG8_BAR; PG8_SCHED;
;             PG8_LDB(B0, 1, 0); PG8_LDB(B1, 1, 1); PG8_SCHED; PG8_LDA(At, 1, 0); PG8_STAGE(PG8_SA(0, 1), a2 + hstepA, voffA);
;             PG8_WAIT_V(8); PG8_WAIT_L(0); PG8_BAR; PG8_MMA(0, 0, At, B0); PG8_MMA(0, 1, At, B1); PG8_BAR; PG8_SCHED;
;             PG8_LDA(At, 1, 1); PG8_STAGE(PG8_SB(1, 0), b3, voffB); PG8_STAGE(PG8_SB(1, 1), b3 + hstepB, voffB); PG8_STAGE(PG8_SA(1, 0), a3, voffA);
	v_mfma_f32_16x16x32_bf16 v[60:63], v[96:99], v[160:163], 0
	v_mfma_f32_16x16x32_bf16 v[56:59], v[108:111], v[160:163], 0
	v_mfma_f32_16x16x32_bf16 v[44:47], v[96:99], v[182:185], 0
	v_mfma_f32_16x16x32_bf16 v[40:43], v[108:111], v[182:185], 0
	v_mfma_f32_16x16x32_bf16 v[28:31], v[96:99], v[194:197], 0
	v_mfma_f32_16x16x32_bf16 v[24:27], v[108:111], v[194:197], 0
	v_mfma_f32_16x16x32_bf16 v[12:15], v[96:99], v[208:211], 0
	v_mfma_f32_16x16x32_bf16 v[8:11], v[108:111], v[208:211], 0
	v_mfma_f32_16x16x32_bf16 v[60:63], v[100:103], v[164:167], v[60:63]
	v_mfma_f32_16x16x32_bf16 v[56:59], v[116:119], v[164:167], v[56:59]
	v_mfma_f32_16x16x32_bf16 v[44:47], v[100:103], v[186:189], v[44:47]
	v_mfma_f32_16x16x32_bf16 v[40:43], v[116:119], v[186:189], v[40:43]
	v_mfma_f32_16x16x32_bf16 v[28:31], v[100:103], v[204:207], v[28:31]
	v_mfma_f32_16x16x32_bf16 v[24:27], v[116:119], v[204:207], v[24:27]
	v_mfma_f32_16x16x32_bf16 v[12:15], v[100:103], v[212:215], v[12:15]
	v_mfma_f32_16x16x32_bf16 v[8:11], v[116:119], v[212:215], v[8:11]
	v_mfma_f32_16x16x32_bf16 v[52:55], v[144:147], v[160:163], 0
	v_mfma_f32_16x16x32_bf16 v[48:51], v[152:155], v[160:163], 0
	v_mfma_f32_16x16x32_bf16 v[36:39], v[144:147], v[182:185], 0
	v_mfma_f32_16x16x32_bf16 v[32:35], v[152:155], v[182:185], 0
	v_mfma_f32_16x16x32_bf16 v[20:23], v[144:147], v[194:197], 0
	v_mfma_f32_16x16x32_bf16 v[16:19], v[152:155], v[194:197], 0
	v_mfma_f32_16x16x32_bf16 v[4:7], v[144:147], v[208:211], 0
	v_mfma_f32_16x16x32_bf16 v[0:3], v[152:155], v[208:211], 0
	v_mfma_f32_16x16x32_bf16 v[52:55], v[148:151], v[164:167], v[52:55]
	v_mfma_f32_16x16x32_bf16 v[48:51], v[156:159], v[164:167], v[48:51]
	v_mfma_f32_16x16x32_bf16 v[36:39], v[148:151], v[186:189], v[36:39]
	v_mfma_f32_16x16x32_bf16 v[32:35], v[156:159], v[186:189], v[32:35]
	v_mfma_f32_16x16x32_bf16 v[20:23], v[148:151], v[204:207], v[20:23]
	v_mfma_f32_16x16x32_bf16 v[16:19], v[156:159], v[204:207], v[16:19]
	v_mfma_f32_16x16x32_bf16 v[4:7], v[148:151], v[212:215], v[4:7]
	v_mfma_f32_16x16x32_bf16 v[0:3], v[156:159], v[212:215], v[0:3]
	s_barrier
	s_add_i32 s86, 0, 0x18000
	s_add_i32 s87, 0, 0x1c000
	v_add_u32_e32 v116, s86, v198
	v_add_u32_e32 v156, s87, v198
	ds_read_b128 v[96:99], v116
	ds_read_b128 v[100:103], v116 offset:1024
	ds_read_b128 v[108:111], v116 offset:2048
	ds_read_b128 v[116:119], v116 offset:3072
	ds_read_b128 v[144:147], v156
	ds_read_b128 v[148:151], v156 offset:1024
	ds_read_b128 v[152:155], v156 offset:2048
	ds_read_b128 v[156:159], v156 offset:3072
	s_add_u32 s46, s46, 0x160000
	s_addc_u32 s47, s47, 0
	s_mov_b32 m0, s50
	v_lshl_add_u64 v[222:223], s[46:47], 0, v[168:169]
	ds_read_b128 v[160:163], v203 offset:32768
	ds_read_b128 v[164:167], v203 offset:33792
	ds_read_b128 v[182:185], v203 offset:34816
	ds_read_b128 v[186:189], v203 offset:35840
	ds_read_b128 v[194:197], v203 offset:36864
	ds_read_b128 v[204:207], v203 offset:37888
	ds_read_b128 v[208:211], v203 offset:38912
	ds_read_b128 v[212:215], v203 offset:39936
	global_load_lds_dwordx4 v[222:223], off
	v_lshl_add_u64 v[222:223], s[46:47], 0, v[172:173]
	s_mov_b32 m0, s51
	s_nop 0
	global_load_lds_dwordx4 v[222:223], off
	s_waitcnt vmcnt(8)
	s_waitcnt lgkmcnt(0)
	s_barrier
	v_mfma_f32_16x16x32_bf16 v[140:143], v[96:99], v[160:163], v[140:143]
	v_mfma_f32_16x16x32_bf16 v[136:139], v[108:111], v[160:163], v[136:139]
	v_mfma_f32_16x16x32_bf16 v[124:127], v[96:99], v[182:185], v[124:127]
	v_mfma_f32_16x16x32_bf16 v[120:123], v[108:111], v[182:185], v[120:123]
	v_mfma_f32_16x16x32_bf16 v[92:95], v[96:99], v[194:197], v[92:95]
	v_mfma_f32_16x16x32_bf16 v[88:91], v[108:111], v[194:197], v[88:91]
	v_mfma_f32_16x16x32_bf16 v[76:79], v[96:99], v[208:211], v[76:79]
	v_mfma_f32_16x16x32_bf16 v[72:75], v[108:111], v[208:211], v[72:75]
	v_mfma_f32_16x16x32_bf16 v[140:143], v[100:103], v[164:167], v[140:143]
	v_mfma_f32_16x16x32_bf16 v[136:139], v[116:119], v[164:167], v[136:139]
	v_mfma_f32_16x16x32_bf16 v[124:127], v[100:103], v[186:189], v[124:127]
	v_mfma_f32_16x16x32_bf16 v[120:123], v[116:119], v[186:189], v[120:123]
	v_mfma_f32_16x16x32_bf16 v[92:95], v[100:103], v[204:207], v[92:95]
	v_mfma_f32_16x16x32_bf16 v[88:91], v[116:119], v[204:207], v[88:91]
	v_mfma_f32_16x16x32_bf16 v[76:79], v[100:103], v[212:215], v[76:79]
	v_mfma_f32_16x16x32_bf16 v[72:75], v[116:119], v[212:215], v[72:75]
	v_mfma_f32_16x16x32_bf16 v[132:135], v[144:147], v[160:163], v[132:135]
	v_mfma_f32_16x16x32_bf16 v[128:131], v[152:155], v[160:163], v[128:131]
	v_mfma_f32_16x16x32_bf16 v[112:115], v[144:147], v[182:185], v[112:115]
	v_mfma_f32_16x16x32_bf16 v[104:107], v[152:155], v[182:185], v[104:107]
	v_mfma_f32_16x16x32_bf16 v[84:87], v[144:147], v[194:197], v[84:87]
	v_mfma_f32_16x16x32_bf16 v[80:83], v[152:155], v[194:197], v[80:83]
	v_mfma_f32_16x16x32_bf16 v[68:71], v[144:147], v[208:211], v[68:71]
	v_mfma_f32_16x16x32_bf16 v[64:67], v[152:155], v[208:211], v[64:67]
	v_mfma_f32_16x16x32_bf16 v[132:135], v[148:151], v[164:167], v[132:135]
	v_mfma_f32_16x16x32_bf16 v[128:131], v[156:159], v[164:167], v[128:131]
	v_mfma_f32_16x16x32_bf16 v[112:115], v[148:151], v[186:189], v[112:115]
	v_mfma_f32_16x16x32_bf16 v[104:107], v[156:159], v[186:189], v[104:107]
	v_mfma_f32_16x16x32_bf16 v[84:87], v[148:151], v[204:207], v[84:87]
	v_mfma_f32_16x16x32_bf16 v[80:83], v[156:159], v[204:207], v[80:83]
	v_mfma_f32_16x16x32_bf16 v[68:71], v[148:151], v[212:215], v[68:71]
	v_mfma_f32_16x16x32_bf16 v[64:67], v[156:159], v[212:215], v[64:67]
	s_barrier
; #define PG8_STAGE(bufoff, gbase, voff) do { _Pragma("unroll") for (int _i = 0; _i < 2; ++_i) \
;         __builtin_amdgcn_global_load_lds((const unsigned*)((const char*)(gbase) + (voff)[_i]), (LAS unsigned*)(lds + (bufoff) + ldsw + _i * 8192), 16, 0, 0); } while (0)
; #define PG8_LDA(dst, b, h) do { _Pragma("unroll") for (int m = 0; m < 4; ++m) _Pragma("unroll") for (int k = 0; k < 2; ++k) dst[m][k] = *(const LAS bf16x8*)(lds + PG8_SA(b, h) + aoff + m * 2048 + k * 1024); } while (0)
; #define PG8_LDB(dst, b, h) do { _Pragma("unroll") for (int n = 0; n < 2; ++n) _Pragma("unroll") for (int k = 0; k < 2; ++k) dst[n][k] = *(const LAS bf16x8*)(lds + PG8_SB(b, h) + boff + n * 2048 + k * 1024); } while (0)
; template <class Epi, class Sched = StaticOrder, class EpiSub = NoSub, bool FAST = false>
; __device__ __forceinline__ void gemm_phase(LAS unsigned char* lds, const Gemm g, const Sched& S, const Epi& E, const EpiSub& ES = EpiSub()) {
;     ...
;         for (int t = 0; t < nt; t += 2) {
;             const bool last = (t == nt - 2);
;             const char* a1 = cA + (size_t)(t + 1) * kstep;
;             const char* a2 = last ? nA : cA + (size_t)(t + 2) * kstep; const char* b2 = last ? nB : cB + (size_t)(t + 2) * kstep;
;             const char* a3 = a2 + kstep; const char* b3 = b2 + kstep;
;             if constexpr (FAST && PG8_SP2) {
;             PG8_LDB(B0, 0, 0); PG8_LDB(B1, 0, 1); PG8_SCHED; PG8_LDA(At, 0, 0); PG8_STAGE(PG8_SA(1, 1), a1 + hstepA, voffA);
;             PG8_WAIT_V(8); PG8_WAIT_L(0); PG8_BAR; PG8_MMA(0, 0, At, B0); PG8_MMA(0, 1, At, B1); PG8_BAR; PG8_SCHED;
;             PG8_LDA(At, 0, 1); PG8_STAGE(PG8_SB(0, 0), b2, voffB); PG8_STAGE(PG8_SB(0, 1), b2 + hstepB, voffB); PG8_STAGE(PG8_SA(0, 0), a2, voffA);
;             PG8_WAIT_V(8); PG8_WAIT_L(0); PG8_BAR; PG8_MMA(1, 0, At, B0); PG8_MMA(1, 1, At, B1); PG8_BAR; PG8_SCHED;
;             PG8_LDB(B0, 1, 0); PG8_LDB(B1, 1, 1); PG8_SCHED; PG8_LDA(At, 1, 0); PG8_STAGE(PG8_SA(0, 1), a2 + hstepA, voffA);
;             PG8_WAIT_V(8); PG8_WAIT_L(0); PG8_BAR; PG8_MMA(0, 0, At, B0); PG8_MMA(0, 1, At, B1); PG8_BAR; PG8_SCHED;
;             PG8_LDA(At, 1, 1); PG8_STAGE(PG8_SB(1, 0), b3, voffB); PG8_STAGE(PG8_SB(1, 1), b3 + hstepB, voffB); PG8_STAGE(PG8_SA(1, 0), a3, voffA);
;             PG8_WAIT_V(8); PG8_WAIT_L(0); PG8_BAR; PG8_MMA(1, 0, At, B0); PG8_MMA(1, 1, At, B1); PG8_BAR; PG8_SCHED;
	s_add_i32 s46, s86, s27
	v_lshl_add_u64 v[190:191], v[190:191], 0, s[16:17]
	s_mov_b32 m0, s46
	ds_read_b128 v[160:163], v203 offset:49152
	ds_read_b128 v[164:167], v203 offset:50176
	ds_read_b128 v[182:185], v203 offset:51200
	ds_read_b128 v[186:189], v203 offset:52224
	ds_read_b128 v[194:197], v203 offset:53248
	ds_read_b128 v[204:207], v203 offset:54272
	ds_read_b128 v[208:211], v203 offset:55296
	ds_read_b128 v[212:215], v203 offset:56320
	global_load_lds_dwordx4 v[190:191], off
	s_add_i32 m0, s46, 0x2000
	s_add_u32 s44, s44, 0x160080
	v_lshl_add_u64 v[190:191], v[216:217], 0, s[16:17]
	s_addc_u32 s45, s45, 0
	s_add_i32 s46, s87, s27
	global_load_lds_dwordx4 v[190:191], off
	v_lshl_add_u64 v[190:191], s[44:45], 0, v[170:171]
	s_mov_b32 m0, s46
	s_nop 0
	global_load_lds_dwordx4 v[190:191], off
	v_lshl_add_u64 v[190:191], s[44:45], 0, v[174:175]
	s_add_i32 m0, s46, 0x2000
	s_nop 0
	global_load_lds_dwordx4 v[190:191], off
	v_lshl_add_u64 v[190:191], v[218:219], 0, s[16:17]
	s_mov_b32 m0, s53
	s_nop 0
	global_load_lds_dwordx4 v[190:191], off
	v_lshl_add_u64 v[190:191], v[220:221], 0, s[16:17]
	s_mov_b32 m0, s54
	s_nop 0
	global_load_lds_dwordx4 v[190:191], off
	s_add_u32 s42, s42, 0x100
	s_addc_u32 s43, s43, 0
	s_add_u32 s83, s83, 0x100
	s_addc_u32 s84, s84, 0
	s_waitcnt vmcnt(8)
	s_waitcnt lgkmcnt(0)
	s_barrier
	v_mfma_f32_16x16x32_bf16 v[60:63], v[96:99], v[160:163], v[60:63]
	v_mfma_f32_16x16x32_bf16 v[56:59], v[108:111], v[160:163], v[56:59]
	v_mfma_f32_16x16x32_bf16 v[44:47], v[96:99], v[182:185], v[44:47]
	v_mfma_f32_16x16x32_bf16 v[40:43], v[108:111], v[182:185], v[40:43]
	v_mfma_f32_16x16x32_bf16 v[28:31], v[96:99], v[194:197], v[28:31]
	v_mfma_f32_16x16x32_bf16 v[24:27], v[108:111], v[194:197], v[24:27]
	v_mfma_f32_16x16x32_bf16 v[12:15], v[96:99], v[208:211], v[12:15]
	v_mfma_f32_16x16x32_bf16 v[8:11], v[108:111], v[208:211], v[8:11]
	v_mfma_f32_16x16x32_bf16 v[60:63], v[100:103], v[164:167], v[60:63]
	v_mfma_f32_16x16x32_bf16 v[56:59], v[116:119], v[164:167], v[56:59]
	v_mfma_f32_16x16x32_bf16 v[44:47], v[100:103], v[186:189], v[44:47]
	v_mfma_f32_16x16x32_bf16 v[40:43], v[116:119], v[186:189], v[40:43]
	v_mfma_f32_16x16x32_bf16 v[28:31], v[100:103], v[204:207], v[28:31]
	v_mfma_f32_16x16x32_bf16 v[24:27], v[116:119], v[204:207], v[24:27]
	v_mfma_f32_16x16x32_bf16 v[12:15], v[100:103], v[212:215], v[12:15]
	v_mfma_f32_16x16x32_bf16 v[8:11], v[116:119], v[212:215], v[8:11]
	v_mfma_f32_16x16x32_bf16 v[52:55], v[144:147], v[160:163], v[52:55]
	v_mfma_f32_16x16x32_bf16 v[48:51], v[152:155], v[160:163], v[48:51]
	v_mfma_f32_16x16x32_bf16 v[36:39], v[144:147], v[182:185], v[36:39]
	v_mfma_f32_16x16x32_bf16 v[32:35], v[152:155], v[182:185], v[32:35]
	v_mfma_f32_16x16x32_bf16 v[20:23], v[144:147], v[194:197], v[20:23]
	v_mfma_f32_16x16x32_bf16 v[16:19], v[152:155], v[194:197], v[16:19]
	v_mfma_f32_16x16x32_bf16 v[4:7], v[144:147], v[208:211], v[4:7]
	v_mfma_f32_16x16x32_bf16 v[0:3], v[152:155], v[208:211], v[0:3]
	v_mfma_f32_16x16x32_bf16 v[52:55], v[148:151], v[164:167], v[52:55]
	v_mfma_f32_16x16x32_bf16 v[48:51], v[156:159], v[164:167], v[48:51]
	v_mfma_f32_16x16x32_bf16 v[36:39], v[148:151], v[186:189], v[36:39]
	v_mfma_f32_16x16x32_bf16 v[32:35], v[156:159], v[186:189], v[32:35]
	v_mfma_f32_16x16x32_bf16 v[20:23], v[148:151], v[204:207], v[20:23]
	v_mfma_f32_16x16x32_bf16 v[16:19], v[156:159], v[204:207], v[16:19]
	v_mfma_f32_16x16x32_bf16 v[4:7], v[148:151], v[212:215], v[4:7]
	v_mfma_f32_16x16x32_bf16 v[0:3], v[156:159], v[212:215], v[0:3]
	s_barrier
	s_cmp_ge_u32 s85, s70
	s_mov_b32 s46, s85
	s_cbranch_scc1 .Lkpeel_1079_exit
.LBB0_1079:
	ds_read_b128 v[96:99], v201
	ds_read_b128 v[100:103], v201 offset:1024
	ds_read_b128 v[108:111], v201 offset:2048
	ds_read_b128 v[116:119], v201 offset:3072
	ds_read_b128 v[144:147], v202
	ds_read_b128 v[148:151], v202 offset:1024
	ds_read_b128 v[152:155], v202 offset:2048
	ds_read_b128 v[156:159], v202 offset:3072
	s_add_i32 s85, s46, 2
	s_add_u32 s44, s42, 0xffea0080
	s_addc_u32 s45, s43, -1
	s_cmp_eq_u32 s71, s46
	s_cselect_b32 s46, s38, s44
	s_cselect_b32 s47, s39, s45
	s_cselect_b32 s45, s41, s84
	s_cselect_b32 s44, s40, s83
	v_lshl_add_u64 v[190:191], s[42:43], 0, v[176:177]
	s_add_i32 m0, s48, 0xc000
	ds_read_b128 v[160:163], v203
	ds_read_b128 v[164:167], v203 offset:1024
	ds_read_b128 v[182:185], v203 offset:2048
	ds_read_b128 v[186:189], v203 offset:3072
	ds_read_b128 v[194:197], v203 offset:4096
	ds_read_b128 v[204:207], v203 offset:5120
	ds_read_b128 v[208:211], v203 offset:6144
	ds_read_b128 v[212:215], v203 offset:7168
	global_load_lds_dwordx4 v[190:191], off
	v_lshl_add_u64 v[190:191], s[42:43], 0, v[178:179]
	s_add_i32 m0, s48, 0xe000
	s_nop 0
	global_load_lds_dwordx4 v[190:191], off
	s_waitcnt vmcnt(8)
	s_waitcnt lgkmcnt(0)
	s_barrier
; #define PG8_STAGE(bufoff, gbase, voff) do { _Pragma("unroll") for (int _i = 0; _i < 2; ++_i) \
;         __builtin_amdgcn_global_load_lds((const unsigned*)((const char*)(gbase) + (voff)[_i]), (LAS unsigned*)(lds + (bufoff) + ldsw + _i * 8192), 16, 0, 0); } while (0)
; #define PG8_LDA(dst, b, h) do { _Pragma("unroll") for (int m = 0; m < 4; ++m) _Pragma("unroll") for (int k = 0; k < 2; ++k) dst[m][k] = *(const LAS bf16x8*)(lds + PG8_SA(b, h) + aoff + m * 2048 + k * 1024); } while (0)
; #define PG8_LDB(dst, b, h) do { _Pragma("unroll") for (int n = 0; n < 2; ++n) _Pragma("unroll") for (int k = 0; k < 2; ++k) dst[n][k] = *(const LAS bf16x8*)(lds + PG8_SB(b, h) + boff + n * 2048 + k * 1024); } while (0)
; #define PG8_MMA(ai, bj, At, Bt) do { __builtin_amdgcn_s_setprio(1); _Pragma("unroll") for (int m = 0; m < 4; ++m) _Pragma("unroll") for (int n = 0; n < 2; ++n) _Pragma("unroll") for (int k = 0; k < 2; ++k) \
;         acc[ai][bj][m][n] = __builtin_amdgcn_mfma_f32_16x16x32_bf16(Bt[n][k], At[m][k], acc[ai][bj][m][n], 0, 0, 0); __builtin_amdgcn_s_setprio(0); } while (0)
; #define PG8_WAIT_V(n) asm volatile("s_waitcnt vmcnt(" #n ")" ::: "memory")
; #define PG8_WAIT_L(n) asm volatile("s_waitcnt lgkmcnt(" #n ")" ::: "memory")
; #define PG8_BAR __builtin_amdgcn_s_barrier()
; #define PG8_SCHED __builtin_amdgcn_sched_barrier(0)
; template <class Epi, class Sched = StaticOrder, class EpiSub = NoSub, bool FAST = false>
; __device__ __forceinline__ void gemm_phase(LAS unsigned char* lds, const Gemm g, const Sched& S, const Epi& E, const EpiSub& ES = EpiSub()) {
;     ...
;             PG8_WAIT_V(8); PG8_WAIT_L(0); PG8_BAR; PG8_MMA(0, 0, At, B0); PG8_MMA(0, 1, At, B1); PG8_BAR; PG8_SCHED;
;             PG8_LDA(At, 0, 1); PG8_STAGE(PG8_SB(0, 0), b2, voffB); PG8_STAGE(PG8_SB(0, 1), b2 + hstepB, voffB); PG8_STAGE(PG8_SA(0, 0), a2, voffA);
;             PG8_WAIT_V(8); PG8_WAIT_L(0); PG8_BAR; PG8_MMA(1, 0, At, B0); PG8_MMA(1, 1, At, B1); PG8_BAR; PG8_SCHED;
;             PG8_LDB(B0, 1, 0); PG8_LDB(B1, 1, 1); PG8_SCHED; PG8_LDA(At, 1, 0); PG8_STAGE(PG8_SA(0, 1), a2 + hstepA, voffA);
;             PG8_WAIT_V(8); PG8_WAIT_L(0); PG8_BAR; PG8_MMA(0, 0, At, B0); PG8_MMA(0, 1, At, B1); PG8_BAR; PG8_SCHED;
;             PG8_LDA(At, 1, 1); PG8_STAGE(PG8_SB(1, 0), b3, voffB); PG8_STAGE(PG8_SB(1, 1), b3 + hstepB, voffB); PG8_STAGE(PG8_SA(1, 0), a3, voffA);
	v_mfma_f32_16x16x32_bf16 v[140:143], v[96:99], v[160:163], v[140:143]
	v_mfma_f32_16x16x32_bf16 v[136:139], v[108:111], v[160:163], v[136:139]
	v_mfma_f32_16x16x32_bf16 v[124:127], v[96:99], v[182:185], v[124:127]
	v_mfma_f32_16x16x32_bf16 v[120:123], v[108:111], v[182:185], v[120:123]
	v_mfma_f32_16x16x32_bf16 v[92:95], v[96:99], v[194:197], v[92:95]
	v_mfma_f32_16x16x32_bf16 v[88:91], v[108:111], v[194:197], v[88:91]
	v_mfma_f32_16x16x32_bf16 v[76:79], v[96:99], v[208:211], v[76:79]
	v_mfma_f32_16x16x32_bf16 v[72:75], v[108:111], v[208:211], v[72:75]
	v_mfma_f32_16x16x32_bf16 v[140:143], v[100:103], v[164:167], v[140:143]
	v_mfma_f32_16x16x32_bf16 v[136:139], v[116:119], v[164:167], v[136:139]
	v_mfma_f32_16x16x32_bf16 v[124:127], v[100:103], v[186:189], v[124:127]
	v_mfma_f32_16x16x32_bf16 v[120:123], v[116:119], v[186:189], v[120:123]
	v_mfma_f32_16x16x32_bf16 v[92:95], v[100:103], v[204:207], v[92:95]
	v_mfma_f32_16x16x32_bf16 v[88:91], v[116:119], v[204:207], v[88:91]
	v_mfma_f32_16x16x32_bf16 v[76:79], v[100:103], v[212:215], v[76:79]
	v_mfma_f32_16x16x32_bf16 v[72:75], v[116:119], v[212:215], v[72:75]
	v_mfma_f32_16x16x32_bf16 v[132:135], v[144:147], v[160:163], v[132:135]
	v_mfma_f32_16x16x32_bf16 v[128:131], v[152:155], v[160:163], v[128:131]
	v_mfma_f32_16x16x32_bf16 v[112:115], v[144:147], v[182:185], v[112:115]
	v_mfma_f32_16x16x32_bf16 v[104:107], v[152:155], v[182:185], v[104:107]
	v_mfma_f32_16x16x32_bf16 v[84:87], v[144:147], v[194:197], v[84:87]
	v_mfma_f32_16x16x32_bf16 v[80:83], v[152:155], v[194:197], v[80:83]
	v_mfma_f32_16x16x32_bf16 v[68:71], v[144:147], v[208:211], v[68:71]
	v_mfma_f32_16x16x32_bf16 v[64:67], v[152:155], v[208:211], v[64:67]
	v_mfma_f32_16x16x32_bf16 v[132:135], v[148:151], v[164:167], v[132:135]
	v_mfma_f32_16x16x32_bf16 v[128:131], v[156:159], v[164:167], v[128:131]
	v_mfma_f32_16x16x32_bf16 v[112:115], v[148:151], v[186:189], v[112:115]
	v_mfma_f32_16x16x32_bf16 v[104:107], v[156:159], v[186:189], v[104:107]
	v_mfma_f32_16x16x32_bf16 v[84:87], v[148:151], v[204:207], v[84:87]
	v_mfma_f32_16x16x32_bf16 v[80:83], v[156:159], v[204:207], v[80:83]
	v_mfma_f32_16x16x32_bf16 v[68:71], v[148:151], v[212:215], v[68:71]
	v_mfma_f32_16x16x32_bf16 v[64:67], v[156:159], v[212:215], v[64:67]
	s_barrier
	s_add_i32 s86, s58, s27
	v_lshl_add_u64 v[190:191], s[44:45], 0, v[170:171]
	s_mov_b32 m0, s86
	ds_read_b128 v[160:163], v203 offset:16384
	ds_read_b128 v[164:167], v203 offset:17408
	ds_read_b128 v[182:185], v203 offset:18432
	ds_read_b128 v[186:189], v203 offset:19456
	ds_read_b128 v[194:197], v203 offset:20480
	ds_read_b128 v[204:207], v203 offset:21504
	ds_read_b128 v[208:211], v203 offset:22528
	ds_read_b128 v[212:215], v203 offset:23552
	global_load_lds_dwordx4 v[190:191], off
	s_add_i32 m0, s86, 0x2000
	s_add_u32 s86, s44, 0x160000
	v_lshl_add_u64 v[216:217], s[44:45], 0, v[174:175]
	s_addc_u32 s87, s45, 0
	s_add_i32 s88, s59, s27
	global_load_lds_dwordx4 v[216:217], off
	v_lshl_add_u64 v[218:219], s[86:87], 0, v[170:171]
	s_mov_b32 m0, s88
	v_lshl_add_u64 v[220:221], s[46:47], 0, v[172:173]
	global_load_lds_dwordx4 v[218:219], off
	v_lshl_add_u64 v[218:219], s[86:87], 0, v[174:175]
	s_add_i32 m0, s88, 0x2000
	s_nop 0
	global_load_lds_dwordx4 v[218:219], off
	v_lshl_add_u64 v[218:219], s[46:47], 0, v[168:169]
	s_mov_b32 m0, s48
	s_nop 0
	global_load_lds_dwordx4 v[218:219], off
	s_mov_b32 m0, s49
	s_nop 0
	global_load_lds_dwordx4 v[220:221], off
	s_waitcnt vmcnt(8)
	s_waitcnt lgkmcnt(0)
	s_barrier
	v_mfma_f32_16x16x32_bf16 v[60:63], v[96:99], v[160:163], v[60:63]
	v_mfma_f32_16x16x32_bf16 v[56:59], v[108:111], v[160:163], v[56:59]
	v_mfma_f32_16x16x32_bf16 v[44:47], v[96:99], v[182:185], v[44:47]
	v_mfma_f32_16x16x32_bf16 v[40:43], v[108:111], v[182:185], v[40:43]
	v_mfma_f32_16x16x32_bf16 v[28:31], v[96:99], v[194:197], v[28:31]
	v_mfma_f32_16x16x32_bf16 v[24:27], v[108:111], v[194:197], v[24:27]
	v_mfma_f32_16x16x32_bf16 v[12:15], v[96:99], v[208:211], v[12:15]
	v_mfma_f32_16x16x32_bf16 v[8:11], v[108:111], v[208:211], v[8:11]
	v_mfma_f32_16x16x32_bf16 v[60:63], v[100:103], v[164:167], v[60:63]
	v_mfma_f32_16x16x32_bf16 v[56:59], v[116:119], v[164:167], v[56:59]
	v_mfma_f32_16x16x32_bf16 v[44:47], v[100:103], v[186:189], v[44:47]
	v_mfma_f32_16x16x32_bf16 v[40:43], v[116:119], v[186:189], v[40:43]
	v_mfma_f32_16x16x32_bf16 v[28:31], v[100:103], v[204:207], v[28:31]
	v_mfma_f32_16x16x32_bf16 v[24:27], v[116:119], v[204:207], v[24:27]
	v_mfma_f32_16x16x32_bf16 v[12:15], v[100:103], v[212:215], v[12:15]
	v_mfma_f32_16x16x32_bf16 v[8:11], v[116:119], v[212:215], v[8:11]
	v_mfma_f32_16x16x32_bf16 v[52:55], v[144:147], v[160:163], v[52:55]
	v_mfma_f32_16x16x32_bf16 v[48:51], v[152:155], v[160:163], v[48:51]
	v_mfma_f32_16x16x32_bf16 v[36:39], v[144:147], v[182:185], v[36:39]
	v_mfma_f32_16x16x32_bf16 v[32:35], v[152:155], v[182:185], v[32:35]
	v_mfma_f32_16x16x32_bf16 v[20:23], v[144:147], v[194:197], v[20:23]
	v_mfma_f32_16x16x32_bf16 v[16:19], v[152:155], v[194:197], v[16:19]
	v_mfma_f32_16x16x32_bf16 v[4:7], v[144:147], v[208:211], v[4:7]
	v_mfma_f32_16x16x32_bf16 v[0:3], v[152:155], v[208:211], v[0:3]
	v_mfma_f32_16x16x32_bf16 v[52:55], v[148:151], v[164:167], v[52:55]
	v_mfma_f32_16x16x32_bf16 v[48:51], v[156:159], v[164:167], v[48:51]
	v_mfma_f32_16x16x32_bf16 v[36:39], v[148:151], v[186:189], v[36:39]
	v_mfma_f32_16x16x32_bf16 v[32:35], v[156:159], v[186:189], v[32:35]
	v_mfma_f32_16x16x32_bf16 v[20:23], v[148:151], v[204:207], v[20:23]
	v_mfma_f32_16x16x32_bf16 v[16:19], v[156:159], v[204:207], v[16:19]
	v_mfma_f32_16x16x32_bf16 v[4:7], v[148:151], v[212:215], v[4:7]
	v_mfma_f32_16x16x32_bf16 v[0:3], v[156:159], v[212:215], v[0:3]
	s_barrier
; #define PG8_STAGE(bufoff, gbase, voff) do { _Pragma("unroll") for (int _i = 0; _i < 2; ++_i) \
;         __builtin_amdgcn_global_load_lds((const unsigned*)((const char*)(gbase) + (voff)[_i]), (LAS unsigned*)(lds + (bufoff) + ldsw + _i * 8192), 16, 0, 0); } while (0)
; #define PG8_LDA(dst, b, h) do { _Pragma("unroll") for (int m = 0; m < 4; ++m) _Pragma("unroll") for (int k = 0; k < 2; ++k) dst[m][k] = *(const LAS bf16x8*)(lds + PG8_SA(b, h) + aoff + m * 2048 + k * 1024); } while (0)
; #define PG8_LDB(dst, b, h) do { _Pragma("unroll") for (int n = 0; n < 2; ++n) _Pragma("unroll") for (int k = 0; k < 2; ++k) dst[n][k] = *(const LAS bf16x8*)(lds + PG8_SB(b, h) + boff + n * 2048 + k * 1024); } while (0)
; #define PG8_MMA(ai, bj, At, Bt) do { __builtin_amdgcn_s_setprio(1); _Pragma("unroll") for (int m = 0; m < 4; ++m) _Pragma("unroll") for (int n = 0; n < 2; ++n) _Pragma("unroll") for (int k = 0; k < 2; ++k) \
;         acc[ai][bj][m][n] = __builtin_amdgcn_mfma_f32_16x16x32_bf16(Bt[n][k], At[m][k], acc[ai][bj][m][n], 0, 0, 0); __builtin_amdgcn_s_setprio(0); } while (0)
; #define PG8_WAIT_V(n) asm volatile("s_waitcnt vmcnt(" #n ")" ::: "memory")
; #define PG8_WAIT_L(n) asm volatile("s_waitcnt lgkmcnt(" #n ")" ::: "memory")
; #define PG8_BAR __builtin_amdgcn_s_barrier()
; #define PG8_SCHED __builtin_amdgcn_sched_barrier(0)
; template <class Epi, class Sched = StaticOrder, class EpiSub = NoSub, bool FAST = false>
; __device__ __forceinline__ void gemm_phase(LAS unsigned char* lds, const Gemm g, const Sched& S, const Epi& E, const EpiSub& ES = EpiSub()) {
;     ...
;             PG8_LDB(B0, 1, 0); PG8_LDB(B1, 1, 1); PG8_SCHED; PG8_LDA(At, 1, 0); PG8_STAGE(PG8_SA(0, 1), a2 + hstepA, voffA);
;             PG8_WAIT_V(8); PG8_WAIT_L(0); PG8_BAR; PG8_MMA(0, 0, At, B0); PG8_MMA(0, 1, At, B1); PG8_BAR; PG8_SCHED;
;             PG8_LDA(At, 1, 1); PG8_STAGE(PG8_SB(1, 0), b3, voffB); PG8_STAGE(PG8_SB(1, 1), b3 + hstepB, voffB); PG8_STAGE(PG8_SA(1, 0), a3, voffA);
;             PG8_WAIT_V(8); PG8_WAIT_L(0); PG8_BAR; PG8_MMA(1, 0, At, B0); PG8_MMA(1, 1, At, B1); PG8_BAR; PG8_SCHED;
	s_add_i32 s86, 0, 0x18000
	s_add_i32 s87, 0, 0x1c000
	v_add_u32_e32 v116, s86, v198
	v_add_u32_e32 v156, s87, v198
	ds_read_b128 v[96:99], v116
	ds_read_b128 v[100:103], v116 offset:1024
	ds_read_b128 v[108:111], v116 offset:2048
	ds_read_b128 v[116:119], v116 offset:3072
	ds_read_b128 v[144:147], v156
	ds_read_b128 v[148:151], v156 offset:1024
	ds_read_b128 v[152:155], v156 offset:2048
	ds_read_b128 v[156:159], v156 offset:3072
	s_add_u32 s46, s46, 0x160000
	s_addc_u32 s47, s47, 0
	s_mov_b32 m0, s50
	v_lshl_add_u64 v[222:223], s[46:47], 0, v[168:169]
	ds_read_b128 v[160:163], v203 offset:32768
	ds_read_b128 v[164:167], v203 offset:33792
	ds_read_b128 v[182:185], v203 offset:34816
	ds_read_b128 v[186:189], v203 offset:35840
	ds_read_b128 v[194:197], v203 offset:36864
	ds_read_b128 v[204:207], v203 offset:37888
	ds_read_b128 v[208:211], v203 offset:38912
	ds_read_b128 v[212:215], v203 offset:39936
	global_load_lds_dwordx4 v[222:223], off
	v_lshl_add_u64 v[222:223], s[46:47], 0, v[172:173]
	s_mov_b32 m0, s51
	s_nop 0
	global_load_lds_dwordx4 v[222:223], off
	s_waitcnt vmcnt(8)
	s_waitcnt lgkmcnt(0)
	s_barrier
	v_mfma_f32_16x16x32_bf16 v[140:143], v[96:99], v[160:163], v[140:143]
	v_mfma_f32_16x16x32_bf16 v[136:139], v[108:111], v[160:163], v[136:139]
	v_mfma_f32_16x16x32_bf16 v[124:127], v[96:99], v[182:185], v[124:127]
	v_mfma_f32_16x16x32_bf16 v[120:123], v[108:111], v[182:185], v[120:123]
	v_mfma_f32_16x16x32_bf16 v[92:95], v[96:99], v[194:197], v[92:95]
	v_mfma_f32_16x16x32_bf16 v[88:91], v[108:111], v[194:197], v[88:91]
	v_mfma_f32_16x16x32_bf16 v[76:79], v[96:99], v[208:211], v[76:79]
	v_mfma_f32_16x16x32_bf16 v[72:75], v[108:111], v[208:211], v[72:75]
	v_mfma_f32_16x16x32_bf16 v[140:143], v[100:103], v[164:167], v[140:143]
	v_mfma_f32_16x16x32_bf16 v[136:139], v[116:119], v[164:167], v[136:139]
	v_mfma_f32_16x16x32_bf16 v[124:127], v[100:103], v[186:189], v[124:127]
	v_mfma_f32_16x16x32_bf16 v[120:123], v[116:119], v[186:189], v[120:123]
	v_mfma_f32_16x16x32_bf16 v[92:95], v[100:103], v[204:207], v[92:95]
	v_mfma_f32_16x16x32_bf16 v[88:91], v[116:119], v[204:207], v[88:91]
	v_mfma_f32_16x16x32_bf16 v[76:79], v[100:103], v[212:215], v[76:79]
	v_mfma_f32_16x16x32_bf16 v[72:75], v[116:119], v[212:215], v[72:75]
	v_mfma_f32_16x16x32_bf16 v[132:135], v[144:147], v[160:163], v[132:135]
	v_mfma_f32_16x16x32_bf16 v[128:131], v[152:155], v[160:163], v[128:131]
	v_mfma_f32_16x16x32_bf16 v[112:115], v[144:147], v[182:185], v[112:115]
	v_mfma_f32_16x16x32_bf16 v[104:107], v[152:155], v[182:185], v[104:107]
	v_mfma_f32_16x16x32_bf16 v[84:87], v[144:147], v[194:197], v[84:87]
	v_mfma_f32_16x16x32_bf16 v[80:83], v[152:155], v[194:197], v[80:83]
	v_mfma_f32_16x16x32_bf16 v[68:71], v[144:147], v[208:211], v[68:71]
	v_mfma_f32_16x16x32_bf16 v[64:67], v[152:155], v[208:211], v[64:67]
	v_mfma_f32_16x16x32_bf16 v[132:135], v[148:151], v[164:167], v[132:135]
	v_mfma_f32_16x16x32_bf16 v[128:131], v[156:159], v[164:167], v[128:131]
	v_mfma_f32_16x16x32_bf16 v[112:115], v[148:151], v[186:189], v[112:115]
	v_mfma_f32_16x16x32_bf16 v[104:107], v[156:159], v[186:189], v[104:107]
	v_mfma_f32_16x16x32_bf16 v[84:87], v[148:151], v[204:207], v[84:87]
	v_mfma_f32_16x16x32_bf16 v[80:83], v[156:159], v[204:207], v[80:83]
	v_mfma_f32_16x16x32_bf16 v[68:71], v[148:151], v[212:215], v[68:71]
	v_mfma_f32_16x16x32_bf16 v[64:67], v[156:159], v[212:215], v[64:67]
	s_barrier
	s_add_i32 s46, s86, s27
	v_lshl_add_u64 v[190:191], v[190:191], 0, s[16:17]
	s_mov_b32 m0, s46
	ds_read_b128 v[160:163], v203 offset:49152
	ds_read_b128 v[164:167], v203 offset:50176
	ds_read_b128 v[182:185], v203 offset:51200
	ds_read_b128 v[186:189], v203 offset:52224
	ds_read_b128 v[194:197], v203 offset:53248
	ds_read_b128 v[204:207], v203 offset:54272
	ds_read_b128 v[208:211], v203 offset:55296
	ds_read_b128 v[212:215], v203 offset:56320
	global_load_lds_dwordx4 v[190:191], off
	s_add_i32 m0, s46, 0x2000
	s_add_u32 s44, s44, 0x160080
	v_lshl_add_u64 v[190:191], v[216:217], 0, s[16:17]
	s_addc_u32 s45, s45, 0
	s_add_i32 s46, s87, s27
	global_load_lds_dwordx4 v[190:191], off
	v_lshl_add_u64 v[190:191], s[44:45], 0, v[170:171]
	s_mov_b32 m0, s46
	s_nop 0
	global_load_lds_dwordx4 v[190:191], off
	v_lshl_add_u64 v[190:191], s[44:45], 0, v[174:175]
	s_add_i32 m0, s46, 0x2000
	s_nop 0
	global_load_lds_dwordx4 v[190:191], off
	v_lshl_add_u64 v[190:191], v[218:219], 0, s[16:17]
	s_mov_b32 m0, s53
	s_nop 0
	global_load_lds_dwordx4 v[190:191], off
	v_lshl_add_u64 v[190:191], v[220:221], 0, s[16:17]
	s_mov_b32 m0, s54
	s_nop 0
	global_load_lds_dwordx4 v[190:191], off
	s_add_u32 s42, s42, 0x100
	s_addc_u32 s43, s43, 0
	s_add_u32 s83, s83, 0x100
	s_addc_u32 s84, s84, 0
	s_waitcnt vmcnt(8)
	s_waitcnt lgkmcnt(0)
	s_barrier
	v_mfma_f32_16x16x32_bf16 v[60:63], v[96:99], v[160:163], v[60:63]
	v_mfma_f32_16x16x32_bf16 v[56:59], v[108:111], v[160:163], v[56:59]
	v_mfma_f32_16x16x32_bf16 v[44:47], v[96:99], v[182:185], v[44:47]
	v_mfma_f32_16x16x32_bf16 v[40:43], v[108:111], v[182:185], v[40:43]
	v_mfma_f32_16x16x32_bf16 v[28:31], v[96:99], v[194:197], v[28:31]
	v_mfma_f32_16x16x32_bf16 v[24:27], v[108:111], v[194:197], v[24:27]
	v_mfma_f32_16x16x32_bf16 v[12:15], v[96:99], v[208:211], v[12:15]
	v_mfma_f32_16x16x32_bf16 v[8:11], v[108:111], v[208:211], v[8:11]
	v_mfma_f32_16x16x32_bf16 v[60:63], v[100:103], v[164:167], v[60:63]
	v_mfma_f32_16x16x32_bf16 v[56:59], v[116:119], v[164:167], v[56:59]
	v_mfma_f32_16x16x32_bf16 v[44:47], v[100:103], v[186:189], v[44:47]
	v_mfma_f32_16x16x32_bf16 v[40:43], v[116:119], v[186:189], v[40:43]
	v_mfma_f32_16x16x32_bf16 v[28:31], v[100:103], v[204:207], v[28:31]
	v_mfma_f32_16x16x32_bf16 v[24:27], v[116:119], v[204:207], v[24:27]
	v_mfma_f32_16x16x32_bf16 v[12:15], v[100:103], v[212:215], v[12:15]
	v_mfma_f32_16x16x32_bf16 v[8:11], v[116:119], v[212:215], v[8:11]
	v_mfma_f32_16x16x32_bf16 v[52:55], v[144:147], v[160:163], v[52:55]
	v_mfma_f32_16x16x32_bf16 v[48:51], v[152:155], v[160:163], v[48:51]
	v_mfma_f32_16x16x32_bf16 v[36:39], v[144:147], v[182:185], v[36:39]
	v_mfma_f32_16x16x32_bf16 v[32:35], v[152:155], v[182:185], v[32:35]
	v_mfma_f32_16x16x32_bf16 v[20:23], v[144:147], v[194:197], v[20:23]
	v_mfma_f32_16x16x32_bf16 v[16:19], v[152:155], v[194:197], v[16:19]
	v_mfma_f32_16x16x32_bf16 v[4:7], v[144:147], v[208:211], v[4:7]
	v_mfma_f32_16x16x32_bf16 v[0:3], v[152:155], v[208:211], v[0:3]
	v_mfma_f32_16x16x32_bf16 v[52:55], v[148:151], v[164:167], v[52:55]
	v_mfma_f32_16x16x32_bf16 v[48:51], v[156:159], v[164:167], v[48:51]
	v_mfma_f32_16x16x32_bf16 v[36:39], v[148:151], v[186:189], v[36:39]
	v_mfma_f32_16x16x32_bf16 v[32:35], v[156:159], v[186:189], v[32:35]
	v_mfma_f32_16x16x32_bf16 v[20:23], v[148:151], v[204:207], v[20:23]
	v_mfma_f32_16x16x32_bf16 v[16:19], v[156:159], v[204:207], v[16:19]
	v_mfma_f32_16x16x32_bf16 v[4:7], v[148:151], v[212:215], v[4:7]
	v_mfma_f32_16x16x32_bf16 v[0:3], v[156:159], v[212:215], v[0:3]
	s_barrier
	s_cmp_ge_u32 s85, s70
	s_mov_b32 s46, s85
	s_cbranch_scc0 .LBB0_1079
